# baseline (speedup 1.0000x reference)
; #define STA(b, h, half, kt) STAGE(((b) * 2 + (h)) * G_HT * 2, pA, ((size_t)(half) * G_HALF * lda + (size_t)(kt) * G_BK) * 2, lda)
; #define STB(b, h, half, kt) STAGE((4 + (b) * 2 + (h)) * G_HT * 2, pB, ((size_t)(half) * G_HALF * K + (size_t)(kt) * G_BK) * 2, K)
; #define LDA(dst, b, h) for (int m = 0; m < 4; ++m) for (int k = 0; k < 2; ++k) \
;     dst[m][k] = *reinterpret_cast<const bf16x8*>(aRd + (((b) * 2 + (h)) * G_HT * 2 + m * 2048 + k * 1024))
; #define LDB(dst, b, h) for (int n = 0; n < 2; ++n) for (int k = 0; k < 2; ++k) \
;     dst[n][k] = *reinterpret_cast<const bf16x8*>(bRd + (((b) * 2 + (h)) * G_HT * 2 + n * 2048 + k * 1024))
; #define MMA(ai, bj, At, Bx) do { __builtin_amdgcn_s_setprio(1); \
;     for (int m = 0; m < 4; ++m) for (int n = 0; n < 2; ++n) for (int k = 0; k < 2; ++k) \
;       acc[ai][bj][m][n] = __builtin_amdgcn_mfma_f32_16x16x32_bf16(Bx[n][k], At[m][k], acc[ai][bj][m][n], 0, 0, 0);     \
;     __builtin_amdgcn_s_setprio(0); } while (0)
; #define WAIT_V(n) asm volatile("s_waitcnt vmcnt(" #n ")" ::: "memory")
; #define WAIT_L(n) asm volatile("s_waitcnt lgkmcnt(" #n ")" ::: "memory")
; #define BAR __builtin_amdgcn_s_barrier()
; #define SCHED __builtin_amdgcn_sched_barrier(0)
; template <int EPI>
; __device__ __forceinline__ void gemm_tile(const bf16* __restrict__ A, int lda, const bf16* __restrict__ Bt, int K,
;                                           int brow, int bcol, const EpiArgs& ea, char* shmc, bool has_next, int nbrow, int nbcol, bool first_tile) {
;     ...
;   for (int t = 0; t < nt - 2; t += 2) {
;     LDB(B0, 0, 0); SCHED; LDA(At, 0, 0); STA(1, 1, 1, t + 1);
;     WAIT_L(8); BAR; WAIT_L(0); MMA(0, 0, At, B0); BAR; SCHED;
;     LDB(B1, 0, 1); STB(0, 0, 0, t + 2);
;     BAR; WAIT_L(0); MMA(0, 1, At, B1); BAR;
;     LDA(At, 0, 1); STA(0, 0, 0, t + 2);
;     BAR; WAIT_L(0); MMA(1, 0, At, B0); BAR; SCHED;
;     STB(0, 1, 1, t + 2);
;     WAIT_V(6); BAR; MMA(1, 1, At, B1); BAR;
.LBB0_96:
	ds_read_b128 v[162:165], v141
	ds_read_b128 v[166:169], v142
	ds_read_b128 v[170:173], v143
	ds_read_b128 v[174:177], v144
	s_add_u32 s82, s34, 0xffffff00
	s_addc_u32 s83, s35, -1
	s_mov_b32 m0, s77
	ds_read_b128 v[178:181], v160
	ds_read_b128 v[182:185], v160 offset:1024
	ds_read_b128 v[186:189], v160 offset:2048
	ds_read_b128 v[190:193], v160 offset:3072
	ds_read_b128 v[194:197], v160 offset:4096
	ds_read_b128 v[198:201], v160 offset:5120
	ds_read_b128 v[202:205], v160 offset:6144
	ds_read_b128 v[206:209], v160 offset:7168
	v_lshl_add_u64 v[210:211], v[134:135], 0, s[82:83]
	global_load_lds_dwordx4 v[210:211], off
	s_mov_b32 m0, s68
	v_lshl_add_u64 v[210:211], v[210:211], 0, s[0:1]
	global_load_lds_dwordx4 v[210:211], off
	s_waitcnt lgkmcnt(8)
	s_barrier
	s_waitcnt lgkmcnt(0)
	s_setprio 1
	v_mfma_f32_16x16x32_bf16 v[124:127], v[162:165], v[178:181], v[124:127]
	v_mfma_f32_16x16x32_bf16 v[120:123], v[170:173], v[178:181], v[120:123]
	v_mfma_f32_16x16x32_bf16 v[116:119], v[162:165], v[186:189], v[116:119]
	v_mfma_f32_16x16x32_bf16 v[112:115], v[170:173], v[186:189], v[112:115]
	v_mfma_f32_16x16x32_bf16 v[108:111], v[162:165], v[194:197], v[108:111]
	v_mfma_f32_16x16x32_bf16 v[104:107], v[170:173], v[194:197], v[104:107]
	v_mfma_f32_16x16x32_bf16 v[100:103], v[162:165], v[202:205], v[100:103]
	v_mfma_f32_16x16x32_bf16 v[96:99], v[170:173], v[202:205], v[96:99]
	v_mfma_f32_16x16x32_bf16 v[124:127], v[166:169], v[182:185], v[124:127]
	v_mfma_f32_16x16x32_bf16 v[120:123], v[174:177], v[182:185], v[120:123]
	v_mfma_f32_16x16x32_bf16 v[116:119], v[166:169], v[190:193], v[116:119]
	v_mfma_f32_16x16x32_bf16 v[112:115], v[174:177], v[190:193], v[112:115]
	v_mfma_f32_16x16x32_bf16 v[108:111], v[166:169], v[198:201], v[108:111]
	v_mfma_f32_16x16x32_bf16 v[104:107], v[174:177], v[198:201], v[104:107]
	v_mfma_f32_16x16x32_bf16 v[100:103], v[166:169], v[206:209], v[100:103]
	v_mfma_f32_16x16x32_bf16 v[96:99], v[174:177], v[206:209], v[96:99]
	s_setprio 0
	s_barrier
	s_add_u32 s82, s34, 0xffefff80
	s_addc_u32 s83, s35, -1
	s_mov_b64 s[84:85], s[82:83]
	s_mov_b32 m0, s71
	ds_read_b128 v[210:213], v145
	ds_read_b128 v[214:217], v146
	ds_read_b128 v[218:221], v147
	ds_read_b128 v[222:225], v148
	v_lshl_add_u64 v[226:227], v[136:137], 0, s[84:85]
	global_load_lds_dwordx4 v[226:227], off
	s_mov_b32 m0, s72
	v_lshl_add_u64 v[226:227], v[226:227], 0, s[0:1]
	global_load_lds_dwordx4 v[226:227], off
	s_barrier
	s_waitcnt lgkmcnt(0)
	s_setprio 1
	v_mfma_f32_16x16x32_bf16 v[92:95], v[210:213], v[178:181], v[92:95]
	v_mfma_f32_16x16x32_bf16 v[88:91], v[218:221], v[178:181], v[88:91]
	v_mfma_f32_16x16x32_bf16 v[84:87], v[210:213], v[186:189], v[84:87]
	v_mfma_f32_16x16x32_bf16 v[80:83], v[218:221], v[186:189], v[80:83]
	v_mfma_f32_16x16x32_bf16 v[76:79], v[210:213], v[194:197], v[76:79]
	v_mfma_f32_16x16x32_bf16 v[72:75], v[218:221], v[194:197], v[72:75]
	v_mfma_f32_16x16x32_bf16 v[68:71], v[210:213], v[202:205], v[68:71]
	v_mfma_f32_16x16x32_bf16 v[64:67], v[218:221], v[202:205], v[64:67]
	v_mfma_f32_16x16x32_bf16 v[92:95], v[214:217], v[182:185], v[92:95]
	v_mfma_f32_16x16x32_bf16 v[88:91], v[222:225], v[182:185], v[88:91]
	v_mfma_f32_16x16x32_bf16 v[84:87], v[214:217], v[190:193], v[84:87]
	v_mfma_f32_16x16x32_bf16 v[80:83], v[222:225], v[190:193], v[80:83]
	v_mfma_f32_16x16x32_bf16 v[76:79], v[214:217], v[198:201], v[76:79]
	v_mfma_f32_16x16x32_bf16 v[72:75], v[222:225], v[198:201], v[72:75]
	v_mfma_f32_16x16x32_bf16 v[68:71], v[214:217], v[206:209], v[68:71]
	v_mfma_f32_16x16x32_bf16 v[64:67], v[222:225], v[206:209], v[64:67]
	s_setprio 0
	s_mov_b32 m0, s7
	s_barrier
	ds_read_b128 v[178:181], v160 offset:16384
	ds_read_b128 v[182:185], v160 offset:17408
	ds_read_b128 v[186:189], v160 offset:18432
	ds_read_b128 v[190:193], v160 offset:19456
	ds_read_b128 v[194:197], v160 offset:20480
	ds_read_b128 v[198:201], v160 offset:21504
	ds_read_b128 v[202:205], v160 offset:22528
	ds_read_b128 v[206:209], v160 offset:23552
	v_lshl_add_u64 v[226:227], v[134:135], 0, s[82:83]
	global_load_lds_dwordx4 v[226:227], off
	s_mov_b32 m0, s79
	v_lshl_add_u64 v[226:227], v[226:227], 0, s[0:1]
	global_load_lds_dwordx4 v[226:227], off
	s_barrier
	s_waitcnt lgkmcnt(0)
	s_setprio 1
	v_mfma_f32_16x16x32_bf16 v[60:63], v[162:165], v[178:181], v[60:63]
	v_mfma_f32_16x16x32_bf16 v[56:59], v[170:173], v[178:181], v[56:59]
	v_mfma_f32_16x16x32_bf16 v[52:55], v[162:165], v[186:189], v[52:55]
	v_mfma_f32_16x16x32_bf16 v[48:51], v[170:173], v[186:189], v[48:51]
	v_mfma_f32_16x16x32_bf16 v[44:47], v[162:165], v[194:197], v[44:47]
	v_mfma_f32_16x16x32_bf16 v[40:43], v[170:173], v[194:197], v[40:43]
	v_mfma_f32_16x16x32_bf16 v[36:39], v[162:165], v[202:205], v[36:39]
	v_mfma_f32_16x16x32_bf16 v[32:35], v[170:173], v[202:205], v[32:35]
	v_mfma_f32_16x16x32_bf16 v[60:63], v[166:169], v[182:185], v[60:63]
	v_mfma_f32_16x16x32_bf16 v[56:59], v[174:177], v[182:185], v[56:59]
	v_mfma_f32_16x16x32_bf16 v[52:55], v[166:169], v[190:193], v[52:55]
	v_mfma_f32_16x16x32_bf16 v[48:51], v[174:177], v[190:193], v[48:51]
	v_mfma_f32_16x16x32_bf16 v[44:47], v[166:169], v[198:201], v[44:47]
	v_mfma_f32_16x16x32_bf16 v[40:43], v[174:177], v[198:201], v[40:43]
	v_mfma_f32_16x16x32_bf16 v[36:39], v[166:169], v[206:209], v[36:39]
	v_mfma_f32_16x16x32_bf16 v[32:35], v[174:177], v[206:209], v[32:35]
	s_setprio 0
	s_barrier
	s_add_u32 s82, s34, 0xffffff80
	s_addc_u32 s83, s35, -1
	s_mov_b64 s[84:85], s[82:83]
	s_mov_b32 m0, s73
	v_lshl_add_u64 v[162:163], v[136:137], 0, s[84:85]
	global_load_lds_dwordx4 v[162:163], off
	s_mov_b32 m0, s74
	v_lshl_add_u64 v[162:163], v[162:163], 0, s[0:1]
	global_load_lds_dwordx4 v[162:163], off
	s_waitcnt vmcnt(6)
	s_barrier
; #define STA(b, h, half, kt) STAGE(((b) * 2 + (h)) * G_HT * 2, pA, ((size_t)(half) * G_HALF * lda + (size_t)(kt) * G_BK) * 2, lda)
; #define STB(b, h, half, kt) STAGE((4 + (b) * 2 + (h)) * G_HT * 2, pB, ((size_t)(half) * G_HALF * K + (size_t)(kt) * G_BK) * 2, K)
; #define LDA(dst, b, h) for (int m = 0; m < 4; ++m) for (int k = 0; k < 2; ++k) \
;     dst[m][k] = *reinterpret_cast<const bf16x8*>(aRd + (((b) * 2 + (h)) * G_HT * 2 + m * 2048 + k * 1024))
; #define LDB(dst, b, h) for (int n = 0; n < 2; ++n) for (int k = 0; k < 2; ++k) \
;     dst[n][k] = *reinterpret_cast<const bf16x8*>(bRd + (((b) * 2 + (h)) * G_HT * 2 + n * 2048 + k * 1024))
; #define MMA(ai, bj, At, Bx) do { __builtin_amdgcn_s_setprio(1); \
;     for (int m = 0; m < 4; ++m) for (int n = 0; n < 2; ++n) for (int k = 0; k < 2; ++k) \
;       acc[ai][bj][m][n] = __builtin_amdgcn_mfma_f32_16x16x32_bf16(Bx[n][k], At[m][k], acc[ai][bj][m][n], 0, 0, 0);     \
;     __builtin_amdgcn_s_setprio(0); } while (0)
; #define WAIT_V(n) asm volatile("s_waitcnt vmcnt(" #n ")" ::: "memory")
; #define WAIT_L(n) asm volatile("s_waitcnt lgkmcnt(" #n ")" ::: "memory")
; #define BAR __builtin_amdgcn_s_barrier()
; #define SCHED __builtin_amdgcn_sched_barrier(0)
; template <int EPI>
; __device__ __forceinline__ void gemm_tile(const bf16* __restrict__ A, int lda, const bf16* __restrict__ Bt, int K,
;                                           int brow, int bcol, const EpiArgs& ea, char* shmc, bool has_next, int nbrow, int nbcol, bool first_tile) {
;     ...
;     WAIT_V(6); BAR; MMA(1, 1, At, B1); BAR;
;     LDB(B0, 1, 0); SCHED; LDA(At, 1, 0); STA(0, 1, 1, t + 2);
;     WAIT_L(8); BAR; WAIT_L(0); MMA(0, 0, At, B0); BAR; SCHED;
;     LDB(B1, 1, 1); STB(1, 0, 0, t + 3);
;     BAR; WAIT_L(0); MMA(0, 1, At, B1); BAR;
;     LDA(At, 1, 1); STA(1, 0, 0, t + 3);
;     BAR; WAIT_L(0); MMA(1, 0, At, B0); BAR; SCHED;
	s_setprio 1
	v_mfma_f32_16x16x32_bf16 v[28:31], v[210:213], v[178:181], v[28:31]
	v_mfma_f32_16x16x32_bf16 v[24:27], v[218:221], v[178:181], v[24:27]
	v_mfma_f32_16x16x32_bf16 v[20:23], v[210:213], v[186:189], v[20:23]
	v_mfma_f32_16x16x32_bf16 v[16:19], v[218:221], v[186:189], v[16:19]
	v_mfma_f32_16x16x32_bf16 v[12:15], v[210:213], v[194:197], v[12:15]
	v_mfma_f32_16x16x32_bf16 v[8:11], v[218:221], v[194:197], v[8:11]
	v_mfma_f32_16x16x32_bf16 v[4:7], v[210:213], v[202:205], v[4:7]
	v_mfma_f32_16x16x32_bf16 v[0:3], v[218:221], v[202:205], v[0:3]
	v_mfma_f32_16x16x32_bf16 v[28:31], v[214:217], v[182:185], v[28:31]
	v_mfma_f32_16x16x32_bf16 v[24:27], v[222:225], v[182:185], v[24:27]
	v_mfma_f32_16x16x32_bf16 v[20:23], v[214:217], v[190:193], v[20:23]
	v_mfma_f32_16x16x32_bf16 v[16:19], v[222:225], v[190:193], v[16:19]
	v_mfma_f32_16x16x32_bf16 v[12:15], v[214:217], v[198:201], v[12:15]
	v_mfma_f32_16x16x32_bf16 v[8:11], v[222:225], v[198:201], v[8:11]
	v_mfma_f32_16x16x32_bf16 v[4:7], v[214:217], v[206:209], v[4:7]
	v_mfma_f32_16x16x32_bf16 v[0:3], v[222:225], v[206:209], v[0:3]
	s_setprio 0
	s_barrier
	ds_read_b128 v[162:165], v149
	ds_read_b128 v[166:169], v150
	ds_read_b128 v[170:173], v151
	ds_read_b128 v[174:177], v152
	s_mov_b32 m0, s80
	ds_read_b128 v[178:181], v160 offset:32768
	ds_read_b128 v[182:185], v160 offset:33792
	ds_read_b128 v[186:189], v160 offset:34816
	ds_read_b128 v[190:193], v160 offset:35840
	ds_read_b128 v[194:197], v160 offset:36864
	ds_read_b128 v[198:201], v160 offset:37888
	ds_read_b128 v[202:205], v160 offset:38912
	ds_read_b128 v[206:209], v160 offset:39936
	v_lshl_add_u64 v[210:211], v[134:135], 0, s[82:83]
	global_load_lds_dwordx4 v[210:211], off
	s_mov_b32 m0, s81
	v_lshl_add_u64 v[210:211], v[210:211], 0, s[0:1]
	global_load_lds_dwordx4 v[210:211], off
	s_waitcnt lgkmcnt(8)
	s_barrier
	s_waitcnt lgkmcnt(0)
	s_setprio 1
	v_mfma_f32_16x16x32_bf16 v[124:127], v[162:165], v[178:181], v[124:127]
	v_mfma_f32_16x16x32_bf16 v[120:123], v[170:173], v[178:181], v[120:123]
	v_mfma_f32_16x16x32_bf16 v[116:119], v[162:165], v[186:189], v[116:119]
	v_mfma_f32_16x16x32_bf16 v[112:115], v[170:173], v[186:189], v[112:115]
	v_mfma_f32_16x16x32_bf16 v[108:111], v[162:165], v[194:197], v[108:111]
	v_mfma_f32_16x16x32_bf16 v[104:107], v[170:173], v[194:197], v[104:107]
	v_mfma_f32_16x16x32_bf16 v[100:103], v[162:165], v[202:205], v[100:103]
	v_mfma_f32_16x16x32_bf16 v[96:99], v[170:173], v[202:205], v[96:99]
	v_mfma_f32_16x16x32_bf16 v[124:127], v[166:169], v[182:185], v[124:127]
	v_mfma_f32_16x16x32_bf16 v[120:123], v[174:177], v[182:185], v[120:123]
	v_mfma_f32_16x16x32_bf16 v[116:119], v[166:169], v[190:193], v[116:119]
	v_mfma_f32_16x16x32_bf16 v[112:115], v[174:177], v[190:193], v[112:115]
	v_mfma_f32_16x16x32_bf16 v[108:111], v[166:169], v[198:201], v[108:111]
	v_mfma_f32_16x16x32_bf16 v[104:107], v[174:177], v[198:201], v[104:107]
	v_mfma_f32_16x16x32_bf16 v[100:103], v[166:169], v[206:209], v[100:103]
	v_mfma_f32_16x16x32_bf16 v[96:99], v[174:177], v[206:209], v[96:99]
	s_setprio 0
	s_barrier
	s_add_u32 s82, s34, 0xfff00000
	s_addc_u32 s83, s35, -1
	s_mov_b64 s[84:85], s[82:83]
	s_mov_b32 m0, s11
	ds_read_b128 v[210:213], v153
	ds_read_b128 v[214:217], v154
	ds_read_b128 v[218:221], v155
	ds_read_b128 v[222:225], v156
	v_lshl_add_u64 v[226:227], v[136:137], 0, s[84:85]
	global_load_lds_dwordx4 v[226:227], off
	s_mov_b32 m0, s63
	v_lshl_add_u64 v[226:227], v[226:227], 0, s[0:1]
	global_load_lds_dwordx4 v[226:227], off
	s_barrier
	s_waitcnt lgkmcnt(0)
	s_setprio 1
	v_mfma_f32_16x16x32_bf16 v[92:95], v[210:213], v[178:181], v[92:95]
	v_mfma_f32_16x16x32_bf16 v[88:91], v[218:221], v[178:181], v[88:91]
	v_mfma_f32_16x16x32_bf16 v[84:87], v[210:213], v[186:189], v[84:87]
	v_mfma_f32_16x16x32_bf16 v[80:83], v[218:221], v[186:189], v[80:83]
	v_mfma_f32_16x16x32_bf16 v[76:79], v[210:213], v[194:197], v[76:79]
	v_mfma_f32_16x16x32_bf16 v[72:75], v[218:221], v[194:197], v[72:75]
	v_mfma_f32_16x16x32_bf16 v[68:71], v[210:213], v[202:205], v[68:71]
	v_mfma_f32_16x16x32_bf16 v[64:67], v[218:221], v[202:205], v[64:67]
	v_mfma_f32_16x16x32_bf16 v[92:95], v[214:217], v[182:185], v[92:95]
	v_mfma_f32_16x16x32_bf16 v[88:91], v[222:225], v[182:185], v[88:91]
	v_mfma_f32_16x16x32_bf16 v[84:87], v[214:217], v[190:193], v[84:87]
	v_mfma_f32_16x16x32_bf16 v[80:83], v[222:225], v[190:193], v[80:83]
	v_mfma_f32_16x16x32_bf16 v[76:79], v[214:217], v[198:201], v[76:79]
	v_mfma_f32_16x16x32_bf16 v[72:75], v[222:225], v[198:201], v[72:75]
	v_mfma_f32_16x16x32_bf16 v[68:71], v[214:217], v[206:209], v[68:71]
	v_mfma_f32_16x16x32_bf16 v[64:67], v[222:225], v[206:209], v[64:67]
	s_setprio 0
	s_mov_b32 m0, s66
	s_barrier
	ds_read_b128 v[178:181], v160 offset:49152
	ds_read_b128 v[182:185], v160 offset:50176
	ds_read_b128 v[186:189], v160 offset:51200
	ds_read_b128 v[190:193], v160 offset:52224
	ds_read_b128 v[194:197], v160 offset:53248
	ds_read_b128 v[198:201], v160 offset:54272
	ds_read_b128 v[202:205], v160 offset:55296
	ds_read_b128 v[206:209], v160 offset:56320
	v_lshl_add_u64 v[226:227], v[134:135], 0, s[82:83]
	global_load_lds_dwordx4 v[226:227], off
	s_mov_b32 m0, s67
	v_lshl_add_u64 v[226:227], v[226:227], 0, s[0:1]
	global_load_lds_dwordx4 v[226:227], off
	s_barrier
; #define STA(b, h, half, kt) STAGE(((b) * 2 + (h)) * G_HT * 2, pA, ((size_t)(half) * G_HALF * lda + (size_t)(kt) * G_BK) * 2, lda)
; #define STB(b, h, half, kt) STAGE((4 + (b) * 2 + (h)) * G_HT * 2, pB, ((size_t)(half) * G_HALF * K + (size_t)(kt) * G_BK) * 2, K)
; #define LDA(dst, b, h) for (int m = 0; m < 4; ++m) for (int k = 0; k < 2; ++k) \
;     dst[m][k] = *reinterpret_cast<const bf16x8*>(aRd + (((b) * 2 + (h)) * G_HT * 2 + m * 2048 + k * 1024))
; #define LDB(dst, b, h) for (int n = 0; n < 2; ++n) for (int k = 0; k < 2; ++k) \
;     dst[n][k] = *reinterpret_cast<const bf16x8*>(bRd + (((b) * 2 + (h)) * G_HT * 2 + n * 2048 + k * 1024))
; #define MMA(ai, bj, At, Bx) do { __builtin_amdgcn_s_setprio(1); \
;     for (int m = 0; m < 4; ++m) for (int n = 0; n < 2; ++n) for (int k = 0; k < 2; ++k) \
;       acc[ai][bj][m][n] = __builtin_amdgcn_mfma_f32_16x16x32_bf16(Bx[n][k], At[m][k], acc[ai][bj][m][n], 0, 0, 0);     \
;     __builtin_amdgcn_s_setprio(0); } while (0)
; #define WAIT_V(n) asm volatile("s_waitcnt vmcnt(" #n ")" ::: "memory")
; #define WAIT_L(n) asm volatile("s_waitcnt lgkmcnt(" #n ")" ::: "memory")
; #define BAR __builtin_amdgcn_s_barrier()
; #define SCHED __builtin_amdgcn_sched_barrier(0)
; template <int EPI>
; __device__ __forceinline__ void gemm_tile(const bf16* __restrict__ A, int lda, const bf16* __restrict__ Bt, int K,
;                                           int brow, int bcol, const EpiArgs& ea, char* shmc, bool has_next, int nbrow, int nbcol, bool first_tile) {
;     ...
;     BAR; WAIT_L(0); MMA(1, 0, At, B0); BAR; SCHED;
;     STB(1, 1, 1, t + 3);
;     WAIT_V(6); BAR; MMA(1, 1, At, B1); BAR;
;   }
;   { LDB(B0, 0, 0); LDA(At, 0, 0); STA(1, 1, 1, nt - 1);
;     BAR; WAIT_L(0); MMA(0, 0, At, B0); BAR;
;     LDB(B1, 0, 1); BAR; WAIT_L(0); MMA(0, 1, At, B1); BAR;
;     LDA(At, 0, 1); WAIT_V(4); BAR; WAIT_L(0); MMA(1, 0, At, B0); MMA(1, 1, At, B1); BAR; }
	s_waitcnt lgkmcnt(0)
	s_setprio 1
	v_mfma_f32_16x16x32_bf16 v[60:63], v[162:165], v[178:181], v[60:63]
	v_mfma_f32_16x16x32_bf16 v[56:59], v[170:173], v[178:181], v[56:59]
	v_mfma_f32_16x16x32_bf16 v[52:55], v[162:165], v[186:189], v[52:55]
	v_mfma_f32_16x16x32_bf16 v[48:51], v[170:173], v[186:189], v[48:51]
	v_mfma_f32_16x16x32_bf16 v[44:47], v[162:165], v[194:197], v[44:47]
	v_mfma_f32_16x16x32_bf16 v[40:43], v[170:173], v[194:197], v[40:43]
	v_mfma_f32_16x16x32_bf16 v[36:39], v[162:165], v[202:205], v[36:39]
	v_mfma_f32_16x16x32_bf16 v[32:35], v[170:173], v[202:205], v[32:35]
	v_mfma_f32_16x16x32_bf16 v[60:63], v[166:169], v[182:185], v[60:63]
	v_mfma_f32_16x16x32_bf16 v[56:59], v[174:177], v[182:185], v[56:59]
	v_mfma_f32_16x16x32_bf16 v[52:55], v[166:169], v[190:193], v[52:55]
	v_mfma_f32_16x16x32_bf16 v[48:51], v[174:177], v[190:193], v[48:51]
	v_mfma_f32_16x16x32_bf16 v[44:47], v[166:169], v[198:201], v[44:47]
	v_mfma_f32_16x16x32_bf16 v[40:43], v[174:177], v[198:201], v[40:43]
	v_mfma_f32_16x16x32_bf16 v[36:39], v[166:169], v[206:209], v[36:39]
	v_mfma_f32_16x16x32_bf16 v[32:35], v[174:177], v[206:209], v[32:35]
	s_setprio 0
	s_barrier
	s_mov_b64 s[82:83], s[34:35]
	s_mov_b32 m0, s69
	v_lshl_add_u64 v[162:163], v[136:137], 0, s[82:83]
	global_load_lds_dwordx4 v[162:163], off
	s_mov_b32 m0, s70
	v_lshl_add_u64 v[162:163], v[162:163], 0, s[0:1]
	global_load_lds_dwordx4 v[162:163], off
	s_waitcnt vmcnt(6)
	s_barrier
	s_setprio 1
	v_mfma_f32_16x16x32_bf16 v[28:31], v[210:213], v[178:181], v[28:31]
	v_mfma_f32_16x16x32_bf16 v[24:27], v[218:221], v[178:181], v[24:27]
	v_mfma_f32_16x16x32_bf16 v[20:23], v[210:213], v[186:189], v[20:23]
	v_mfma_f32_16x16x32_bf16 v[16:19], v[218:221], v[186:189], v[16:19]
	v_mfma_f32_16x16x32_bf16 v[12:15], v[210:213], v[194:197], v[12:15]
	v_mfma_f32_16x16x32_bf16 v[8:11], v[218:221], v[194:197], v[8:11]
	v_mfma_f32_16x16x32_bf16 v[4:7], v[210:213], v[202:205], v[4:7]
	v_mfma_f32_16x16x32_bf16 v[0:3], v[218:221], v[202:205], v[0:3]
	v_mfma_f32_16x16x32_bf16 v[28:31], v[214:217], v[182:185], v[28:31]
	v_mfma_f32_16x16x32_bf16 v[24:27], v[222:225], v[182:185], v[24:27]
	v_mfma_f32_16x16x32_bf16 v[20:23], v[214:217], v[190:193], v[20:23]
	v_mfma_f32_16x16x32_bf16 v[16:19], v[222:225], v[190:193], v[16:19]
	v_mfma_f32_16x16x32_bf16 v[12:15], v[214:217], v[198:201], v[12:15]
	v_mfma_f32_16x16x32_bf16 v[8:11], v[222:225], v[198:201], v[8:11]
	v_mfma_f32_16x16x32_bf16 v[4:7], v[214:217], v[206:209], v[4:7]
	v_mfma_f32_16x16x32_bf16 v[0:3], v[222:225], v[206:209], v[0:3]
	s_setprio 0
	s_add_i32 s75, s75, 2
	s_add_u32 s34, s34, 0x100
	s_addc_u32 s35, s35, 0
	s_cmp_lt_u32 s75, 60
	s_barrier
	s_cbranch_scc1 .LBB0_96
	s_mov_b64 s[34:35], 0x101f80
	s_mov_b32 m0, s77
	ds_read_b128 v[162:165], v141
	ds_read_b128 v[166:169], v142
	ds_read_b128 v[170:173], v143
	ds_read_b128 v[174:177], v144
	ds_read_b128 v[178:181], v160
	ds_read_b128 v[182:185], v160 offset:1024
	ds_read_b128 v[186:189], v160 offset:2048
	ds_read_b128 v[190:193], v160 offset:3072
	ds_read_b128 v[194:197], v160 offset:4096
	ds_read_b128 v[198:201], v160 offset:5120
	ds_read_b128 v[202:205], v160 offset:6144
	ds_read_b128 v[206:209], v160 offset:7168
	s_nop 0
	v_lshl_add_u64 v[134:135], v[134:135], 0, s[34:35]
	global_load_lds_dwordx4 v[134:135], off
	v_lshl_add_u64 v[134:135], v[134:135], 0, s[0:1]
	s_mov_b32 m0, s68
	s_nop 0
	global_load_lds_dwordx4 v[134:135], off
	s_barrier
	s_waitcnt lgkmcnt(0)
	s_setprio 1
	s_waitcnt lgkmcnt(0)
	v_mfma_f32_16x16x32_bf16 v[124:127], v[162:165], v[178:181], v[124:127]
	v_mfma_f32_16x16x32_bf16 v[116:119], v[162:165], v[186:189], v[116:119]
	v_mfma_f32_16x16x32_bf16 v[112:115], v[170:173], v[186:189], v[112:115]
	v_mfma_f32_16x16x32_bf16 v[100:103], v[162:165], v[202:205], v[100:103]
	v_mfma_f32_16x16x32_bf16 v[96:99], v[170:173], v[202:205], v[96:99]
	v_mfma_f32_16x16x32_bf16 v[124:127], v[166:169], v[182:185], v[124:127]
	v_mfma_f32_16x16x32_bf16 v[120:123], v[170:173], v[178:181], v[120:123]
	v_mfma_f32_16x16x32_bf16 v[116:119], v[166:169], v[190:193], v[116:119]
	v_mfma_f32_16x16x32_bf16 v[112:115], v[174:177], v[190:193], v[112:115]
	v_mfma_f32_16x16x32_bf16 v[108:111], v[162:165], v[194:197], v[108:111]
	v_mfma_f32_16x16x32_bf16 v[104:107], v[170:173], v[194:197], v[104:107]
	v_mfma_f32_16x16x32_bf16 v[100:103], v[166:169], v[206:209], v[100:103]
	v_mfma_f32_16x16x32_bf16 v[96:99], v[174:177], v[206:209], v[96:99]
	v_mfma_f32_16x16x32_bf16 v[134:137], v[174:177], v[182:185], v[120:123]
	v_mfma_f32_16x16x32_bf16 v[210:213], v[166:169], v[198:201], v[108:111]
	v_mfma_f32_16x16x32_bf16 v[214:217], v[174:177], v[198:201], v[104:107]
	s_setprio 0
	s_barrier
	s_nop 0
	ds_read_b128 v[104:107], v145
	ds_read_b128 v[108:111], v146
	ds_read_b128 v[120:123], v147
	ds_read_b128 v[218:221], v148
	s_barrier
	s_waitcnt lgkmcnt(0)
	s_setprio 1
	s_waitcnt lgkmcnt(0)
	v_mfma_f32_16x16x32_bf16 v[84:87], v[104:107], v[186:189], v[84:87]
	v_mfma_f32_16x16x32_bf16 v[80:83], v[120:123], v[186:189], v[80:83]
	v_mfma_f32_16x16x32_bf16 v[68:71], v[104:107], v[202:205], v[68:71]
	v_mfma_f32_16x16x32_bf16 v[92:95], v[104:107], v[178:181], v[92:95]
	v_mfma_f32_16x16x32_bf16 v[88:91], v[120:123], v[178:181], v[88:91]
	v_mfma_f32_16x16x32_bf16 v[84:87], v[108:111], v[190:193], v[84:87]
	v_mfma_f32_16x16x32_bf16 v[80:83], v[218:221], v[190:193], v[80:83]
	v_mfma_f32_16x16x32_bf16 v[76:79], v[104:107], v[194:197], v[76:79]
	v_mfma_f32_16x16x32_bf16 v[72:75], v[120:123], v[194:197], v[72:75]
	v_mfma_f32_16x16x32_bf16 v[68:71], v[108:111], v[206:209], v[68:71]
	v_mfma_f32_16x16x32_bf16 v[64:67], v[120:123], v[202:205], v[64:67]
	v_mfma_f32_16x16x32_bf16 v[222:225], v[108:111], v[182:185], v[92:95]
	v_mfma_f32_16x16x32_bf16 v[178:181], v[218:221], v[182:185], v[88:91]
	v_mfma_f32_16x16x32_bf16 v[182:185], v[108:111], v[198:201], v[76:79]
	v_mfma_f32_16x16x32_bf16 v[186:189], v[218:221], v[198:201], v[72:75]
	v_mfma_f32_16x16x32_bf16 v[190:193], v[218:221], v[206:209], v[64:67]
	s_setprio 0
	s_barrier
; #define LDA(dst, b, h) for (int m = 0; m < 4; ++m) for (int k = 0; k < 2; ++k) \
;     dst[m][k] = *reinterpret_cast<const bf16x8*>(aRd + (((b) * 2 + (h)) * G_HT * 2 + m * 2048 + k * 1024))
; #define LDB(dst, b, h) for (int n = 0; n < 2; ++n) for (int k = 0; k < 2; ++k) \
;     dst[n][k] = *reinterpret_cast<const bf16x8*>(bRd + (((b) * 2 + (h)) * G_HT * 2 + n * 2048 + k * 1024))
; #define MMA(ai, bj, At, Bx) do { __builtin_amdgcn_s_setprio(1); \
;     for (int m = 0; m < 4; ++m) for (int n = 0; n < 2; ++n) for (int k = 0; k < 2; ++k) \
;       acc[ai][bj][m][n] = __builtin_amdgcn_mfma_f32_16x16x32_bf16(Bx[n][k], At[m][k], acc[ai][bj][m][n], 0, 0, 0);     \
;     __builtin_amdgcn_s_setprio(0); } while (0)
; #define WAIT_V(n) asm volatile("s_waitcnt vmcnt(" #n ")" ::: "memory")
; #define WAIT_L(n) asm volatile("s_waitcnt lgkmcnt(" #n ")" ::: "memory")
; #define BAR __builtin_amdgcn_s_barrier()
; template <int EPI>
; __device__ __forceinline__ void gemm_tile(const bf16* __restrict__ A, int lda, const bf16* __restrict__ Bt, int K,
;                                           int brow, int bcol, const EpiArgs& ea, char* shmc, bool has_next, int nbrow, int nbcol, bool first_tile) {
;     ...
;     LDA(At, 0, 1); WAIT_V(4); BAR; WAIT_L(0); MMA(1, 0, At, B0); MMA(1, 1, At, B1); BAR; }
;   { LDB(B0, 1, 0); LDA(At, 1, 0); WAIT_V(2); BAR; WAIT_L(0); MMA(0, 0, At, B0); BAR;
	s_nop 0
	ds_read_b128 v[64:67], v160 offset:16384
	ds_read_b128 v[72:75], v160 offset:17408
	ds_read_b128 v[76:79], v160 offset:18432
	ds_read_b128 v[88:91], v160 offset:19456
	ds_read_b128 v[92:95], v160 offset:20480
	ds_read_b128 v[194:197], v160 offset:21504
	ds_read_b128 v[198:201], v160 offset:22528
	ds_read_b128 v[202:205], v160 offset:23552
	s_waitcnt vmcnt(4)
	s_barrier
	s_waitcnt lgkmcnt(0)
	s_setprio 1
	s_waitcnt lgkmcnt(0)
	v_mfma_f32_16x16x32_bf16 v[60:63], v[162:165], v[64:67], v[60:63]
	v_mfma_f32_16x16x32_bf16 v[52:55], v[162:165], v[76:79], v[52:55]
	v_mfma_f32_16x16x32_bf16 v[48:51], v[170:173], v[76:79], v[48:51]
	v_mfma_f32_16x16x32_bf16 v[36:39], v[162:165], v[198:201], v[36:39]
	v_mfma_f32_16x16x32_bf16 v[32:35], v[170:173], v[198:201], v[32:35]
	v_mfma_f32_16x16x32_bf16 v[60:63], v[166:169], v[72:75], v[60:63]
	v_mfma_f32_16x16x32_bf16 v[56:59], v[170:173], v[64:67], v[56:59]
	v_mfma_f32_16x16x32_bf16 v[52:55], v[166:169], v[88:91], v[52:55]
	v_mfma_f32_16x16x32_bf16 v[48:51], v[174:177], v[88:91], v[48:51]
	v_mfma_f32_16x16x32_bf16 v[44:47], v[162:165], v[92:95], v[44:47]
	v_mfma_f32_16x16x32_bf16 v[40:43], v[170:173], v[92:95], v[40:43]
	v_mfma_f32_16x16x32_bf16 v[36:39], v[166:169], v[202:205], v[36:39]
	v_mfma_f32_16x16x32_bf16 v[32:35], v[174:177], v[202:205], v[32:35]
	v_mfma_f32_16x16x32_bf16 v[206:209], v[174:177], v[72:75], v[56:59]
	v_mfma_f32_16x16x32_bf16 v[226:229], v[166:169], v[194:197], v[44:47]
	v_mfma_f32_16x16x32_bf16 v[230:233], v[174:177], v[194:197], v[40:43]
	s_setprio 0
	s_setprio 1
	v_mfma_f32_16x16x32_bf16 v[20:23], v[104:107], v[76:79], v[20:23]
	v_mfma_f32_16x16x32_bf16 v[16:19], v[120:123], v[76:79], v[16:19]
	v_mfma_f32_16x16x32_bf16 v[4:7], v[104:107], v[198:201], v[4:7]
	v_mfma_f32_16x16x32_bf16 v[28:31], v[104:107], v[64:67], v[28:31]
	v_mfma_f32_16x16x32_bf16 v[24:27], v[120:123], v[64:67], v[24:27]
	v_mfma_f32_16x16x32_bf16 v[20:23], v[108:111], v[88:91], v[20:23]
	v_mfma_f32_16x16x32_bf16 v[16:19], v[218:221], v[88:91], v[16:19]
	v_mfma_f32_16x16x32_bf16 v[12:15], v[104:107], v[92:95], v[12:15]
	v_mfma_f32_16x16x32_bf16 v[8:11], v[120:123], v[92:95], v[8:11]
	v_mfma_f32_16x16x32_bf16 v[4:7], v[108:111], v[202:205], v[4:7]
	v_mfma_f32_16x16x32_bf16 v[0:3], v[120:123], v[198:201], v[0:3]
	v_mfma_f32_16x16x32_bf16 v[162:165], v[108:111], v[72:75], v[28:31]
	v_mfma_f32_16x16x32_bf16 v[166:169], v[218:221], v[72:75], v[24:27]
	v_mfma_f32_16x16x32_bf16 v[170:173], v[108:111], v[194:197], v[12:15]
	v_mfma_f32_16x16x32_bf16 v[174:177], v[218:221], v[194:197], v[8:11]
	v_mfma_f32_16x16x32_bf16 v[194:197], v[218:221], v[202:205], v[0:3]
	s_setprio 0
	s_barrier
	s_nop 0
	ds_read_b128 v[0:3], v149
	ds_read_b128 v[8:11], v150
	ds_read_b128 v[12:15], v151
	ds_read_b128 v[198:201], v152
	ds_read_b128 v[24:27], v160 offset:32768
	ds_read_b128 v[28:31], v160 offset:33792
	ds_read_b128 v[40:43], v160 offset:34816
	ds_read_b128 v[44:47], v160 offset:35840
	ds_read_b128 v[56:59], v160 offset:36864
	ds_read_b128 v[64:67], v160 offset:37888
	ds_read_b128 v[202:205], v160 offset:38912
	ds_read_b128 v[218:221], v160 offset:39936
	s_waitcnt vmcnt(2)
	s_barrier
	s_waitcnt lgkmcnt(0)
	s_setprio 1
	s_waitcnt lgkmcnt(0)
	v_mfma_f32_16x16x32_bf16 v[72:75], v[0:3], v[24:27], v[124:127]
	v_mfma_f32_16x16x32_bf16 v[120:123], v[8:11], v[28:31], v[72:75]
	v_mfma_f32_16x16x32_bf16 v[72:75], v[12:15], v[24:27], v[134:137]
	v_mfma_f32_16x16x32_bf16 v[124:127], v[198:201], v[28:31], v[72:75]
	v_mfma_f32_16x16x32_bf16 v[72:75], v[0:3], v[40:43], v[116:119]
	v_mfma_f32_16x16x32_bf16 v[104:107], v[8:11], v[44:47], v[72:75]
	v_mfma_f32_16x16x32_bf16 v[72:75], v[12:15], v[40:43], v[112:115]
	v_mfma_f32_16x16x32_bf16 v[108:111], v[198:201], v[44:47], v[72:75]
	v_mfma_f32_16x16x32_bf16 v[72:75], v[0:3], v[56:59], v[210:213]
	v_mfma_f32_16x16x32_bf16 v[88:91], v[8:11], v[64:67], v[72:75]
	v_mfma_f32_16x16x32_bf16 v[72:75], v[12:15], v[56:59], v[214:217]
	v_mfma_f32_16x16x32_bf16 v[92:95], v[198:201], v[64:67], v[72:75]
	v_mfma_f32_16x16x32_bf16 v[72:75], v[0:3], v[202:205], v[100:103]
	v_mfma_f32_16x16x32_bf16 v[76:79], v[12:15], v[202:205], v[96:99]
	v_mfma_f32_16x16x32_bf16 v[72:75], v[8:11], v[218:221], v[72:75]
	v_mfma_f32_16x16x32_bf16 v[76:79], v[198:201], v[218:221], v[76:79]
	s_setprio 0
	s_barrier
; #define LDA(dst, b, h) for (int m = 0; m < 4; ++m) for (int k = 0; k < 2; ++k) \
;     dst[m][k] = *reinterpret_cast<const bf16x8*>(aRd + (((b) * 2 + (h)) * G_HT * 2 + m * 2048 + k * 1024))
; #define LDB(dst, b, h) for (int n = 0; n < 2; ++n) for (int k = 0; k < 2; ++k) \
;     dst[n][k] = *reinterpret_cast<const bf16x8*>(bRd + (((b) * 2 + (h)) * G_HT * 2 + n * 2048 + k * 1024))
; #define MMA(ai, bj, At, Bx) do { __builtin_amdgcn_s_setprio(1); \
;     for (int m = 0; m < 4; ++m) for (int n = 0; n < 2; ++n) for (int k = 0; k < 2; ++k) \
;       acc[ai][bj][m][n] = __builtin_amdgcn_mfma_f32_16x16x32_bf16(Bx[n][k], At[m][k], acc[ai][bj][m][n], 0, 0, 0);     \
;     __builtin_amdgcn_s_setprio(0); } while (0)
; #define WAIT_V(n) asm volatile("s_waitcnt vmcnt(" #n ")" ::: "memory")
; #define WAIT_L(n) asm volatile("s_waitcnt lgkmcnt(" #n ")" ::: "memory")
; #define BAR __builtin_amdgcn_s_barrier()
; template <int EPI>
; __device__ __forceinline__ void gemm_tile(const bf16* __restrict__ A, int lda, const bf16* __restrict__ Bt, int K,
;                                           int brow, int bcol, const EpiArgs& ea, char* shmc, bool has_next, int nbrow, int nbcol, bool first_tile) {
;     ...
;   { LDB(B0, 1, 0); LDA(At, 1, 0); WAIT_V(2); BAR; WAIT_L(0); MMA(0, 0, At, B0); BAR;
;     LDB(B1, 1, 1); WAIT_V(0); BAR; WAIT_L(0); MMA(0, 1, At, B1); BAR;
;     LDA(At, 1, 1); BAR; WAIT_L(0); MMA(1, 0, At, B0); MMA(1, 1, At, B1); BAR; }
;   if (wr == 0) BAR;
	ds_read_b128 v[134:137], v153
	ds_read_b128 v[210:213], v154
	ds_read_b128 v[214:217], v155
	ds_read_b128 v[234:237], v156
	s_waitcnt vmcnt(0)
	s_barrier
	s_waitcnt lgkmcnt(0)
	s_setprio 1
	s_waitcnt lgkmcnt(0)
	v_mfma_f32_16x16x32_bf16 v[96:99], v[134:137], v[24:27], v[222:225]
	v_mfma_f32_16x16x32_bf16 v[24:27], v[214:217], v[24:27], v[178:181]
	v_mfma_f32_16x16x32_bf16 v[116:119], v[234:237], v[28:31], v[24:27]
	v_mfma_f32_16x16x32_bf16 v[24:27], v[134:137], v[40:43], v[84:87]
	v_mfma_f32_16x16x32_bf16 v[112:115], v[210:213], v[28:31], v[96:99]
	v_mfma_f32_16x16x32_bf16 v[96:99], v[210:213], v[44:47], v[24:27]
	v_mfma_f32_16x16x32_bf16 v[24:27], v[214:217], v[40:43], v[80:83]
	v_mfma_f32_16x16x32_bf16 v[100:103], v[234:237], v[44:47], v[24:27]
	v_mfma_f32_16x16x32_bf16 v[24:27], v[134:137], v[56:59], v[182:185]
	v_mfma_f32_16x16x32_bf16 v[80:83], v[210:213], v[64:67], v[24:27]
	v_mfma_f32_16x16x32_bf16 v[24:27], v[214:217], v[56:59], v[186:189]
	v_mfma_f32_16x16x32_bf16 v[84:87], v[234:237], v[64:67], v[24:27]
	v_mfma_f32_16x16x32_bf16 v[24:27], v[134:137], v[202:205], v[68:71]
	v_mfma_f32_16x16x32_bf16 v[64:67], v[210:213], v[218:221], v[24:27]
	v_mfma_f32_16x16x32_bf16 v[24:27], v[214:217], v[202:205], v[190:193]
	v_mfma_f32_16x16x32_bf16 v[68:71], v[234:237], v[218:221], v[24:27]
	s_setprio 0
	s_barrier
	ds_read_b128 v[178:181], v160 offset:49152
	ds_read_b128 v[182:185], v160 offset:50176
	ds_read_b128 v[186:189], v160 offset:51200
	ds_read_b128 v[190:193], v160 offset:52224
	ds_read_b128 v[202:205], v160 offset:53248
	ds_read_b128 v[218:221], v160 offset:54272
	ds_read_b128 v[222:225], v160 offset:55296
	ds_read_b128 v[238:241], v160 offset:56320
	s_barrier
	s_waitcnt lgkmcnt(0)
	s_setprio 1
	s_waitcnt lgkmcnt(0)
	v_mfma_f32_16x16x32_bf16 v[24:27], v[0:3], v[178:181], v[60:63]
	v_mfma_f32_16x16x32_bf16 v[56:59], v[8:11], v[182:185], v[24:27]
	v_mfma_f32_16x16x32_bf16 v[24:27], v[12:15], v[178:181], v[206:209]
	v_mfma_f32_16x16x32_bf16 v[60:63], v[198:201], v[182:185], v[24:27]
	v_mfma_f32_16x16x32_bf16 v[24:27], v[0:3], v[186:189], v[52:55]
	v_mfma_f32_16x16x32_bf16 v[40:43], v[8:11], v[190:193], v[24:27]
	v_mfma_f32_16x16x32_bf16 v[24:27], v[12:15], v[186:189], v[48:51]
	v_mfma_f32_16x16x32_bf16 v[44:47], v[198:201], v[190:193], v[24:27]
	v_mfma_f32_16x16x32_bf16 v[24:27], v[0:3], v[202:205], v[226:229]
	v_mfma_f32_16x16x32_bf16 v[0:3], v[0:3], v[222:225], v[36:39]
	v_mfma_f32_16x16x32_bf16 v[24:27], v[8:11], v[218:221], v[24:27]
	v_mfma_f32_16x16x32_bf16 v[28:31], v[12:15], v[202:205], v[230:233]
	v_mfma_f32_16x16x32_bf16 v[8:11], v[8:11], v[238:241], v[0:3]
	v_mfma_f32_16x16x32_bf16 v[0:3], v[12:15], v[222:225], v[32:35]
	v_mfma_f32_16x16x32_bf16 v[28:31], v[198:201], v[218:221], v[28:31]
	v_mfma_f32_16x16x32_bf16 v[12:15], v[198:201], v[238:241], v[0:3]
	s_setprio 0
	s_setprio 1
	v_mfma_f32_16x16x32_bf16 v[0:3], v[134:137], v[178:181], v[162:165]
	v_mfma_f32_16x16x32_bf16 v[48:51], v[210:213], v[182:185], v[0:3]
	v_mfma_f32_16x16x32_bf16 v[0:3], v[214:217], v[178:181], v[166:169]
	v_mfma_f32_16x16x32_bf16 v[52:55], v[234:237], v[182:185], v[0:3]
	v_mfma_f32_16x16x32_bf16 v[0:3], v[134:137], v[186:189], v[20:23]
	v_mfma_f32_16x16x32_bf16 v[32:35], v[210:213], v[190:193], v[0:3]
	v_mfma_f32_16x16x32_bf16 v[0:3], v[214:217], v[186:189], v[16:19]
	v_mfma_f32_16x16x32_bf16 v[36:39], v[234:237], v[190:193], v[0:3]
	v_mfma_f32_16x16x32_bf16 v[0:3], v[134:137], v[202:205], v[170:173]
	v_mfma_f32_16x16x32_bf16 v[16:19], v[210:213], v[218:221], v[0:3]
	v_mfma_f32_16x16x32_bf16 v[0:3], v[214:217], v[202:205], v[174:177]
	v_mfma_f32_16x16x32_bf16 v[20:23], v[234:237], v[218:221], v[0:3]
	v_mfma_f32_16x16x32_bf16 v[0:3], v[134:137], v[222:225], v[4:7]
	v_mfma_f32_16x16x32_bf16 v[4:7], v[214:217], v[222:225], v[194:197]
	v_mfma_f32_16x16x32_bf16 v[0:3], v[210:213], v[238:241], v[0:3]
	v_mfma_f32_16x16x32_bf16 v[4:7], v[234:237], v[238:241], v[4:7]
	s_setprio 0
	s_barrier
	s_and_saveexec_b64 s[34:35], s[4:5]
	s_cbranch_execz .LBB0_99
	s_barrier

; #define STA(b, h, half, kt) STAGE(((b) * 2 + (h)) * G_HT * 2, pA, ((size_t)(half) * G_HALF * lda + (size_t)(kt) * G_BK) * 2, lda)
; #define STB(b, h, half, kt) STAGE((4 + (b) * 2 + (h)) * G_HT * 2, pB, ((size_t)(half) * G_HALF * K + (size_t)(kt) * G_BK) * 2, K)
; #define LDA(dst, b, h) for (int m = 0; m < 4; ++m) for (int k = 0; k < 2; ++k) \
;     dst[m][k] = *reinterpret_cast<const bf16x8*>(aRd + (((b) * 2 + (h)) * G_HT * 2 + m * 2048 + k * 1024))
; #define LDB(dst, b, h) for (int n = 0; n < 2; ++n) for (int k = 0; k < 2; ++k) \
;     dst[n][k] = *reinterpret_cast<const bf16x8*>(bRd + (((b) * 2 + (h)) * G_HT * 2 + n * 2048 + k * 1024))
; #define MMA(ai, bj, At, Bx) do { __builtin_amdgcn_s_setprio(1); \
;     for (int m = 0; m < 4; ++m) for (int n = 0; n < 2; ++n) for (int k = 0; k < 2; ++k) \
;       acc[ai][bj][m][n] = __builtin_amdgcn_mfma_f32_16x16x32_bf16(Bx[n][k], At[m][k], acc[ai][bj][m][n], 0, 0, 0);     \
;     __builtin_amdgcn_s_setprio(0); } while (0)
; #define WAIT_V(n) asm volatile("s_waitcnt vmcnt(" #n ")" ::: "memory")
; #define WAIT_L(n) asm volatile("s_waitcnt lgkmcnt(" #n ")" ::: "memory")
; #define BAR __builtin_amdgcn_s_barrier()
; #define SCHED __builtin_amdgcn_sched_barrier(0)
; template <int EPI>
; __device__ __forceinline__ void gemm_tile(const bf16* __restrict__ A, int lda, const bf16* __restrict__ Bt, int K,
;                                           int brow, int bcol, const EpiArgs& ea, char* shmc, bool has_next, int nbrow, int nbcol, bool first_tile) {
;     ...
;   for (int t = 0; t < nt - 2; t += 2) {
;     LDB(B0, 0, 0); SCHED; LDA(At, 0, 0); STA(1, 1, 1, t + 1);
;     WAIT_L(8); BAR; WAIT_L(0); MMA(0, 0, At, B0); BAR; SCHED;
;     LDB(B1, 0, 1); STB(0, 0, 0, t + 2);
;     BAR; WAIT_L(0); MMA(0, 1, At, B1); BAR;
;     LDA(At, 0, 1); STA(0, 0, 0, t + 2);
;     BAR; WAIT_L(0); MMA(1, 0, At, B0); BAR; SCHED;
;     STB(0, 1, 1, t + 2);
;     WAIT_V(6); BAR; MMA(1, 1, At, B1); BAR;
.LBB0_291:
	ds_read_b128 v[160:163], v137
	ds_read_b128 v[164:167], v138
	ds_read_b128 v[168:171], v139
	ds_read_b128 v[172:175], v140
	s_add_u32 s80, s18, 0xffffff80
	s_addc_u32 s81, s19, -1
	s_mov_b32 m0, s72
	ds_read_b128 v[176:179], v158
	ds_read_b128 v[180:183], v158 offset:1024
	ds_read_b128 v[184:187], v158 offset:2048
	ds_read_b128 v[188:191], v158 offset:3072
	ds_read_b128 v[192:195], v158 offset:4096
	ds_read_b128 v[196:199], v158 offset:5120
	ds_read_b128 v[200:203], v158 offset:6144
	ds_read_b128 v[204:207], v158 offset:7168
	v_lshl_add_u64 v[208:209], v[132:133], 0, s[80:81]
	global_load_lds_dwordx4 v[208:209], off
	s_mov_b32 m0, s62
	v_lshl_add_u64 v[208:209], v[208:209], 0, s[10:11]
	global_load_lds_dwordx4 v[208:209], off
	s_waitcnt lgkmcnt(8)
	s_barrier
	s_waitcnt lgkmcnt(0)
	s_setprio 1
	v_mfma_f32_16x16x32_bf16 v[124:127], v[160:163], v[176:179], v[124:127]
	v_mfma_f32_16x16x32_bf16 v[120:123], v[168:171], v[176:179], v[120:123]
	v_mfma_f32_16x16x32_bf16 v[116:119], v[160:163], v[184:187], v[116:119]
	v_mfma_f32_16x16x32_bf16 v[112:115], v[168:171], v[184:187], v[112:115]
	v_mfma_f32_16x16x32_bf16 v[108:111], v[160:163], v[192:195], v[108:111]
	v_mfma_f32_16x16x32_bf16 v[104:107], v[168:171], v[192:195], v[104:107]
	v_mfma_f32_16x16x32_bf16 v[100:103], v[160:163], v[200:203], v[100:103]
	v_mfma_f32_16x16x32_bf16 v[96:99], v[168:171], v[200:203], v[96:99]
	v_mfma_f32_16x16x32_bf16 v[124:127], v[164:167], v[180:183], v[124:127]
	v_mfma_f32_16x16x32_bf16 v[120:123], v[172:175], v[180:183], v[120:123]
	v_mfma_f32_16x16x32_bf16 v[116:119], v[164:167], v[188:191], v[116:119]
	v_mfma_f32_16x16x32_bf16 v[112:115], v[172:175], v[188:191], v[112:115]
	v_mfma_f32_16x16x32_bf16 v[108:111], v[164:167], v[196:199], v[108:111]
	v_mfma_f32_16x16x32_bf16 v[104:107], v[172:175], v[196:199], v[104:107]
	v_mfma_f32_16x16x32_bf16 v[100:103], v[164:167], v[204:207], v[100:103]
	v_mfma_f32_16x16x32_bf16 v[96:99], v[172:175], v[204:207], v[96:99]
	s_setprio 0
	s_barrier
	s_add_u32 s80, s18, 0xfffa0000
	s_addc_u32 s81, s19, -1
	s_mov_b64 s[82:83], s[80:81]
	s_mov_b32 m0, s67
	ds_read_b128 v[208:211], v141
	ds_read_b128 v[212:215], v142
	ds_read_b128 v[216:219], v143
	ds_read_b128 v[220:223], v144
	v_lshl_add_u64 v[224:225], v[134:135], 0, s[82:83]
	global_load_lds_dwordx4 v[224:225], off
	s_mov_b32 m0, s68
	v_lshl_add_u64 v[224:225], v[224:225], 0, s[8:9]
	global_load_lds_dwordx4 v[224:225], off
	s_barrier
	s_waitcnt lgkmcnt(0)
	s_setprio 1
	v_mfma_f32_16x16x32_bf16 v[92:95], v[208:211], v[176:179], v[92:95]
	v_mfma_f32_16x16x32_bf16 v[88:91], v[216:219], v[176:179], v[88:91]
	v_mfma_f32_16x16x32_bf16 v[84:87], v[208:211], v[184:187], v[84:87]
	v_mfma_f32_16x16x32_bf16 v[80:83], v[216:219], v[184:187], v[80:83]
	v_mfma_f32_16x16x32_bf16 v[76:79], v[208:211], v[192:195], v[76:79]
	v_mfma_f32_16x16x32_bf16 v[72:75], v[216:219], v[192:195], v[72:75]
	v_mfma_f32_16x16x32_bf16 v[68:71], v[208:211], v[200:203], v[68:71]
	v_mfma_f32_16x16x32_bf16 v[64:67], v[216:219], v[200:203], v[64:67]
	v_mfma_f32_16x16x32_bf16 v[92:95], v[212:215], v[180:183], v[92:95]
	v_mfma_f32_16x16x32_bf16 v[88:91], v[220:223], v[180:183], v[88:91]
	v_mfma_f32_16x16x32_bf16 v[84:87], v[212:215], v[188:191], v[84:87]
	v_mfma_f32_16x16x32_bf16 v[80:83], v[220:223], v[188:191], v[80:83]
	v_mfma_f32_16x16x32_bf16 v[76:79], v[212:215], v[196:199], v[76:79]
	v_mfma_f32_16x16x32_bf16 v[72:75], v[220:223], v[196:199], v[72:75]
	v_mfma_f32_16x16x32_bf16 v[68:71], v[212:215], v[204:207], v[68:71]
	v_mfma_f32_16x16x32_bf16 v[64:67], v[220:223], v[204:207], v[64:67]
	s_setprio 0
	s_mov_b32 m0, s31
	s_barrier
	ds_read_b128 v[176:179], v158 offset:16384
	ds_read_b128 v[180:183], v158 offset:17408
	ds_read_b128 v[184:187], v158 offset:18432
	ds_read_b128 v[188:191], v158 offset:19456
	ds_read_b128 v[192:195], v158 offset:20480
	ds_read_b128 v[196:199], v158 offset:21504
	ds_read_b128 v[200:203], v158 offset:22528
	ds_read_b128 v[204:207], v158 offset:23552
	v_lshl_add_u64 v[224:225], v[132:133], 0, s[80:81]
	global_load_lds_dwordx4 v[224:225], off
	s_mov_b32 m0, s73
	v_lshl_add_u64 v[224:225], v[224:225], 0, s[10:11]
	global_load_lds_dwordx4 v[224:225], off
	s_barrier
	s_waitcnt lgkmcnt(0)
	s_setprio 1
	v_mfma_f32_16x16x32_bf16 v[60:63], v[160:163], v[176:179], v[60:63]
	v_mfma_f32_16x16x32_bf16 v[56:59], v[168:171], v[176:179], v[56:59]
	v_mfma_f32_16x16x32_bf16 v[52:55], v[160:163], v[184:187], v[52:55]
	v_mfma_f32_16x16x32_bf16 v[48:51], v[168:171], v[184:187], v[48:51]
	v_mfma_f32_16x16x32_bf16 v[44:47], v[160:163], v[192:195], v[44:47]
	v_mfma_f32_16x16x32_bf16 v[40:43], v[168:171], v[192:195], v[40:43]
	v_mfma_f32_16x16x32_bf16 v[36:39], v[160:163], v[200:203], v[36:39]
	v_mfma_f32_16x16x32_bf16 v[32:35], v[168:171], v[200:203], v[32:35]
	v_mfma_f32_16x16x32_bf16 v[60:63], v[164:167], v[180:183], v[60:63]
	v_mfma_f32_16x16x32_bf16 v[56:59], v[172:175], v[180:183], v[56:59]
	v_mfma_f32_16x16x32_bf16 v[52:55], v[164:167], v[188:191], v[52:55]
	v_mfma_f32_16x16x32_bf16 v[48:51], v[172:175], v[188:191], v[48:51]
	v_mfma_f32_16x16x32_bf16 v[44:47], v[164:167], v[196:199], v[44:47]
	v_mfma_f32_16x16x32_bf16 v[40:43], v[172:175], v[196:199], v[40:43]
	v_mfma_f32_16x16x32_bf16 v[36:39], v[164:167], v[204:207], v[36:39]
	v_mfma_f32_16x16x32_bf16 v[32:35], v[172:175], v[204:207], v[32:35]
	s_setprio 0
	s_barrier
	s_add_u32 s80, s18, 0xfffd0000
	s_addc_u32 s81, s19, -1
	s_mov_b32 m0, s69
	v_lshl_add_u64 v[160:161], v[134:135], 0, s[80:81]
	global_load_lds_dwordx4 v[160:161], off
	s_mov_b32 m0, s70
	v_lshl_add_u64 v[160:161], v[160:161], 0, s[8:9]
	global_load_lds_dwordx4 v[160:161], off
	s_waitcnt vmcnt(6)
	s_barrier
; #define STA(b, h, half, kt) STAGE(((b) * 2 + (h)) * G_HT * 2, pA, ((size_t)(half) * G_HALF * lda + (size_t)(kt) * G_BK) * 2, lda)
; #define STB(b, h, half, kt) STAGE((4 + (b) * 2 + (h)) * G_HT * 2, pB, ((size_t)(half) * G_HALF * K + (size_t)(kt) * G_BK) * 2, K)
; #define LDA(dst, b, h) for (int m = 0; m < 4; ++m) for (int k = 0; k < 2; ++k) \
;     dst[m][k] = *reinterpret_cast<const bf16x8*>(aRd + (((b) * 2 + (h)) * G_HT * 2 + m * 2048 + k * 1024))
; #define LDB(dst, b, h) for (int n = 0; n < 2; ++n) for (int k = 0; k < 2; ++k) \
;     dst[n][k] = *reinterpret_cast<const bf16x8*>(bRd + (((b) * 2 + (h)) * G_HT * 2 + n * 2048 + k * 1024))
; #define MMA(ai, bj, At, Bx) do { __builtin_amdgcn_s_setprio(1); \
;     for (int m = 0; m < 4; ++m) for (int n = 0; n < 2; ++n) for (int k = 0; k < 2; ++k) \
;       acc[ai][bj][m][n] = __builtin_amdgcn_mfma_f32_16x16x32_bf16(Bx[n][k], At[m][k], acc[ai][bj][m][n], 0, 0, 0);     \
;     __builtin_amdgcn_s_setprio(0); } while (0)
; #define WAIT_V(n) asm volatile("s_waitcnt vmcnt(" #n ")" ::: "memory")
; #define WAIT_L(n) asm volatile("s_waitcnt lgkmcnt(" #n ")" ::: "memory")
; #define BAR __builtin_amdgcn_s_barrier()
; #define SCHED __builtin_amdgcn_sched_barrier(0)
; template <int EPI>
; __device__ __forceinline__ void gemm_tile(const bf16* __restrict__ A, int lda, const bf16* __restrict__ Bt, int K,
;                                           int brow, int bcol, const EpiArgs& ea, char* shmc, bool has_next, int nbrow, int nbcol, bool first_tile) {
;     ...
;     WAIT_V(6); BAR; MMA(1, 1, At, B1); BAR;
;     LDB(B0, 1, 0); SCHED; LDA(At, 1, 0); STA(0, 1, 1, t + 2);
;     WAIT_L(8); BAR; WAIT_L(0); MMA(0, 0, At, B0); BAR; SCHED;
;     LDB(B1, 1, 1); STB(1, 0, 0, t + 3);
;     BAR; WAIT_L(0); MMA(0, 1, At, B1); BAR;
;     LDA(At, 1, 1); STA(1, 0, 0, t + 3);
;     BAR; WAIT_L(0); MMA(1, 0, At, B0); BAR; SCHED;
	s_setprio 1
	v_mfma_f32_16x16x32_bf16 v[28:31], v[208:211], v[176:179], v[28:31]
	v_mfma_f32_16x16x32_bf16 v[24:27], v[216:219], v[176:179], v[24:27]
	v_mfma_f32_16x16x32_bf16 v[20:23], v[208:211], v[184:187], v[20:23]
	v_mfma_f32_16x16x32_bf16 v[16:19], v[216:219], v[184:187], v[16:19]
	v_mfma_f32_16x16x32_bf16 v[12:15], v[208:211], v[192:195], v[12:15]
	v_mfma_f32_16x16x32_bf16 v[8:11], v[216:219], v[192:195], v[8:11]
	v_mfma_f32_16x16x32_bf16 v[4:7], v[208:211], v[200:203], v[4:7]
	v_mfma_f32_16x16x32_bf16 v[0:3], v[216:219], v[200:203], v[0:3]
	v_mfma_f32_16x16x32_bf16 v[28:31], v[212:215], v[180:183], v[28:31]
	v_mfma_f32_16x16x32_bf16 v[24:27], v[220:223], v[180:183], v[24:27]
	v_mfma_f32_16x16x32_bf16 v[20:23], v[212:215], v[188:191], v[20:23]
	v_mfma_f32_16x16x32_bf16 v[16:19], v[220:223], v[188:191], v[16:19]
	v_mfma_f32_16x16x32_bf16 v[12:15], v[212:215], v[196:199], v[12:15]
	v_mfma_f32_16x16x32_bf16 v[8:11], v[220:223], v[196:199], v[8:11]
	v_mfma_f32_16x16x32_bf16 v[4:7], v[212:215], v[204:207], v[4:7]
	v_mfma_f32_16x16x32_bf16 v[0:3], v[220:223], v[204:207], v[0:3]
	s_setprio 0
	s_barrier
	ds_read_b128 v[160:163], v145
	ds_read_b128 v[164:167], v146
	ds_read_b128 v[168:171], v147
	ds_read_b128 v[172:175], v148
	s_mov_b64 s[80:81], s[18:19]
	s_mov_b32 m0, s74
	ds_read_b128 v[176:179], v158 offset:32768
	ds_read_b128 v[180:183], v158 offset:33792
	ds_read_b128 v[184:187], v158 offset:34816
	ds_read_b128 v[188:191], v158 offset:35840
	ds_read_b128 v[192:195], v158 offset:36864
	ds_read_b128 v[196:199], v158 offset:37888
	ds_read_b128 v[200:203], v158 offset:38912
	ds_read_b128 v[204:207], v158 offset:39936
	v_lshl_add_u64 v[208:209], v[132:133], 0, s[80:81]
	global_load_lds_dwordx4 v[208:209], off
	s_mov_b32 m0, s75
	v_lshl_add_u64 v[208:209], v[208:209], 0, s[10:11]
	global_load_lds_dwordx4 v[208:209], off
	s_waitcnt lgkmcnt(8)
	s_barrier
	s_waitcnt lgkmcnt(0)
	s_setprio 1
	v_mfma_f32_16x16x32_bf16 v[124:127], v[160:163], v[176:179], v[124:127]
	v_mfma_f32_16x16x32_bf16 v[120:123], v[168:171], v[176:179], v[120:123]
	v_mfma_f32_16x16x32_bf16 v[116:119], v[160:163], v[184:187], v[116:119]
	v_mfma_f32_16x16x32_bf16 v[112:115], v[168:171], v[184:187], v[112:115]
	v_mfma_f32_16x16x32_bf16 v[108:111], v[160:163], v[192:195], v[108:111]
	v_mfma_f32_16x16x32_bf16 v[104:107], v[168:171], v[192:195], v[104:107]
	v_mfma_f32_16x16x32_bf16 v[100:103], v[160:163], v[200:203], v[100:103]
	v_mfma_f32_16x16x32_bf16 v[96:99], v[168:171], v[200:203], v[96:99]
	v_mfma_f32_16x16x32_bf16 v[124:127], v[164:167], v[180:183], v[124:127]
	v_mfma_f32_16x16x32_bf16 v[120:123], v[172:175], v[180:183], v[120:123]
	v_mfma_f32_16x16x32_bf16 v[116:119], v[164:167], v[188:191], v[116:119]
	v_mfma_f32_16x16x32_bf16 v[112:115], v[172:175], v[188:191], v[112:115]
	v_mfma_f32_16x16x32_bf16 v[108:111], v[164:167], v[196:199], v[108:111]
	v_mfma_f32_16x16x32_bf16 v[104:107], v[172:175], v[196:199], v[104:107]
	v_mfma_f32_16x16x32_bf16 v[100:103], v[164:167], v[204:207], v[100:103]
	v_mfma_f32_16x16x32_bf16 v[96:99], v[172:175], v[204:207], v[96:99]
	s_setprio 0
	s_barrier
	s_add_u32 s80, s18, 0xfffa0080
	s_addc_u32 s81, s19, -1
	s_mov_b64 s[82:83], s[80:81]
	s_mov_b32 m0, s34
	ds_read_b128 v[208:211], v149
	ds_read_b128 v[212:215], v150
	ds_read_b128 v[216:219], v151
	ds_read_b128 v[220:223], v152
	v_lshl_add_u64 v[224:225], v[134:135], 0, s[82:83]
	global_load_lds_dwordx4 v[224:225], off
	s_mov_b32 m0, s35
	v_lshl_add_u64 v[224:225], v[224:225], 0, s[8:9]
	global_load_lds_dwordx4 v[224:225], off
	s_barrier
	s_waitcnt lgkmcnt(0)
	s_setprio 1
	v_mfma_f32_16x16x32_bf16 v[92:95], v[208:211], v[176:179], v[92:95]
	v_mfma_f32_16x16x32_bf16 v[88:91], v[216:219], v[176:179], v[88:91]
	v_mfma_f32_16x16x32_bf16 v[84:87], v[208:211], v[184:187], v[84:87]
	v_mfma_f32_16x16x32_bf16 v[80:83], v[216:219], v[184:187], v[80:83]
	v_mfma_f32_16x16x32_bf16 v[76:79], v[208:211], v[192:195], v[76:79]
	v_mfma_f32_16x16x32_bf16 v[72:75], v[216:219], v[192:195], v[72:75]
	v_mfma_f32_16x16x32_bf16 v[68:71], v[208:211], v[200:203], v[68:71]
	v_mfma_f32_16x16x32_bf16 v[64:67], v[216:219], v[200:203], v[64:67]
	v_mfma_f32_16x16x32_bf16 v[92:95], v[212:215], v[180:183], v[92:95]
	v_mfma_f32_16x16x32_bf16 v[88:91], v[220:223], v[180:183], v[88:91]
	v_mfma_f32_16x16x32_bf16 v[84:87], v[212:215], v[188:191], v[84:87]
	v_mfma_f32_16x16x32_bf16 v[80:83], v[220:223], v[188:191], v[80:83]
	v_mfma_f32_16x16x32_bf16 v[76:79], v[212:215], v[196:199], v[76:79]
	v_mfma_f32_16x16x32_bf16 v[72:75], v[220:223], v[196:199], v[72:75]
	v_mfma_f32_16x16x32_bf16 v[68:71], v[212:215], v[204:207], v[68:71]
	v_mfma_f32_16x16x32_bf16 v[64:67], v[220:223], v[204:207], v[64:67]
	s_setprio 0
	s_mov_b32 m0, s54
	s_barrier
	ds_read_b128 v[176:179], v158 offset:49152
	ds_read_b128 v[180:183], v158 offset:50176
	ds_read_b128 v[184:187], v158 offset:51200
	ds_read_b128 v[188:191], v158 offset:52224
	ds_read_b128 v[192:195], v158 offset:53248
	ds_read_b128 v[196:199], v158 offset:54272
	ds_read_b128 v[200:203], v158 offset:55296
	ds_read_b128 v[204:207], v158 offset:56320
	v_lshl_add_u64 v[224:225], v[132:133], 0, s[80:81]
	global_load_lds_dwordx4 v[224:225], off
	s_mov_b32 m0, s55
	v_lshl_add_u64 v[224:225], v[224:225], 0, s[10:11]
	global_load_lds_dwordx4 v[224:225], off
	s_barrier
; #define STA(b, h, half, kt) STAGE(((b) * 2 + (h)) * G_HT * 2, pA, ((size_t)(half) * G_HALF * lda + (size_t)(kt) * G_BK) * 2, lda)
; #define STB(b, h, half, kt) STAGE((4 + (b) * 2 + (h)) * G_HT * 2, pB, ((size_t)(half) * G_HALF * K + (size_t)(kt) * G_BK) * 2, K)
; #define LDA(dst, b, h) for (int m = 0; m < 4; ++m) for (int k = 0; k < 2; ++k) \
;     dst[m][k] = *reinterpret_cast<const bf16x8*>(aRd + (((b) * 2 + (h)) * G_HT * 2 + m * 2048 + k * 1024))
; #define LDB(dst, b, h) for (int n = 0; n < 2; ++n) for (int k = 0; k < 2; ++k) \
;     dst[n][k] = *reinterpret_cast<const bf16x8*>(bRd + (((b) * 2 + (h)) * G_HT * 2 + n * 2048 + k * 1024))
; #define MMA(ai, bj, At, Bx) do { __builtin_amdgcn_s_setprio(1); \
;     for (int m = 0; m < 4; ++m) for (int n = 0; n < 2; ++n) for (int k = 0; k < 2; ++k) \
;       acc[ai][bj][m][n] = __builtin_amdgcn_mfma_f32_16x16x32_bf16(Bx[n][k], At[m][k], acc[ai][bj][m][n], 0, 0, 0);     \
;     __builtin_amdgcn_s_setprio(0); } while (0)
; #define WAIT_V(n) asm volatile("s_waitcnt vmcnt(" #n ")" ::: "memory")
; #define WAIT_L(n) asm volatile("s_waitcnt lgkmcnt(" #n ")" ::: "memory")
; #define BAR __builtin_amdgcn_s_barrier()
; #define SCHED __builtin_amdgcn_sched_barrier(0)
; template <int EPI>
; __device__ __forceinline__ void gemm_tile(const bf16* __restrict__ A, int lda, const bf16* __restrict__ Bt, int K,
;                                           int brow, int bcol, const EpiArgs& ea, char* shmc, bool has_next, int nbrow, int nbcol, bool first_tile) {
;     ...
;     BAR; WAIT_L(0); MMA(1, 0, At, B0); BAR; SCHED;
;     STB(1, 1, 1, t + 3);
;     WAIT_V(6); BAR; MMA(1, 1, At, B1); BAR;
;   }
;   { LDB(B0, 0, 0); LDA(At, 0, 0); STA(1, 1, 1, nt - 1);
;     BAR; WAIT_L(0); MMA(0, 0, At, B0); BAR;
;     LDB(B1, 0, 1); BAR; WAIT_L(0); MMA(0, 1, At, B1); BAR;
;     LDA(At, 0, 1); WAIT_V(4); BAR; WAIT_L(0); MMA(1, 0, At, B0); MMA(1, 1, At, B1); BAR; }
	s_waitcnt lgkmcnt(0)
	s_setprio 1
	v_mfma_f32_16x16x32_bf16 v[60:63], v[160:163], v[176:179], v[60:63]
	v_mfma_f32_16x16x32_bf16 v[56:59], v[168:171], v[176:179], v[56:59]
	v_mfma_f32_16x16x32_bf16 v[52:55], v[160:163], v[184:187], v[52:55]
	v_mfma_f32_16x16x32_bf16 v[48:51], v[168:171], v[184:187], v[48:51]
	v_mfma_f32_16x16x32_bf16 v[44:47], v[160:163], v[192:195], v[44:47]
	v_mfma_f32_16x16x32_bf16 v[40:43], v[168:171], v[192:195], v[40:43]
	v_mfma_f32_16x16x32_bf16 v[36:39], v[160:163], v[200:203], v[36:39]
	v_mfma_f32_16x16x32_bf16 v[32:35], v[168:171], v[200:203], v[32:35]
	v_mfma_f32_16x16x32_bf16 v[60:63], v[164:167], v[180:183], v[60:63]
	v_mfma_f32_16x16x32_bf16 v[56:59], v[172:175], v[180:183], v[56:59]
	v_mfma_f32_16x16x32_bf16 v[52:55], v[164:167], v[188:191], v[52:55]
	v_mfma_f32_16x16x32_bf16 v[48:51], v[172:175], v[188:191], v[48:51]
	v_mfma_f32_16x16x32_bf16 v[44:47], v[164:167], v[196:199], v[44:47]
	v_mfma_f32_16x16x32_bf16 v[40:43], v[172:175], v[196:199], v[40:43]
	v_mfma_f32_16x16x32_bf16 v[36:39], v[164:167], v[204:207], v[36:39]
	v_mfma_f32_16x16x32_bf16 v[32:35], v[172:175], v[204:207], v[32:35]
	s_setprio 0
	s_barrier
	s_add_u32 s80, s18, 0xfffd0080
	s_addc_u32 s81, s19, -1
	s_mov_b32 m0, s63
	v_lshl_add_u64 v[160:161], v[134:135], 0, s[80:81]
	global_load_lds_dwordx4 v[160:161], off
	s_mov_b32 m0, s66
	v_lshl_add_u64 v[160:161], v[160:161], 0, s[8:9]
	global_load_lds_dwordx4 v[160:161], off
	s_waitcnt vmcnt(6)
	s_barrier
	s_setprio 1
	v_mfma_f32_16x16x32_bf16 v[28:31], v[208:211], v[176:179], v[28:31]
	v_mfma_f32_16x16x32_bf16 v[24:27], v[216:219], v[176:179], v[24:27]
	v_mfma_f32_16x16x32_bf16 v[20:23], v[208:211], v[184:187], v[20:23]
	v_mfma_f32_16x16x32_bf16 v[16:19], v[216:219], v[184:187], v[16:19]
	v_mfma_f32_16x16x32_bf16 v[12:15], v[208:211], v[192:195], v[12:15]
	v_mfma_f32_16x16x32_bf16 v[8:11], v[216:219], v[192:195], v[8:11]
	v_mfma_f32_16x16x32_bf16 v[4:7], v[208:211], v[200:203], v[4:7]
	v_mfma_f32_16x16x32_bf16 v[0:3], v[216:219], v[200:203], v[0:3]
	v_mfma_f32_16x16x32_bf16 v[28:31], v[212:215], v[180:183], v[28:31]
	v_mfma_f32_16x16x32_bf16 v[24:27], v[220:223], v[180:183], v[24:27]
	v_mfma_f32_16x16x32_bf16 v[20:23], v[212:215], v[188:191], v[20:23]
	v_mfma_f32_16x16x32_bf16 v[16:19], v[220:223], v[188:191], v[16:19]
	v_mfma_f32_16x16x32_bf16 v[12:15], v[212:215], v[196:199], v[12:15]
	v_mfma_f32_16x16x32_bf16 v[8:11], v[220:223], v[196:199], v[8:11]
	v_mfma_f32_16x16x32_bf16 v[4:7], v[212:215], v[204:207], v[4:7]
	v_mfma_f32_16x16x32_bf16 v[0:3], v[220:223], v[204:207], v[0:3]
	s_setprio 0
	s_add_i32 s71, s71, 2
	s_add_u32 s18, s18, 0x100
	s_addc_u32 s19, s19, 0
	s_cmp_lt_u32 s71, 8
	s_barrier
	s_cbranch_scc1 .LBB0_291
	s_mov_b64 s[18:19], 0x60580
	s_mov_b32 m0, s72
	ds_read_b128 v[160:163], v137
	ds_read_b128 v[164:167], v138
	ds_read_b128 v[168:171], v139
	ds_read_b128 v[172:175], v140
	ds_read_b128 v[176:179], v158
	ds_read_b128 v[180:183], v158 offset:1024
	ds_read_b128 v[184:187], v158 offset:2048
	ds_read_b128 v[188:191], v158 offset:3072
	ds_read_b128 v[192:195], v158 offset:4096
	ds_read_b128 v[196:199], v158 offset:5120
	ds_read_b128 v[200:203], v158 offset:6144
	ds_read_b128 v[204:207], v158 offset:7168
	s_nop 0
	v_lshl_add_u64 v[132:133], v[132:133], 0, s[18:19]
	global_load_lds_dwordx4 v[132:133], off
	v_lshl_add_u64 v[132:133], v[132:133], 0, s[10:11]
	s_mov_b32 m0, s62
	s_nop 0
	global_load_lds_dwordx4 v[132:133], off
	s_barrier
	s_waitcnt lgkmcnt(0)
	s_setprio 1
	s_waitcnt lgkmcnt(0)
	v_mfma_f32_16x16x32_bf16 v[124:127], v[160:163], v[176:179], v[124:127]
	v_mfma_f32_16x16x32_bf16 v[120:123], v[168:171], v[176:179], v[120:123]
	v_mfma_f32_16x16x32_bf16 v[108:111], v[160:163], v[192:195], v[108:111]
	v_mfma_f32_16x16x32_bf16 v[104:107], v[168:171], v[192:195], v[104:107]
	v_mfma_f32_16x16x32_bf16 v[124:127], v[164:167], v[180:183], v[124:127]
	v_mfma_f32_16x16x32_bf16 v[120:123], v[172:175], v[180:183], v[120:123]
	v_mfma_f32_16x16x32_bf16 v[116:119], v[160:163], v[184:187], v[116:119]
	v_mfma_f32_16x16x32_bf16 v[112:115], v[168:171], v[184:187], v[112:115]
	v_mfma_f32_16x16x32_bf16 v[108:111], v[164:167], v[196:199], v[108:111]
	v_mfma_f32_16x16x32_bf16 v[104:107], v[172:175], v[196:199], v[104:107]
	v_mfma_f32_16x16x32_bf16 v[100:103], v[160:163], v[200:203], v[100:103]
	v_mfma_f32_16x16x32_bf16 v[96:99], v[168:171], v[200:203], v[96:99]
	v_mfma_f32_16x16x32_bf16 v[132:135], v[164:167], v[188:191], v[116:119]
	v_mfma_f32_16x16x32_bf16 v[208:211], v[172:175], v[188:191], v[112:115]
	v_mfma_f32_16x16x32_bf16 v[212:215], v[164:167], v[204:207], v[100:103]
	v_mfma_f32_16x16x32_bf16 v[216:219], v[172:175], v[204:207], v[96:99]
	s_setprio 0
	s_barrier
	s_nop 1
	ds_read_b128 v[96:99], v141
	ds_read_b128 v[100:103], v142
	ds_read_b128 v[112:115], v143
	ds_read_b128 v[116:119], v144
	s_barrier
	s_waitcnt lgkmcnt(0)
	s_setprio 1
	s_waitcnt lgkmcnt(0)
	v_mfma_f32_16x16x32_bf16 v[92:95], v[96:99], v[176:179], v[92:95]
	v_mfma_f32_16x16x32_bf16 v[88:91], v[112:115], v[176:179], v[88:91]
	v_mfma_f32_16x16x32_bf16 v[76:79], v[96:99], v[192:195], v[76:79]
	v_mfma_f32_16x16x32_bf16 v[72:75], v[112:115], v[192:195], v[72:75]
	v_mfma_f32_16x16x32_bf16 v[68:71], v[96:99], v[200:203], v[68:71]
	v_mfma_f32_16x16x32_bf16 v[64:67], v[112:115], v[200:203], v[64:67]
	v_mfma_f32_16x16x32_bf16 v[92:95], v[100:103], v[180:183], v[92:95]
	v_mfma_f32_16x16x32_bf16 v[88:91], v[116:119], v[180:183], v[88:91]
	v_mfma_f32_16x16x32_bf16 v[84:87], v[96:99], v[184:187], v[84:87]
	v_mfma_f32_16x16x32_bf16 v[80:83], v[112:115], v[184:187], v[80:83]
	v_mfma_f32_16x16x32_bf16 v[76:79], v[100:103], v[196:199], v[76:79]
	v_mfma_f32_16x16x32_bf16 v[72:75], v[116:119], v[196:199], v[72:75]
	v_mfma_f32_16x16x32_bf16 v[68:71], v[100:103], v[204:207], v[68:71]
	v_mfma_f32_16x16x32_bf16 v[64:67], v[116:119], v[204:207], v[64:67]
	v_mfma_f32_16x16x32_bf16 v[176:179], v[100:103], v[188:191], v[84:87]
	v_mfma_f32_16x16x32_bf16 v[180:183], v[116:119], v[188:191], v[80:83]
	s_setprio 0
	s_barrier
; #define LDA(dst, b, h) for (int m = 0; m < 4; ++m) for (int k = 0; k < 2; ++k) \
;     dst[m][k] = *reinterpret_cast<const bf16x8*>(aRd + (((b) * 2 + (h)) * G_HT * 2 + m * 2048 + k * 1024))
; #define LDB(dst, b, h) for (int n = 0; n < 2; ++n) for (int k = 0; k < 2; ++k) \
;     dst[n][k] = *reinterpret_cast<const bf16x8*>(bRd + (((b) * 2 + (h)) * G_HT * 2 + n * 2048 + k * 1024))
; #define MMA(ai, bj, At, Bx) do { __builtin_amdgcn_s_setprio(1); \
;     for (int m = 0; m < 4; ++m) for (int n = 0; n < 2; ++n) for (int k = 0; k < 2; ++k) \
;       acc[ai][bj][m][n] = __builtin_amdgcn_mfma_f32_16x16x32_bf16(Bx[n][k], At[m][k], acc[ai][bj][m][n], 0, 0, 0);     \
;     __builtin_amdgcn_s_setprio(0); } while (0)
; #define WAIT_V(n) asm volatile("s_waitcnt vmcnt(" #n ")" ::: "memory")
; #define WAIT_L(n) asm volatile("s_waitcnt lgkmcnt(" #n ")" ::: "memory")
; #define BAR __builtin_amdgcn_s_barrier()
; template <int EPI>
; __device__ __forceinline__ void gemm_tile(const bf16* __restrict__ A, int lda, const bf16* __restrict__ Bt, int K,
;                                           int brow, int bcol, const EpiArgs& ea, char* shmc, bool has_next, int nbrow, int nbcol, bool first_tile) {
;     ...
;     LDA(At, 0, 1); WAIT_V(4); BAR; WAIT_L(0); MMA(1, 0, At, B0); MMA(1, 1, At, B1); BAR; }
;   { LDB(B0, 1, 0); LDA(At, 1, 0); WAIT_V(2); BAR; WAIT_L(0); MMA(0, 0, At, B0); BAR;
	s_nop 0
	ds_read_b128 v[80:83], v158 offset:16384
	ds_read_b128 v[84:87], v158 offset:17408
	ds_read_b128 v[184:187], v158 offset:18432
	ds_read_b128 v[188:191], v158 offset:19456
	ds_read_b128 v[192:195], v158 offset:20480
	ds_read_b128 v[196:199], v158 offset:21504
	ds_read_b128 v[200:203], v158 offset:22528
	ds_read_b128 v[204:207], v158 offset:23552
	s_waitcnt vmcnt(4)
	s_barrier
	s_waitcnt lgkmcnt(0)
	s_setprio 1
	s_waitcnt lgkmcnt(0)
	v_mfma_f32_16x16x32_bf16 v[44:47], v[160:163], v[192:195], v[44:47]
	v_mfma_f32_16x16x32_bf16 v[40:43], v[168:171], v[192:195], v[40:43]
	v_mfma_f32_16x16x32_bf16 v[60:63], v[160:163], v[80:83], v[60:63]
	v_mfma_f32_16x16x32_bf16 v[56:59], v[168:171], v[80:83], v[56:59]
	v_mfma_f32_16x16x32_bf16 v[52:55], v[160:163], v[184:187], v[52:55]
	v_mfma_f32_16x16x32_bf16 v[48:51], v[168:171], v[184:187], v[48:51]
	v_mfma_f32_16x16x32_bf16 v[44:47], v[164:167], v[196:199], v[44:47]
	v_mfma_f32_16x16x32_bf16 v[40:43], v[172:175], v[196:199], v[40:43]
	v_mfma_f32_16x16x32_bf16 v[36:39], v[160:163], v[200:203], v[36:39]
	v_mfma_f32_16x16x32_bf16 v[32:35], v[168:171], v[200:203], v[32:35]
	v_mfma_f32_16x16x32_bf16 v[220:223], v[164:167], v[84:87], v[60:63]
	v_mfma_f32_16x16x32_bf16 v[224:227], v[172:175], v[84:87], v[56:59]
	v_mfma_f32_16x16x32_bf16 v[228:231], v[164:167], v[188:191], v[52:55]
	v_mfma_f32_16x16x32_bf16 v[232:235], v[172:175], v[188:191], v[48:51]
	v_mfma_f32_16x16x32_bf16 v[160:163], v[164:167], v[204:207], v[36:39]
	v_mfma_f32_16x16x32_bf16 v[164:167], v[172:175], v[204:207], v[32:35]
	s_setprio 0
	s_setprio 1
	v_mfma_f32_16x16x32_bf16 v[28:31], v[96:99], v[80:83], v[28:31]
	v_mfma_f32_16x16x32_bf16 v[24:27], v[112:115], v[80:83], v[24:27]
	v_mfma_f32_16x16x32_bf16 v[12:15], v[96:99], v[192:195], v[12:15]
	v_mfma_f32_16x16x32_bf16 v[8:11], v[112:115], v[192:195], v[8:11]
	v_mfma_f32_16x16x32_bf16 v[28:31], v[100:103], v[84:87], v[28:31]
	v_mfma_f32_16x16x32_bf16 v[24:27], v[116:119], v[84:87], v[24:27]
	v_mfma_f32_16x16x32_bf16 v[20:23], v[96:99], v[184:187], v[20:23]
	v_mfma_f32_16x16x32_bf16 v[16:19], v[112:115], v[184:187], v[16:19]
	v_mfma_f32_16x16x32_bf16 v[12:15], v[100:103], v[196:199], v[12:15]
	v_mfma_f32_16x16x32_bf16 v[8:11], v[116:119], v[196:199], v[8:11]
	v_mfma_f32_16x16x32_bf16 v[4:7], v[96:99], v[200:203], v[4:7]
	v_mfma_f32_16x16x32_bf16 v[0:3], v[112:115], v[200:203], v[0:3]
	v_mfma_f32_16x16x32_bf16 v[168:171], v[100:103], v[188:191], v[20:23]
	v_mfma_f32_16x16x32_bf16 v[172:175], v[116:119], v[188:191], v[16:19]
	v_mfma_f32_16x16x32_bf16 v[184:187], v[100:103], v[204:207], v[4:7]
	v_mfma_f32_16x16x32_bf16 v[188:191], v[116:119], v[204:207], v[0:3]
	s_setprio 0
	s_barrier
	s_nop 1
	ds_read_b128 v[0:3], v145
	ds_read_b128 v[4:7], v146
	ds_read_b128 v[192:195], v147
	ds_read_b128 v[196:199], v148
	ds_read_b128 v[16:19], v158 offset:32768
	ds_read_b128 v[20:23], v158 offset:33792
	ds_read_b128 v[32:35], v158 offset:34816
	ds_read_b128 v[36:39], v158 offset:35840
	ds_read_b128 v[56:59], v158 offset:36864
	ds_read_b128 v[60:63], v158 offset:37888
	ds_read_b128 v[200:203], v158 offset:38912
	ds_read_b128 v[204:207], v158 offset:39936
	s_waitcnt vmcnt(2)
	s_barrier
	s_waitcnt lgkmcnt(0)
	s_setprio 1
	s_waitcnt lgkmcnt(0)
	v_mfma_f32_16x16x32_bf16 v[48:51], v[0:3], v[16:19], v[124:127]
	v_mfma_f32_16x16x32_bf16 v[112:115], v[4:7], v[20:23], v[48:51]
	v_mfma_f32_16x16x32_bf16 v[48:51], v[192:195], v[16:19], v[120:123]
	v_mfma_f32_16x16x32_bf16 v[116:119], v[196:199], v[20:23], v[48:51]
	v_mfma_f32_16x16x32_bf16 v[48:51], v[0:3], v[32:35], v[132:135]
	v_mfma_f32_16x16x32_bf16 v[96:99], v[4:7], v[36:39], v[48:51]
	v_mfma_f32_16x16x32_bf16 v[48:51], v[192:195], v[32:35], v[208:211]
	v_mfma_f32_16x16x32_bf16 v[100:103], v[196:199], v[36:39], v[48:51]
	v_mfma_f32_16x16x32_bf16 v[48:51], v[0:3], v[56:59], v[108:111]
	v_mfma_f32_16x16x32_bf16 v[80:83], v[4:7], v[60:63], v[48:51]
	v_mfma_f32_16x16x32_bf16 v[48:51], v[192:195], v[56:59], v[104:107]
	v_mfma_f32_16x16x32_bf16 v[84:87], v[196:199], v[60:63], v[48:51]
	v_mfma_f32_16x16x32_bf16 v[48:51], v[0:3], v[200:203], v[212:215]
	v_mfma_f32_16x16x32_bf16 v[52:55], v[192:195], v[200:203], v[216:219]
	v_mfma_f32_16x16x32_bf16 v[48:51], v[4:7], v[204:207], v[48:51]
	v_mfma_f32_16x16x32_bf16 v[52:55], v[196:199], v[204:207], v[52:55]
	s_setprio 0
	s_barrier
; #define LDA(dst, b, h) for (int m = 0; m < 4; ++m) for (int k = 0; k < 2; ++k) \
;     dst[m][k] = *reinterpret_cast<const bf16x8*>(aRd + (((b) * 2 + (h)) * G_HT * 2 + m * 2048 + k * 1024))
; #define LDB(dst, b, h) for (int n = 0; n < 2; ++n) for (int k = 0; k < 2; ++k) \
;     dst[n][k] = *reinterpret_cast<const bf16x8*>(bRd + (((b) * 2 + (h)) * G_HT * 2 + n * 2048 + k * 1024))
; #define MMA(ai, bj, At, Bx) do { __builtin_amdgcn_s_setprio(1); \
;     for (int m = 0; m < 4; ++m) for (int n = 0; n < 2; ++n) for (int k = 0; k < 2; ++k) \
;       acc[ai][bj][m][n] = __builtin_amdgcn_mfma_f32_16x16x32_bf16(Bx[n][k], At[m][k], acc[ai][bj][m][n], 0, 0, 0);     \
;     __builtin_amdgcn_s_setprio(0); } while (0)
; #define WAIT_V(n) asm volatile("s_waitcnt vmcnt(" #n ")" ::: "memory")
; #define WAIT_L(n) asm volatile("s_waitcnt lgkmcnt(" #n ")" ::: "memory")
; #define BAR __builtin_amdgcn_s_barrier()
; template <int EPI>
; __device__ __forceinline__ void gemm_tile(const bf16* __restrict__ A, int lda, const bf16* __restrict__ Bt, int K,
;                                           int brow, int bcol, const EpiArgs& ea, char* shmc, bool has_next, int nbrow, int nbcol, bool first_tile) {
;     ...
;   { LDB(B0, 1, 0); LDA(At, 1, 0); WAIT_V(2); BAR; WAIT_L(0); MMA(0, 0, At, B0); BAR;
;     LDB(B1, 1, 1); WAIT_V(0); BAR; WAIT_L(0); MMA(0, 1, At, B1); BAR;
;     LDA(At, 1, 1); BAR; WAIT_L(0); MMA(1, 0, At, B0); MMA(1, 1, At, B1); BAR; }
;   if (wr == 0) BAR;
	ds_read_b128 v[132:135], v149
	ds_read_b128 v[208:211], v150
	ds_read_b128 v[212:215], v151
	ds_read_b128 v[216:219], v152
	s_waitcnt vmcnt(0)
	s_barrier
	s_waitcnt lgkmcnt(0)
	s_setprio 1
	s_waitcnt lgkmcnt(0)
	v_mfma_f32_16x16x32_bf16 v[92:95], v[132:135], v[16:19], v[92:95]
	v_mfma_f32_16x16x32_bf16 v[16:19], v[212:215], v[16:19], v[88:91]
	v_mfma_f32_16x16x32_bf16 v[124:127], v[216:219], v[20:23], v[16:19]
	v_mfma_f32_16x16x32_bf16 v[16:19], v[132:135], v[32:35], v[176:179]
	v_mfma_f32_16x16x32_bf16 v[104:107], v[208:211], v[36:39], v[16:19]
	v_mfma_f32_16x16x32_bf16 v[16:19], v[212:215], v[32:35], v[180:183]
	v_mfma_f32_16x16x32_bf16 v[108:111], v[216:219], v[36:39], v[16:19]
	v_mfma_f32_16x16x32_bf16 v[16:19], v[132:135], v[56:59], v[76:79]
	v_mfma_f32_16x16x32_bf16 v[88:91], v[208:211], v[60:63], v[16:19]
	v_mfma_f32_16x16x32_bf16 v[16:19], v[212:215], v[56:59], v[72:75]
	v_mfma_f32_16x16x32_bf16 v[120:123], v[208:211], v[20:23], v[92:95]
	v_mfma_f32_16x16x32_bf16 v[92:95], v[216:219], v[60:63], v[16:19]
	v_mfma_f32_16x16x32_bf16 v[16:19], v[132:135], v[200:203], v[68:71]
	v_mfma_f32_16x16x32_bf16 v[56:59], v[208:211], v[204:207], v[16:19]
	v_mfma_f32_16x16x32_bf16 v[16:19], v[212:215], v[200:203], v[64:67]
	v_mfma_f32_16x16x32_bf16 v[60:63], v[216:219], v[204:207], v[16:19]
	s_setprio 0
	s_barrier
	ds_read_b128 v[76:79], v158 offset:49152
	ds_read_b128 v[176:179], v158 offset:50176
	ds_read_b128 v[180:183], v158 offset:51200
	ds_read_b128 v[200:203], v158 offset:52224
	ds_read_b128 v[204:207], v158 offset:53248
	ds_read_b128 v[236:239], v158 offset:54272
	ds_read_b128 v[240:243], v158 offset:55296
	ds_read_b128 v[244:247], v158 offset:56320
	s_barrier
	s_waitcnt lgkmcnt(0)
	s_setprio 1
	s_waitcnt lgkmcnt(0)
	v_mfma_f32_16x16x32_bf16 v[16:19], v[0:3], v[76:79], v[220:223]
	v_mfma_f32_16x16x32_bf16 v[64:67], v[4:7], v[176:179], v[16:19]
	v_mfma_f32_16x16x32_bf16 v[16:19], v[192:195], v[76:79], v[224:227]
	v_mfma_f32_16x16x32_bf16 v[68:71], v[196:199], v[176:179], v[16:19]
	v_mfma_f32_16x16x32_bf16 v[16:19], v[0:3], v[180:183], v[228:231]
	v_mfma_f32_16x16x32_bf16 v[32:35], v[4:7], v[200:203], v[16:19]
	v_mfma_f32_16x16x32_bf16 v[16:19], v[192:195], v[180:183], v[232:235]
	v_mfma_f32_16x16x32_bf16 v[36:39], v[196:199], v[200:203], v[16:19]
	v_mfma_f32_16x16x32_bf16 v[16:19], v[0:3], v[204:207], v[44:47]
	v_mfma_f32_16x16x32_bf16 v[0:3], v[0:3], v[240:243], v[160:163]
	v_mfma_f32_16x16x32_bf16 v[16:19], v[4:7], v[236:239], v[16:19]
	v_mfma_f32_16x16x32_bf16 v[20:23], v[192:195], v[204:207], v[40:43]
	v_mfma_f32_16x16x32_bf16 v[0:3], v[4:7], v[244:247], v[0:3]
	v_mfma_f32_16x16x32_bf16 v[4:7], v[192:195], v[240:243], v[164:167]
	v_mfma_f32_16x16x32_bf16 v[20:23], v[196:199], v[236:239], v[20:23]
	v_mfma_f32_16x16x32_bf16 v[4:7], v[196:199], v[244:247], v[4:7]
	s_setprio 0
	s_setprio 1
	v_mfma_f32_16x16x32_bf16 v[24:27], v[212:215], v[76:79], v[24:27]
	v_mfma_f32_16x16x32_bf16 v[28:31], v[132:135], v[76:79], v[28:31]
	v_mfma_f32_16x16x32_bf16 v[76:79], v[216:219], v[176:179], v[24:27]
	v_mfma_f32_16x16x32_bf16 v[24:27], v[132:135], v[180:183], v[168:171]
	v_mfma_f32_16x16x32_bf16 v[40:43], v[208:211], v[200:203], v[24:27]
	v_mfma_f32_16x16x32_bf16 v[24:27], v[212:215], v[180:183], v[172:175]
	v_mfma_f32_16x16x32_bf16 v[12:15], v[132:135], v[204:207], v[12:15]
	v_mfma_f32_16x16x32_bf16 v[8:11], v[212:215], v[204:207], v[8:11]
	v_mfma_f32_16x16x32_bf16 v[72:75], v[208:211], v[176:179], v[28:31]
	v_mfma_f32_16x16x32_bf16 v[44:47], v[216:219], v[200:203], v[24:27]
	v_mfma_f32_16x16x32_bf16 v[24:27], v[208:211], v[236:239], v[12:15]
	v_mfma_f32_16x16x32_bf16 v[28:31], v[216:219], v[236:239], v[8:11]
	v_mfma_f32_16x16x32_bf16 v[8:11], v[132:135], v[240:243], v[184:187]
	v_mfma_f32_16x16x32_bf16 v[12:15], v[212:215], v[240:243], v[188:191]
	v_mfma_f32_16x16x32_bf16 v[8:11], v[208:211], v[244:247], v[8:11]
	v_mfma_f32_16x16x32_bf16 v[12:15], v[216:219], v[244:247], v[12:15]
	s_setprio 0
	s_barrier
	s_and_saveexec_b64 s[18:19], s[4:5]
	s_cbranch_execz .LBB0_294
	s_barrier

; #define STA(b, h, half, kt) STAGE(((b) * 2 + (h)) * G_HT * 2, pA, ((size_t)(half) * G_HALF * lda + (size_t)(kt) * G_BK) * 2, lda)
; #define STB(b, h, half, kt) STAGE((4 + (b) * 2 + (h)) * G_HT * 2, pB, ((size_t)(half) * G_HALF * K + (size_t)(kt) * G_BK) * 2, K)
; #define LDA(dst, b, h) for (int m = 0; m < 4; ++m) for (int k = 0; k < 2; ++k) \
;     dst[m][k] = *reinterpret_cast<const bf16x8*>(aRd + (((b) * 2 + (h)) * G_HT * 2 + m * 2048 + k * 1024))
; #define LDB(dst, b, h) for (int n = 0; n < 2; ++n) for (int k = 0; k < 2; ++k) \
;     dst[n][k] = *reinterpret_cast<const bf16x8*>(bRd + (((b) * 2 + (h)) * G_HT * 2 + n * 2048 + k * 1024))
; #define MMA(ai, bj, At, Bx) do { __builtin_amdgcn_s_setprio(1); \
;     for (int m = 0; m < 4; ++m) for (int n = 0; n < 2; ++n) for (int k = 0; k < 2; ++k) \
;       acc[ai][bj][m][n] = __builtin_amdgcn_mfma_f32_16x16x32_bf16(Bx[n][k], At[m][k], acc[ai][bj][m][n], 0, 0, 0);     \
;     __builtin_amdgcn_s_setprio(0); } while (0)
; #define WAIT_V(n) asm volatile("s_waitcnt vmcnt(" #n ")" ::: "memory")
; #define WAIT_L(n) asm volatile("s_waitcnt lgkmcnt(" #n ")" ::: "memory")
; #define BAR __builtin_amdgcn_s_barrier()
; #define SCHED __builtin_amdgcn_sched_barrier(0)
; template <int EPI>
; __device__ __forceinline__ void gemm_tile(const bf16* __restrict__ A, int lda, const bf16* __restrict__ Bt, int K,
;                                           int brow, int bcol, const EpiArgs& ea, char* shmc, bool has_next, int nbrow, int nbcol, bool first_tile) {
;     ...
;   for (int t = 0; t < nt - 2; t += 2) {
;     LDB(B0, 0, 0); SCHED; LDA(At, 0, 0); STA(1, 1, 1, t + 1);
;     WAIT_L(8); BAR; WAIT_L(0); MMA(0, 0, At, B0); BAR; SCHED;
;     LDB(B1, 0, 1); STB(0, 0, 0, t + 2);
;     BAR; WAIT_L(0); MMA(0, 1, At, B1); BAR;
;     LDA(At, 0, 1); STA(0, 0, 0, t + 2);
;     BAR; WAIT_L(0); MMA(1, 0, At, B0); BAR; SCHED;
;     STB(0, 1, 1, t + 2);
;     WAIT_V(6); BAR; MMA(1, 1, At, B1); BAR;
.LBB0_310:
	ds_read_b128 v[160:163], v138
	ds_read_b128 v[164:167], v139
	ds_read_b128 v[168:171], v140
	ds_read_b128 v[172:175], v141
	s_add_u32 s84, s30, 0xffffff80
	s_addc_u32 s85, s31, -1
	s_mov_b32 m0, s81
	ds_read_b128 v[176:179], v158
	ds_read_b128 v[180:183], v158 offset:1024
	ds_read_b128 v[184:187], v158 offset:2048
	ds_read_b128 v[188:191], v158 offset:3072
	ds_read_b128 v[192:195], v158 offset:4096
	ds_read_b128 v[196:199], v158 offset:5120
	ds_read_b128 v[200:203], v158 offset:6144
	ds_read_b128 v[204:207], v158 offset:7168
	v_lshl_add_u64 v[208:209], v[134:135], 0, s[84:85]
	global_load_lds_dwordx4 v[208:209], off
	s_mov_b32 m0, s71
	v_lshl_add_u64 v[208:209], v[208:209], 0, s[8:9]
	global_load_lds_dwordx4 v[208:209], off
	s_waitcnt lgkmcnt(8)
	s_barrier
	s_waitcnt lgkmcnt(0)
	s_setprio 1
	v_mfma_f32_16x16x32_bf16 v[124:127], v[160:163], v[176:179], v[124:127]
	v_mfma_f32_16x16x32_bf16 v[120:123], v[168:171], v[176:179], v[120:123]
	v_mfma_f32_16x16x32_bf16 v[116:119], v[160:163], v[184:187], v[116:119]
	v_mfma_f32_16x16x32_bf16 v[112:115], v[168:171], v[184:187], v[112:115]
	v_mfma_f32_16x16x32_bf16 v[108:111], v[160:163], v[192:195], v[108:111]
	v_mfma_f32_16x16x32_bf16 v[104:107], v[168:171], v[192:195], v[104:107]
	v_mfma_f32_16x16x32_bf16 v[100:103], v[160:163], v[200:203], v[100:103]
	v_mfma_f32_16x16x32_bf16 v[96:99], v[168:171], v[200:203], v[96:99]
	v_mfma_f32_16x16x32_bf16 v[124:127], v[164:167], v[180:183], v[124:127]
	v_mfma_f32_16x16x32_bf16 v[120:123], v[172:175], v[180:183], v[120:123]
	v_mfma_f32_16x16x32_bf16 v[116:119], v[164:167], v[188:191], v[116:119]
	v_mfma_f32_16x16x32_bf16 v[112:115], v[172:175], v[188:191], v[112:115]
	v_mfma_f32_16x16x32_bf16 v[108:111], v[164:167], v[196:199], v[108:111]
	v_mfma_f32_16x16x32_bf16 v[104:107], v[172:175], v[196:199], v[104:107]
	v_mfma_f32_16x16x32_bf16 v[100:103], v[164:167], v[204:207], v[100:103]
	v_mfma_f32_16x16x32_bf16 v[96:99], v[172:175], v[204:207], v[96:99]
	s_setprio 0
	s_barrier
	s_add_u32 s84, s30, 0xfffa0000
	s_addc_u32 s85, s31, -1
	s_mov_b64 s[86:87], s[84:85]
	s_mov_b32 m0, s74
	ds_read_b128 v[208:211], v142
	ds_read_b128 v[212:215], v143
	ds_read_b128 v[216:219], v144
	ds_read_b128 v[220:223], v145
	v_lshl_add_u64 v[224:225], v[136:137], 0, s[86:87]
	global_load_lds_dwordx4 v[224:225], off
	s_mov_b32 m0, s75
	v_lshl_add_u64 v[224:225], v[224:225], 0, s[6:7]
	global_load_lds_dwordx4 v[224:225], off
	s_barrier
	s_waitcnt lgkmcnt(0)
	s_setprio 1
	v_mfma_f32_16x16x32_bf16 v[92:95], v[208:211], v[176:179], v[92:95]
	v_mfma_f32_16x16x32_bf16 v[88:91], v[216:219], v[176:179], v[88:91]
	v_mfma_f32_16x16x32_bf16 v[84:87], v[208:211], v[184:187], v[84:87]
	v_mfma_f32_16x16x32_bf16 v[80:83], v[216:219], v[184:187], v[80:83]
	v_mfma_f32_16x16x32_bf16 v[76:79], v[208:211], v[192:195], v[76:79]
	v_mfma_f32_16x16x32_bf16 v[72:75], v[216:219], v[192:195], v[72:75]
	v_mfma_f32_16x16x32_bf16 v[68:71], v[208:211], v[200:203], v[68:71]
	v_mfma_f32_16x16x32_bf16 v[64:67], v[216:219], v[200:203], v[64:67]
	v_mfma_f32_16x16x32_bf16 v[92:95], v[212:215], v[180:183], v[92:95]
	v_mfma_f32_16x16x32_bf16 v[88:91], v[220:223], v[180:183], v[88:91]
	v_mfma_f32_16x16x32_bf16 v[84:87], v[212:215], v[188:191], v[84:87]
	v_mfma_f32_16x16x32_bf16 v[80:83], v[220:223], v[188:191], v[80:83]
	v_mfma_f32_16x16x32_bf16 v[76:79], v[212:215], v[196:199], v[76:79]
	v_mfma_f32_16x16x32_bf16 v[72:75], v[220:223], v[196:199], v[72:75]
	v_mfma_f32_16x16x32_bf16 v[68:71], v[212:215], v[204:207], v[68:71]
	v_mfma_f32_16x16x32_bf16 v[64:67], v[220:223], v[204:207], v[64:67]
	s_setprio 0
	s_mov_b32 m0, s29
	s_barrier
	ds_read_b128 v[176:179], v158 offset:16384
	ds_read_b128 v[180:183], v158 offset:17408
	ds_read_b128 v[184:187], v158 offset:18432
	ds_read_b128 v[188:191], v158 offset:19456
	ds_read_b128 v[192:195], v158 offset:20480
	ds_read_b128 v[196:199], v158 offset:21504
	ds_read_b128 v[200:203], v158 offset:22528
	ds_read_b128 v[204:207], v158 offset:23552
	v_lshl_add_u64 v[224:225], v[134:135], 0, s[84:85]
	global_load_lds_dwordx4 v[224:225], off
	s_mov_b32 m0, s82
	v_lshl_add_u64 v[224:225], v[224:225], 0, s[8:9]
	global_load_lds_dwordx4 v[224:225], off
	s_barrier
	s_waitcnt lgkmcnt(0)
	s_setprio 1
	v_mfma_f32_16x16x32_bf16 v[60:63], v[160:163], v[176:179], v[60:63]
	v_mfma_f32_16x16x32_bf16 v[56:59], v[168:171], v[176:179], v[56:59]
	v_mfma_f32_16x16x32_bf16 v[52:55], v[160:163], v[184:187], v[52:55]
	v_mfma_f32_16x16x32_bf16 v[48:51], v[168:171], v[184:187], v[48:51]
	v_mfma_f32_16x16x32_bf16 v[44:47], v[160:163], v[192:195], v[44:47]
	v_mfma_f32_16x16x32_bf16 v[40:43], v[168:171], v[192:195], v[40:43]
	v_mfma_f32_16x16x32_bf16 v[36:39], v[160:163], v[200:203], v[36:39]
	v_mfma_f32_16x16x32_bf16 v[32:35], v[168:171], v[200:203], v[32:35]
	v_mfma_f32_16x16x32_bf16 v[60:63], v[164:167], v[180:183], v[60:63]
	v_mfma_f32_16x16x32_bf16 v[56:59], v[172:175], v[180:183], v[56:59]
	v_mfma_f32_16x16x32_bf16 v[52:55], v[164:167], v[188:191], v[52:55]
	v_mfma_f32_16x16x32_bf16 v[48:51], v[172:175], v[188:191], v[48:51]
	v_mfma_f32_16x16x32_bf16 v[44:47], v[164:167], v[196:199], v[44:47]
	v_mfma_f32_16x16x32_bf16 v[40:43], v[172:175], v[196:199], v[40:43]
	v_mfma_f32_16x16x32_bf16 v[36:39], v[164:167], v[204:207], v[36:39]
	v_mfma_f32_16x16x32_bf16 v[32:35], v[172:175], v[204:207], v[32:35]
	s_setprio 0
	s_barrier
	s_add_u32 s84, s30, 0xfffc0000
	s_addc_u32 s85, s31, -1
	s_mov_b32 m0, s77
	v_lshl_add_u64 v[160:161], v[136:137], 0, s[84:85]
	global_load_lds_dwordx4 v[160:161], off
	s_mov_b32 m0, s79
	v_lshl_add_u64 v[160:161], v[160:161], 0, s[6:7]
	global_load_lds_dwordx4 v[160:161], off
	s_waitcnt vmcnt(6)
	s_barrier
; #define STA(b, h, half, kt) STAGE(((b) * 2 + (h)) * G_HT * 2, pA, ((size_t)(half) * G_HALF * lda + (size_t)(kt) * G_BK) * 2, lda)
; #define STB(b, h, half, kt) STAGE((4 + (b) * 2 + (h)) * G_HT * 2, pB, ((size_t)(half) * G_HALF * K + (size_t)(kt) * G_BK) * 2, K)
; #define LDA(dst, b, h) for (int m = 0; m < 4; ++m) for (int k = 0; k < 2; ++k) \
;     dst[m][k] = *reinterpret_cast<const bf16x8*>(aRd + (((b) * 2 + (h)) * G_HT * 2 + m * 2048 + k * 1024))
; #define LDB(dst, b, h) for (int n = 0; n < 2; ++n) for (int k = 0; k < 2; ++k) \
;     dst[n][k] = *reinterpret_cast<const bf16x8*>(bRd + (((b) * 2 + (h)) * G_HT * 2 + n * 2048 + k * 1024))
; #define MMA(ai, bj, At, Bx) do { __builtin_amdgcn_s_setprio(1); \
;     for (int m = 0; m < 4; ++m) for (int n = 0; n < 2; ++n) for (int k = 0; k < 2; ++k) \
;       acc[ai][bj][m][n] = __builtin_amdgcn_mfma_f32_16x16x32_bf16(Bx[n][k], At[m][k], acc[ai][bj][m][n], 0, 0, 0);     \
;     __builtin_amdgcn_s_setprio(0); } while (0)
; #define WAIT_V(n) asm volatile("s_waitcnt vmcnt(" #n ")" ::: "memory")
; #define WAIT_L(n) asm volatile("s_waitcnt lgkmcnt(" #n ")" ::: "memory")
; #define BAR __builtin_amdgcn_s_barrier()
; #define SCHED __builtin_amdgcn_sched_barrier(0)
; template <int EPI>
; __device__ __forceinline__ void gemm_tile(const bf16* __restrict__ A, int lda, const bf16* __restrict__ Bt, int K,
;                                           int brow, int bcol, const EpiArgs& ea, char* shmc, bool has_next, int nbrow, int nbcol, bool first_tile) {
;     ...
;     WAIT_V(6); BAR; MMA(1, 1, At, B1); BAR;
;     LDB(B0, 1, 0); SCHED; LDA(At, 1, 0); STA(0, 1, 1, t + 2);
;     WAIT_L(8); BAR; WAIT_L(0); MMA(0, 0, At, B0); BAR; SCHED;
;     LDB(B1, 1, 1); STB(1, 0, 0, t + 3);
;     BAR; WAIT_L(0); MMA(0, 1, At, B1); BAR;
;     LDA(At, 1, 1); STA(1, 0, 0, t + 3);
;     BAR; WAIT_L(0); MMA(1, 0, At, B0); BAR; SCHED;
	s_setprio 1
	v_mfma_f32_16x16x32_bf16 v[28:31], v[208:211], v[176:179], v[28:31]
	v_mfma_f32_16x16x32_bf16 v[24:27], v[216:219], v[176:179], v[24:27]
	v_mfma_f32_16x16x32_bf16 v[20:23], v[208:211], v[184:187], v[20:23]
	v_mfma_f32_16x16x32_bf16 v[16:19], v[216:219], v[184:187], v[16:19]
	v_mfma_f32_16x16x32_bf16 v[12:15], v[208:211], v[192:195], v[12:15]
	v_mfma_f32_16x16x32_bf16 v[8:11], v[216:219], v[192:195], v[8:11]
	v_mfma_f32_16x16x32_bf16 v[4:7], v[208:211], v[200:203], v[4:7]
	v_mfma_f32_16x16x32_bf16 v[0:3], v[216:219], v[200:203], v[0:3]
	v_mfma_f32_16x16x32_bf16 v[28:31], v[212:215], v[180:183], v[28:31]
	v_mfma_f32_16x16x32_bf16 v[24:27], v[220:223], v[180:183], v[24:27]
	v_mfma_f32_16x16x32_bf16 v[20:23], v[212:215], v[188:191], v[20:23]
	v_mfma_f32_16x16x32_bf16 v[16:19], v[220:223], v[188:191], v[16:19]
	v_mfma_f32_16x16x32_bf16 v[12:15], v[212:215], v[196:199], v[12:15]
	v_mfma_f32_16x16x32_bf16 v[8:11], v[220:223], v[196:199], v[8:11]
	v_mfma_f32_16x16x32_bf16 v[4:7], v[212:215], v[204:207], v[4:7]
	v_mfma_f32_16x16x32_bf16 v[0:3], v[220:223], v[204:207], v[0:3]
	s_setprio 0
	s_barrier
	ds_read_b128 v[160:163], v146
	ds_read_b128 v[164:167], v147
	ds_read_b128 v[168:171], v148
	ds_read_b128 v[172:175], v149
	s_mov_b64 s[84:85], s[30:31]
	s_mov_b32 m0, s83
	ds_read_b128 v[176:179], v158 offset:32768
	ds_read_b128 v[180:183], v158 offset:33792
	ds_read_b128 v[184:187], v158 offset:34816
	ds_read_b128 v[188:191], v158 offset:35840
	ds_read_b128 v[192:195], v158 offset:36864
	ds_read_b128 v[196:199], v158 offset:37888
	ds_read_b128 v[200:203], v158 offset:38912
	ds_read_b128 v[204:207], v158 offset:39936
	v_lshl_add_u64 v[208:209], v[134:135], 0, s[84:85]
	global_load_lds_dwordx4 v[208:209], off
	s_add_i32 m0, s29, 0x6000
	v_lshl_add_u64 v[208:209], v[208:209], 0, s[8:9]
	global_load_lds_dwordx4 v[208:209], off
	s_waitcnt lgkmcnt(8)
	s_barrier
	s_waitcnt lgkmcnt(0)
	s_setprio 1
	v_mfma_f32_16x16x32_bf16 v[124:127], v[160:163], v[176:179], v[124:127]
	v_mfma_f32_16x16x32_bf16 v[120:123], v[168:171], v[176:179], v[120:123]
	v_mfma_f32_16x16x32_bf16 v[116:119], v[160:163], v[184:187], v[116:119]
	v_mfma_f32_16x16x32_bf16 v[112:115], v[168:171], v[184:187], v[112:115]
	v_mfma_f32_16x16x32_bf16 v[108:111], v[160:163], v[192:195], v[108:111]
	v_mfma_f32_16x16x32_bf16 v[104:107], v[168:171], v[192:195], v[104:107]
	v_mfma_f32_16x16x32_bf16 v[100:103], v[160:163], v[200:203], v[100:103]
	v_mfma_f32_16x16x32_bf16 v[96:99], v[168:171], v[200:203], v[96:99]
	v_mfma_f32_16x16x32_bf16 v[124:127], v[164:167], v[180:183], v[124:127]
	v_mfma_f32_16x16x32_bf16 v[120:123], v[172:175], v[180:183], v[120:123]
	v_mfma_f32_16x16x32_bf16 v[116:119], v[164:167], v[188:191], v[116:119]
	v_mfma_f32_16x16x32_bf16 v[112:115], v[172:175], v[188:191], v[112:115]
	v_mfma_f32_16x16x32_bf16 v[108:111], v[164:167], v[196:199], v[108:111]
	v_mfma_f32_16x16x32_bf16 v[104:107], v[172:175], v[196:199], v[104:107]
	v_mfma_f32_16x16x32_bf16 v[100:103], v[164:167], v[204:207], v[100:103]
	v_mfma_f32_16x16x32_bf16 v[96:99], v[172:175], v[204:207], v[96:99]
	s_setprio 0
	s_barrier
	s_add_u32 s84, s30, 0xfffa0080
	s_addc_u32 s85, s31, -1
	s_mov_b64 s[86:87], s[84:85]
	s_mov_b32 m0, s67
	ds_read_b128 v[208:211], v150
	ds_read_b128 v[212:215], v151
	ds_read_b128 v[216:219], v152
	ds_read_b128 v[220:223], v153
	v_lshl_add_u64 v[224:225], v[136:137], 0, s[86:87]
	global_load_lds_dwordx4 v[224:225], off
	s_mov_b32 m0, s68
	v_lshl_add_u64 v[224:225], v[224:225], 0, s[6:7]
	global_load_lds_dwordx4 v[224:225], off
	s_barrier
	s_waitcnt lgkmcnt(0)
	s_setprio 1
	v_mfma_f32_16x16x32_bf16 v[92:95], v[208:211], v[176:179], v[92:95]
	v_mfma_f32_16x16x32_bf16 v[88:91], v[216:219], v[176:179], v[88:91]
	v_mfma_f32_16x16x32_bf16 v[84:87], v[208:211], v[184:187], v[84:87]
	v_mfma_f32_16x16x32_bf16 v[80:83], v[216:219], v[184:187], v[80:83]
	v_mfma_f32_16x16x32_bf16 v[76:79], v[208:211], v[192:195], v[76:79]
	v_mfma_f32_16x16x32_bf16 v[72:75], v[216:219], v[192:195], v[72:75]
	v_mfma_f32_16x16x32_bf16 v[68:71], v[208:211], v[200:203], v[68:71]
	v_mfma_f32_16x16x32_bf16 v[64:67], v[216:219], v[200:203], v[64:67]
	v_mfma_f32_16x16x32_bf16 v[92:95], v[212:215], v[180:183], v[92:95]
	v_mfma_f32_16x16x32_bf16 v[88:91], v[220:223], v[180:183], v[88:91]
	v_mfma_f32_16x16x32_bf16 v[84:87], v[212:215], v[188:191], v[84:87]
	v_mfma_f32_16x16x32_bf16 v[80:83], v[220:223], v[188:191], v[80:83]
	v_mfma_f32_16x16x32_bf16 v[76:79], v[212:215], v[196:199], v[76:79]
	v_mfma_f32_16x16x32_bf16 v[72:75], v[220:223], v[196:199], v[72:75]
	v_mfma_f32_16x16x32_bf16 v[68:71], v[212:215], v[204:207], v[68:71]
	v_mfma_f32_16x16x32_bf16 v[64:67], v[220:223], v[204:207], v[64:67]
	s_setprio 0
	s_mov_b32 m0, s69
	s_barrier
	ds_read_b128 v[176:179], v158 offset:49152
	ds_read_b128 v[180:183], v158 offset:50176
	ds_read_b128 v[184:187], v158 offset:51200
	ds_read_b128 v[188:191], v158 offset:52224
	ds_read_b128 v[192:195], v158 offset:53248
	ds_read_b128 v[196:199], v158 offset:54272
	ds_read_b128 v[200:203], v158 offset:55296
	ds_read_b128 v[204:207], v158 offset:56320
	v_lshl_add_u64 v[224:225], v[134:135], 0, s[84:85]
	global_load_lds_dwordx4 v[224:225], off
	s_mov_b32 m0, s70
	v_lshl_add_u64 v[224:225], v[224:225], 0, s[8:9]
	global_load_lds_dwordx4 v[224:225], off
	s_barrier
; #define STA(b, h, half, kt) STAGE(((b) * 2 + (h)) * G_HT * 2, pA, ((size_t)(half) * G_HALF * lda + (size_t)(kt) * G_BK) * 2, lda)
; #define STB(b, h, half, kt) STAGE((4 + (b) * 2 + (h)) * G_HT * 2, pB, ((size_t)(half) * G_HALF * K + (size_t)(kt) * G_BK) * 2, K)
; #define LDA(dst, b, h) for (int m = 0; m < 4; ++m) for (int k = 0; k < 2; ++k) \
;     dst[m][k] = *reinterpret_cast<const bf16x8*>(aRd + (((b) * 2 + (h)) * G_HT * 2 + m * 2048 + k * 1024))
; #define LDB(dst, b, h) for (int n = 0; n < 2; ++n) for (int k = 0; k < 2; ++k) \
;     dst[n][k] = *reinterpret_cast<const bf16x8*>(bRd + (((b) * 2 + (h)) * G_HT * 2 + n * 2048 + k * 1024))
; #define MMA(ai, bj, At, Bx) do { __builtin_amdgcn_s_setprio(1); \
;     for (int m = 0; m < 4; ++m) for (int n = 0; n < 2; ++n) for (int k = 0; k < 2; ++k) \
;       acc[ai][bj][m][n] = __builtin_amdgcn_mfma_f32_16x16x32_bf16(Bx[n][k], At[m][k], acc[ai][bj][m][n], 0, 0, 0);     \
;     __builtin_amdgcn_s_setprio(0); } while (0)
; #define WAIT_V(n) asm volatile("s_waitcnt vmcnt(" #n ")" ::: "memory")
; #define WAIT_L(n) asm volatile("s_waitcnt lgkmcnt(" #n ")" ::: "memory")
; #define BAR __builtin_amdgcn_s_barrier()
; #define SCHED __builtin_amdgcn_sched_barrier(0)
; template <int EPI>
; __device__ __forceinline__ void gemm_tile(const bf16* __restrict__ A, int lda, const bf16* __restrict__ Bt, int K,
;                                           int brow, int bcol, const EpiArgs& ea, char* shmc, bool has_next, int nbrow, int nbcol, bool first_tile) {
;     ...
;     BAR; WAIT_L(0); MMA(1, 0, At, B0); BAR; SCHED;
;     STB(1, 1, 1, t + 3);
;     WAIT_V(6); BAR; MMA(1, 1, At, B1); BAR;
;   }
;   { LDB(B0, 0, 0); LDA(At, 0, 0); STA(1, 1, 1, nt - 1);
;     BAR; WAIT_L(0); MMA(0, 0, At, B0); BAR;
;     LDB(B1, 0, 1); BAR; WAIT_L(0); MMA(0, 1, At, B1); BAR;
;     LDA(At, 0, 1); WAIT_V(4); BAR; WAIT_L(0); MMA(1, 0, At, B0); MMA(1, 1, At, B1); BAR; }
	s_waitcnt lgkmcnt(0)
	s_setprio 1
	v_mfma_f32_16x16x32_bf16 v[60:63], v[160:163], v[176:179], v[60:63]
	v_mfma_f32_16x16x32_bf16 v[56:59], v[168:171], v[176:179], v[56:59]
	v_mfma_f32_16x16x32_bf16 v[52:55], v[160:163], v[184:187], v[52:55]
	v_mfma_f32_16x16x32_bf16 v[48:51], v[168:171], v[184:187], v[48:51]
	v_mfma_f32_16x16x32_bf16 v[44:47], v[160:163], v[192:195], v[44:47]
	v_mfma_f32_16x16x32_bf16 v[40:43], v[168:171], v[192:195], v[40:43]
	v_mfma_f32_16x16x32_bf16 v[36:39], v[160:163], v[200:203], v[36:39]
	v_mfma_f32_16x16x32_bf16 v[32:35], v[168:171], v[200:203], v[32:35]
	v_mfma_f32_16x16x32_bf16 v[60:63], v[164:167], v[180:183], v[60:63]
	v_mfma_f32_16x16x32_bf16 v[56:59], v[172:175], v[180:183], v[56:59]
	v_mfma_f32_16x16x32_bf16 v[52:55], v[164:167], v[188:191], v[52:55]
	v_mfma_f32_16x16x32_bf16 v[48:51], v[172:175], v[188:191], v[48:51]
	v_mfma_f32_16x16x32_bf16 v[44:47], v[164:167], v[196:199], v[44:47]
	v_mfma_f32_16x16x32_bf16 v[40:43], v[172:175], v[196:199], v[40:43]
	v_mfma_f32_16x16x32_bf16 v[36:39], v[164:167], v[204:207], v[36:39]
	v_mfma_f32_16x16x32_bf16 v[32:35], v[172:175], v[204:207], v[32:35]
	s_setprio 0
	s_barrier
	s_add_u32 s84, s30, 0xfffc0080
	s_addc_u32 s85, s31, -1
	s_mov_b32 m0, s72
	v_lshl_add_u64 v[160:161], v[136:137], 0, s[84:85]
	global_load_lds_dwordx4 v[160:161], off
	s_mov_b32 m0, s73
	v_lshl_add_u64 v[160:161], v[160:161], 0, s[6:7]
	global_load_lds_dwordx4 v[160:161], off
	s_waitcnt vmcnt(6)
	s_barrier
	s_setprio 1
	v_mfma_f32_16x16x32_bf16 v[28:31], v[208:211], v[176:179], v[28:31]
	v_mfma_f32_16x16x32_bf16 v[24:27], v[216:219], v[176:179], v[24:27]
	v_mfma_f32_16x16x32_bf16 v[20:23], v[208:211], v[184:187], v[20:23]
	v_mfma_f32_16x16x32_bf16 v[16:19], v[216:219], v[184:187], v[16:19]
	v_mfma_f32_16x16x32_bf16 v[12:15], v[208:211], v[192:195], v[12:15]
	v_mfma_f32_16x16x32_bf16 v[8:11], v[216:219], v[192:195], v[8:11]
	v_mfma_f32_16x16x32_bf16 v[4:7], v[208:211], v[200:203], v[4:7]
	v_mfma_f32_16x16x32_bf16 v[0:3], v[216:219], v[200:203], v[0:3]
	v_mfma_f32_16x16x32_bf16 v[28:31], v[212:215], v[180:183], v[28:31]
	v_mfma_f32_16x16x32_bf16 v[24:27], v[220:223], v[180:183], v[24:27]
	v_mfma_f32_16x16x32_bf16 v[20:23], v[212:215], v[188:191], v[20:23]
	v_mfma_f32_16x16x32_bf16 v[16:19], v[220:223], v[188:191], v[16:19]
	v_mfma_f32_16x16x32_bf16 v[12:15], v[212:215], v[196:199], v[12:15]
	v_mfma_f32_16x16x32_bf16 v[8:11], v[220:223], v[196:199], v[8:11]
	v_mfma_f32_16x16x32_bf16 v[4:7], v[212:215], v[204:207], v[4:7]
	v_mfma_f32_16x16x32_bf16 v[0:3], v[220:223], v[204:207], v[0:3]
	s_setprio 0
	s_add_i32 s80, s80, 2
	s_add_u32 s30, s30, 0x100
	s_addc_u32 s31, s31, 0
	s_cmp_lt_u32 s80, 4
	s_barrier
	s_cbranch_scc1 .LBB0_310
	s_mov_b64 s[30:31], 0x60380
	s_mov_b32 m0, s81
	ds_read_b128 v[160:163], v138
	ds_read_b128 v[164:167], v139
	ds_read_b128 v[168:171], v140
	ds_read_b128 v[172:175], v141
	ds_read_b128 v[176:179], v158
	ds_read_b128 v[180:183], v158 offset:1024
	ds_read_b128 v[184:187], v158 offset:2048
	ds_read_b128 v[188:191], v158 offset:3072
	ds_read_b128 v[192:195], v158 offset:4096
	ds_read_b128 v[196:199], v158 offset:5120
	ds_read_b128 v[200:203], v158 offset:6144
	ds_read_b128 v[204:207], v158 offset:7168
	s_nop 0
	v_lshl_add_u64 v[134:135], v[134:135], 0, s[30:31]
	global_load_lds_dwordx4 v[134:135], off
	v_lshl_add_u64 v[134:135], v[134:135], 0, s[8:9]
	s_mov_b32 m0, s71
	s_nop 0
	global_load_lds_dwordx4 v[134:135], off
	s_barrier
	s_waitcnt lgkmcnt(0)
	s_setprio 1
	s_waitcnt lgkmcnt(0)
	v_mfma_f32_16x16x32_bf16 v[124:127], v[160:163], v[176:179], v[124:127]
	v_mfma_f32_16x16x32_bf16 v[120:123], v[168:171], v[176:179], v[120:123]
	v_mfma_f32_16x16x32_bf16 v[108:111], v[160:163], v[192:195], v[108:111]
	v_mfma_f32_16x16x32_bf16 v[104:107], v[168:171], v[192:195], v[104:107]
	v_mfma_f32_16x16x32_bf16 v[124:127], v[164:167], v[180:183], v[124:127]
	v_mfma_f32_16x16x32_bf16 v[120:123], v[172:175], v[180:183], v[120:123]
	v_mfma_f32_16x16x32_bf16 v[116:119], v[160:163], v[184:187], v[116:119]
	v_mfma_f32_16x16x32_bf16 v[112:115], v[168:171], v[184:187], v[112:115]
	v_mfma_f32_16x16x32_bf16 v[108:111], v[164:167], v[196:199], v[108:111]
	v_mfma_f32_16x16x32_bf16 v[104:107], v[172:175], v[196:199], v[104:107]
	v_mfma_f32_16x16x32_bf16 v[100:103], v[160:163], v[200:203], v[100:103]
	v_mfma_f32_16x16x32_bf16 v[96:99], v[168:171], v[200:203], v[96:99]
	v_mfma_f32_16x16x32_bf16 v[134:137], v[164:167], v[188:191], v[116:119]
	v_mfma_f32_16x16x32_bf16 v[208:211], v[172:175], v[188:191], v[112:115]
	v_mfma_f32_16x16x32_bf16 v[212:215], v[164:167], v[204:207], v[100:103]
	v_mfma_f32_16x16x32_bf16 v[216:219], v[172:175], v[204:207], v[96:99]
	s_setprio 0
	s_barrier
	s_nop 1
	ds_read_b128 v[96:99], v142
	ds_read_b128 v[100:103], v143
	ds_read_b128 v[112:115], v144
	ds_read_b128 v[116:119], v145
	s_barrier
	s_waitcnt lgkmcnt(0)
	s_setprio 1
	s_waitcnt lgkmcnt(0)
	v_mfma_f32_16x16x32_bf16 v[92:95], v[96:99], v[176:179], v[92:95]
	v_mfma_f32_16x16x32_bf16 v[88:91], v[112:115], v[176:179], v[88:91]
	v_mfma_f32_16x16x32_bf16 v[76:79], v[96:99], v[192:195], v[76:79]
	v_mfma_f32_16x16x32_bf16 v[72:75], v[112:115], v[192:195], v[72:75]
	v_mfma_f32_16x16x32_bf16 v[68:71], v[96:99], v[200:203], v[68:71]
	v_mfma_f32_16x16x32_bf16 v[64:67], v[112:115], v[200:203], v[64:67]
	v_mfma_f32_16x16x32_bf16 v[92:95], v[100:103], v[180:183], v[92:95]
	v_mfma_f32_16x16x32_bf16 v[88:91], v[116:119], v[180:183], v[88:91]
	v_mfma_f32_16x16x32_bf16 v[84:87], v[96:99], v[184:187], v[84:87]
	v_mfma_f32_16x16x32_bf16 v[80:83], v[112:115], v[184:187], v[80:83]
	v_mfma_f32_16x16x32_bf16 v[76:79], v[100:103], v[196:199], v[76:79]
	v_mfma_f32_16x16x32_bf16 v[72:75], v[116:119], v[196:199], v[72:75]
	v_mfma_f32_16x16x32_bf16 v[68:71], v[100:103], v[204:207], v[68:71]
	v_mfma_f32_16x16x32_bf16 v[64:67], v[116:119], v[204:207], v[64:67]
	v_mfma_f32_16x16x32_bf16 v[176:179], v[100:103], v[188:191], v[84:87]
	v_mfma_f32_16x16x32_bf16 v[180:183], v[116:119], v[188:191], v[80:83]
	s_setprio 0
	s_barrier
; #define LDA(dst, b, h) for (int m = 0; m < 4; ++m) for (int k = 0; k < 2; ++k) \
;     dst[m][k] = *reinterpret_cast<const bf16x8*>(aRd + (((b) * 2 + (h)) * G_HT * 2 + m * 2048 + k * 1024))
; #define LDB(dst, b, h) for (int n = 0; n < 2; ++n) for (int k = 0; k < 2; ++k) \
;     dst[n][k] = *reinterpret_cast<const bf16x8*>(bRd + (((b) * 2 + (h)) * G_HT * 2 + n * 2048 + k * 1024))
; #define MMA(ai, bj, At, Bx) do { __builtin_amdgcn_s_setprio(1); \
;     for (int m = 0; m < 4; ++m) for (int n = 0; n < 2; ++n) for (int k = 0; k < 2; ++k) \
;       acc[ai][bj][m][n] = __builtin_amdgcn_mfma_f32_16x16x32_bf16(Bx[n][k], At[m][k], acc[ai][bj][m][n], 0, 0, 0);     \
;     __builtin_amdgcn_s_setprio(0); } while (0)
; #define WAIT_V(n) asm volatile("s_waitcnt vmcnt(" #n ")" ::: "memory")
; #define WAIT_L(n) asm volatile("s_waitcnt lgkmcnt(" #n ")" ::: "memory")
; #define BAR __builtin_amdgcn_s_barrier()
; template <int EPI>
; __device__ __forceinline__ void gemm_tile(const bf16* __restrict__ A, int lda, const bf16* __restrict__ Bt, int K,
;                                           int brow, int bcol, const EpiArgs& ea, char* shmc, bool has_next, int nbrow, int nbcol, bool first_tile) {
;     ...
;     LDA(At, 0, 1); WAIT_V(4); BAR; WAIT_L(0); MMA(1, 0, At, B0); MMA(1, 1, At, B1); BAR; }
;   { LDB(B0, 1, 0); LDA(At, 1, 0); WAIT_V(2); BAR; WAIT_L(0); MMA(0, 0, At, B0); BAR;
	s_nop 0
	ds_read_b128 v[80:83], v158 offset:16384
	ds_read_b128 v[84:87], v158 offset:17408
	ds_read_b128 v[184:187], v158 offset:18432
	ds_read_b128 v[188:191], v158 offset:19456
	ds_read_b128 v[192:195], v158 offset:20480
	ds_read_b128 v[196:199], v158 offset:21504
	ds_read_b128 v[200:203], v158 offset:22528
	ds_read_b128 v[204:207], v158 offset:23552
	s_waitcnt vmcnt(4)
	s_barrier
	s_waitcnt lgkmcnt(0)
	s_setprio 1
	s_waitcnt lgkmcnt(0)
	v_mfma_f32_16x16x32_bf16 v[36:39], v[160:163], v[200:203], v[36:39]
	v_mfma_f32_16x16x32_bf16 v[32:35], v[168:171], v[200:203], v[32:35]
	v_mfma_f32_16x16x32_bf16 v[60:63], v[160:163], v[80:83], v[60:63]
	v_mfma_f32_16x16x32_bf16 v[56:59], v[168:171], v[80:83], v[56:59]
	v_mfma_f32_16x16x32_bf16 v[52:55], v[160:163], v[184:187], v[52:55]
	v_mfma_f32_16x16x32_bf16 v[48:51], v[168:171], v[184:187], v[48:51]
	v_mfma_f32_16x16x32_bf16 v[44:47], v[160:163], v[192:195], v[44:47]
	v_mfma_f32_16x16x32_bf16 v[40:43], v[168:171], v[192:195], v[40:43]
	v_mfma_f32_16x16x32_bf16 v[36:39], v[164:167], v[204:207], v[36:39]
	v_mfma_f32_16x16x32_bf16 v[32:35], v[172:175], v[204:207], v[32:35]
	v_mfma_f32_16x16x32_bf16 v[220:223], v[164:167], v[84:87], v[60:63]
	v_mfma_f32_16x16x32_bf16 v[224:227], v[172:175], v[84:87], v[56:59]
	v_mfma_f32_16x16x32_bf16 v[228:231], v[164:167], v[188:191], v[52:55]
	v_mfma_f32_16x16x32_bf16 v[232:235], v[172:175], v[188:191], v[48:51]
	v_mfma_f32_16x16x32_bf16 v[236:239], v[164:167], v[196:199], v[44:47]
	v_mfma_f32_16x16x32_bf16 v[240:243], v[172:175], v[196:199], v[40:43]
	s_setprio 0
	s_setprio 1
	v_mfma_f32_16x16x32_bf16 v[20:23], v[96:99], v[184:187], v[20:23]
	v_mfma_f32_16x16x32_bf16 v[16:19], v[112:115], v[184:187], v[16:19]
	v_mfma_f32_16x16x32_bf16 v[4:7], v[96:99], v[200:203], v[4:7]
	v_mfma_f32_16x16x32_bf16 v[28:31], v[96:99], v[80:83], v[28:31]
	v_mfma_f32_16x16x32_bf16 v[24:27], v[112:115], v[80:83], v[24:27]
	v_mfma_f32_16x16x32_bf16 v[20:23], v[100:103], v[188:191], v[20:23]
	v_mfma_f32_16x16x32_bf16 v[16:19], v[116:119], v[188:191], v[16:19]
	v_mfma_f32_16x16x32_bf16 v[12:15], v[96:99], v[192:195], v[12:15]
	v_mfma_f32_16x16x32_bf16 v[8:11], v[112:115], v[192:195], v[8:11]
	v_mfma_f32_16x16x32_bf16 v[4:7], v[100:103], v[204:207], v[4:7]
	v_mfma_f32_16x16x32_bf16 v[0:3], v[112:115], v[200:203], v[0:3]
	v_mfma_f32_16x16x32_bf16 v[160:163], v[100:103], v[84:87], v[28:31]
	v_mfma_f32_16x16x32_bf16 v[164:167], v[116:119], v[84:87], v[24:27]
	v_mfma_f32_16x16x32_bf16 v[168:171], v[100:103], v[196:199], v[12:15]
	v_mfma_f32_16x16x32_bf16 v[172:175], v[116:119], v[196:199], v[8:11]
	v_mfma_f32_16x16x32_bf16 v[184:187], v[116:119], v[204:207], v[0:3]
	s_setprio 0
	s_barrier
	s_nop 0
	ds_read_b128 v[0:3], v146
	ds_read_b128 v[8:11], v147
	ds_read_b128 v[12:15], v148
	ds_read_b128 v[188:191], v149
	ds_read_b128 v[24:27], v158 offset:32768
	ds_read_b128 v[28:31], v158 offset:33792
	ds_read_b128 v[40:43], v158 offset:34816
	ds_read_b128 v[44:47], v158 offset:35840
	ds_read_b128 v[56:59], v158 offset:36864
	ds_read_b128 v[60:63], v158 offset:37888
	ds_read_b128 v[192:195], v158 offset:38912
	ds_read_b128 v[196:199], v158 offset:39936
	s_waitcnt vmcnt(2)
	s_barrier
	s_waitcnt lgkmcnt(0)
	s_setprio 1
	s_waitcnt lgkmcnt(0)
	v_mfma_f32_16x16x32_bf16 v[48:51], v[0:3], v[24:27], v[124:127]
	v_mfma_f32_16x16x32_bf16 v[112:115], v[8:11], v[28:31], v[48:51]
	v_mfma_f32_16x16x32_bf16 v[48:51], v[12:15], v[24:27], v[120:123]
	v_mfma_f32_16x16x32_bf16 v[116:119], v[188:191], v[28:31], v[48:51]
	v_mfma_f32_16x16x32_bf16 v[48:51], v[0:3], v[40:43], v[134:137]
	v_mfma_f32_16x16x32_bf16 v[96:99], v[8:11], v[44:47], v[48:51]
	v_mfma_f32_16x16x32_bf16 v[48:51], v[12:15], v[40:43], v[208:211]
	v_mfma_f32_16x16x32_bf16 v[100:103], v[188:191], v[44:47], v[48:51]
	v_mfma_f32_16x16x32_bf16 v[48:51], v[0:3], v[56:59], v[108:111]
	v_mfma_f32_16x16x32_bf16 v[80:83], v[8:11], v[60:63], v[48:51]
	v_mfma_f32_16x16x32_bf16 v[48:51], v[12:15], v[56:59], v[104:107]
	v_mfma_f32_16x16x32_bf16 v[84:87], v[188:191], v[60:63], v[48:51]
	v_mfma_f32_16x16x32_bf16 v[48:51], v[0:3], v[192:195], v[212:215]
	v_mfma_f32_16x16x32_bf16 v[52:55], v[12:15], v[192:195], v[216:219]
	v_mfma_f32_16x16x32_bf16 v[48:51], v[8:11], v[196:199], v[48:51]
	v_mfma_f32_16x16x32_bf16 v[52:55], v[188:191], v[196:199], v[52:55]
	s_setprio 0
	s_barrier
; #define LDA(dst, b, h) for (int m = 0; m < 4; ++m) for (int k = 0; k < 2; ++k) \
;     dst[m][k] = *reinterpret_cast<const bf16x8*>(aRd + (((b) * 2 + (h)) * G_HT * 2 + m * 2048 + k * 1024))
; #define LDB(dst, b, h) for (int n = 0; n < 2; ++n) for (int k = 0; k < 2; ++k) \
;     dst[n][k] = *reinterpret_cast<const bf16x8*>(bRd + (((b) * 2 + (h)) * G_HT * 2 + n * 2048 + k * 1024))
; #define MMA(ai, bj, At, Bx) do { __builtin_amdgcn_s_setprio(1); \
;     for (int m = 0; m < 4; ++m) for (int n = 0; n < 2; ++n) for (int k = 0; k < 2; ++k) \
;       acc[ai][bj][m][n] = __builtin_amdgcn_mfma_f32_16x16x32_bf16(Bx[n][k], At[m][k], acc[ai][bj][m][n], 0, 0, 0);     \
;     __builtin_amdgcn_s_setprio(0); } while (0)
; #define WAIT_V(n) asm volatile("s_waitcnt vmcnt(" #n ")" ::: "memory")
; #define WAIT_L(n) asm volatile("s_waitcnt lgkmcnt(" #n ")" ::: "memory")
; #define BAR __builtin_amdgcn_s_barrier()
; template <int EPI>
; __device__ __forceinline__ void gemm_tile(const bf16* __restrict__ A, int lda, const bf16* __restrict__ Bt, int K,
;                                           int brow, int bcol, const EpiArgs& ea, char* shmc, bool has_next, int nbrow, int nbcol, bool first_tile) {
;     ...
;   { LDB(B0, 1, 0); LDA(At, 1, 0); WAIT_V(2); BAR; WAIT_L(0); MMA(0, 0, At, B0); BAR;
;     LDB(B1, 1, 1); WAIT_V(0); BAR; WAIT_L(0); MMA(0, 1, At, B1); BAR;
;     LDA(At, 1, 1); BAR; WAIT_L(0); MMA(1, 0, At, B0); MMA(1, 1, At, B1); BAR; }
;   if (wr == 0) BAR;
	ds_read_b128 v[134:137], v150
	ds_read_b128 v[200:203], v151
	ds_read_b128 v[204:207], v152
	ds_read_b128 v[208:211], v153
	s_waitcnt vmcnt(0)
	s_barrier
	s_waitcnt lgkmcnt(0)
	s_setprio 1
	s_waitcnt lgkmcnt(0)
	v_mfma_f32_16x16x32_bf16 v[92:95], v[134:137], v[24:27], v[92:95]
	v_mfma_f32_16x16x32_bf16 v[24:27], v[204:207], v[24:27], v[88:91]
	v_mfma_f32_16x16x32_bf16 v[124:127], v[208:211], v[28:31], v[24:27]
	v_mfma_f32_16x16x32_bf16 v[24:27], v[134:137], v[40:43], v[176:179]
	v_mfma_f32_16x16x32_bf16 v[104:107], v[200:203], v[44:47], v[24:27]
	v_mfma_f32_16x16x32_bf16 v[24:27], v[204:207], v[40:43], v[180:183]
	v_mfma_f32_16x16x32_bf16 v[108:111], v[208:211], v[44:47], v[24:27]
	v_mfma_f32_16x16x32_bf16 v[24:27], v[134:137], v[56:59], v[76:79]
	v_mfma_f32_16x16x32_bf16 v[88:91], v[200:203], v[60:63], v[24:27]
	v_mfma_f32_16x16x32_bf16 v[24:27], v[204:207], v[56:59], v[72:75]
	v_mfma_f32_16x16x32_bf16 v[120:123], v[200:203], v[28:31], v[92:95]
	v_mfma_f32_16x16x32_bf16 v[92:95], v[208:211], v[60:63], v[24:27]
	v_mfma_f32_16x16x32_bf16 v[24:27], v[134:137], v[192:195], v[68:71]
	v_mfma_f32_16x16x32_bf16 v[56:59], v[200:203], v[196:199], v[24:27]
	v_mfma_f32_16x16x32_bf16 v[24:27], v[204:207], v[192:195], v[64:67]
	v_mfma_f32_16x16x32_bf16 v[60:63], v[208:211], v[196:199], v[24:27]
	s_setprio 0
	s_barrier
	ds_read_b128 v[68:71], v158 offset:49152
	ds_read_b128 v[176:179], v158 offset:50176
	ds_read_b128 v[180:183], v158 offset:51200
	ds_read_b128 v[192:195], v158 offset:52224
	ds_read_b128 v[196:199], v158 offset:53248
	ds_read_b128 v[212:215], v158 offset:54272
	ds_read_b128 v[216:219], v158 offset:55296
	ds_read_b128 v[244:247], v158 offset:56320
	s_barrier
	s_waitcnt lgkmcnt(0)
	s_setprio 1
	s_waitcnt lgkmcnt(0)
	v_mfma_f32_16x16x32_bf16 v[24:27], v[0:3], v[68:71], v[220:223]
	v_mfma_f32_16x16x32_bf16 v[72:75], v[8:11], v[176:179], v[24:27]
	v_mfma_f32_16x16x32_bf16 v[24:27], v[12:15], v[68:71], v[224:227]
	v_mfma_f32_16x16x32_bf16 v[76:79], v[188:191], v[176:179], v[24:27]
	v_mfma_f32_16x16x32_bf16 v[24:27], v[0:3], v[180:183], v[228:231]
	v_mfma_f32_16x16x32_bf16 v[40:43], v[8:11], v[192:195], v[24:27]
	v_mfma_f32_16x16x32_bf16 v[24:27], v[12:15], v[180:183], v[232:235]
	v_mfma_f32_16x16x32_bf16 v[44:47], v[188:191], v[192:195], v[24:27]
	v_mfma_f32_16x16x32_bf16 v[24:27], v[0:3], v[196:199], v[236:239]
	v_mfma_f32_16x16x32_bf16 v[0:3], v[0:3], v[216:219], v[36:39]
	v_mfma_f32_16x16x32_bf16 v[24:27], v[8:11], v[212:215], v[24:27]
	v_mfma_f32_16x16x32_bf16 v[28:31], v[12:15], v[196:199], v[240:243]
	v_mfma_f32_16x16x32_bf16 v[8:11], v[8:11], v[244:247], v[0:3]
	v_mfma_f32_16x16x32_bf16 v[0:3], v[12:15], v[216:219], v[32:35]
	v_mfma_f32_16x16x32_bf16 v[28:31], v[188:191], v[212:215], v[28:31]
	v_mfma_f32_16x16x32_bf16 v[12:15], v[188:191], v[244:247], v[0:3]
	s_setprio 0
	s_setprio 1
	v_mfma_f32_16x16x32_bf16 v[0:3], v[134:137], v[68:71], v[160:163]
	v_mfma_f32_16x16x32_bf16 v[64:67], v[200:203], v[176:179], v[0:3]
	v_mfma_f32_16x16x32_bf16 v[0:3], v[204:207], v[68:71], v[164:167]
	v_mfma_f32_16x16x32_bf16 v[68:71], v[208:211], v[176:179], v[0:3]
	v_mfma_f32_16x16x32_bf16 v[0:3], v[134:137], v[180:183], v[20:23]
	v_mfma_f32_16x16x32_bf16 v[32:35], v[200:203], v[192:195], v[0:3]
	v_mfma_f32_16x16x32_bf16 v[0:3], v[204:207], v[180:183], v[16:19]
	v_mfma_f32_16x16x32_bf16 v[36:39], v[208:211], v[192:195], v[0:3]
	v_mfma_f32_16x16x32_bf16 v[0:3], v[134:137], v[196:199], v[168:171]
	v_mfma_f32_16x16x32_bf16 v[16:19], v[200:203], v[212:215], v[0:3]
	v_mfma_f32_16x16x32_bf16 v[0:3], v[204:207], v[196:199], v[172:175]
	v_mfma_f32_16x16x32_bf16 v[20:23], v[208:211], v[212:215], v[0:3]
	v_mfma_f32_16x16x32_bf16 v[0:3], v[134:137], v[216:219], v[4:7]
	v_mfma_f32_16x16x32_bf16 v[4:7], v[204:207], v[216:219], v[184:187]
	v_mfma_f32_16x16x32_bf16 v[0:3], v[200:203], v[244:247], v[0:3]
	v_mfma_f32_16x16x32_bf16 v[4:7], v[208:211], v[244:247], v[4:7]
	s_setprio 0
	s_barrier
	s_and_saveexec_b64 s[30:31], s[4:5]
	s_cbranch_execz .LBB0_313
	s_barrier

; #define STA(b, h, half, kt) STAGE(((b) * 2 + (h)) * G_HT * 2, pA, ((size_t)(half) * G_HALF * lda + (size_t)(kt) * G_BK) * 2, lda)
; #define STB(b, h, half, kt) STAGE((4 + (b) * 2 + (h)) * G_HT * 2, pB, ((size_t)(half) * G_HALF * K + (size_t)(kt) * G_BK) * 2, K)
; #define LDA(dst, b, h) for (int m = 0; m < 4; ++m) for (int k = 0; k < 2; ++k) \
;     dst[m][k] = *reinterpret_cast<const bf16x8*>(aRd + (((b) * 2 + (h)) * G_HT * 2 + m * 2048 + k * 1024))
; #define LDB(dst, b, h) for (int n = 0; n < 2; ++n) for (int k = 0; k < 2; ++k) \
;     dst[n][k] = *reinterpret_cast<const bf16x8*>(bRd + (((b) * 2 + (h)) * G_HT * 2 + n * 2048 + k * 1024))
; #define MMA(ai, bj, At, Bx) do { __builtin_amdgcn_s_setprio(1); \
;     for (int m = 0; m < 4; ++m) for (int n = 0; n < 2; ++n) for (int k = 0; k < 2; ++k) \
;       acc[ai][bj][m][n] = __builtin_amdgcn_mfma_f32_16x16x32_bf16(Bx[n][k], At[m][k], acc[ai][bj][m][n], 0, 0, 0);     \
;     __builtin_amdgcn_s_setprio(0); } while (0)
; #define WAIT_V(n) asm volatile("s_waitcnt vmcnt(" #n ")" ::: "memory")
; #define WAIT_L(n) asm volatile("s_waitcnt lgkmcnt(" #n ")" ::: "memory")
; #define BAR __builtin_amdgcn_s_barrier()
; #define SCHED __builtin_amdgcn_sched_barrier(0)
; template <int EPI>
; __device__ __forceinline__ void gemm_tile(const bf16* __restrict__ A, int lda, const bf16* __restrict__ Bt, int K,
;                                           int brow, int bcol, const EpiArgs& ea, char* shmc, bool has_next, int nbrow, int nbcol, bool first_tile) {
;     ...
;   for (int t = 0; t < nt - 2; t += 2) {
;     LDB(B0, 0, 0); SCHED; LDA(At, 0, 0); STA(1, 1, 1, t + 1);
;     WAIT_L(8); BAR; WAIT_L(0); MMA(0, 0, At, B0); BAR; SCHED;
;     LDB(B1, 0, 1); STB(0, 0, 0, t + 2);
;     BAR; WAIT_L(0); MMA(0, 1, At, B1); BAR;
;     LDA(At, 0, 1); STA(0, 0, 0, t + 2);
;     BAR; WAIT_L(0); MMA(1, 0, At, B0); BAR; SCHED;
;     STB(0, 1, 1, t + 2);
;     WAIT_V(6); BAR; MMA(1, 1, At, B1); BAR;
.LBB0_654:
	ds_read_b128 v[140:143], v145
	ds_read_b128 v[166:169], v146
	ds_read_b128 v[170:173], v147
	ds_read_b128 v[174:177], v148
	s_add_u32 s42, s14, 0xffffff00
	s_addc_u32 s43, s15, -1
	s_mov_b32 m0, s29
	ds_read_b128 v[178:181], v164
	ds_read_b128 v[182:185], v164 offset:1024
	ds_read_b128 v[186:189], v164 offset:2048
	ds_read_b128 v[190:193], v164 offset:3072
	ds_read_b128 v[194:197], v164 offset:4096
	ds_read_b128 v[198:201], v164 offset:5120
	ds_read_b128 v[202:205], v164 offset:6144
	ds_read_b128 v[206:209], v164 offset:7168
	v_lshl_add_u64 v[210:211], v[136:137], 0, s[42:43]
	global_load_lds_dwordx4 v[210:211], off
	s_mov_b32 m0, s21
	v_lshl_add_u64 v[210:211], v[210:211], 0, s[10:11]
	global_load_lds_dwordx4 v[210:211], off
	s_waitcnt lgkmcnt(8)
	s_barrier
	s_waitcnt lgkmcnt(0)
	s_setprio 1
	v_mfma_f32_16x16x32_bf16 v[124:127], v[140:143], v[178:181], v[124:127]
	v_mfma_f32_16x16x32_bf16 v[120:123], v[170:173], v[178:181], v[120:123]
	v_mfma_f32_16x16x32_bf16 v[116:119], v[140:143], v[186:189], v[116:119]
	v_mfma_f32_16x16x32_bf16 v[112:115], v[170:173], v[186:189], v[112:115]
	v_mfma_f32_16x16x32_bf16 v[108:111], v[140:143], v[194:197], v[108:111]
	v_mfma_f32_16x16x32_bf16 v[104:107], v[170:173], v[194:197], v[104:107]
	v_mfma_f32_16x16x32_bf16 v[100:103], v[140:143], v[202:205], v[100:103]
	v_mfma_f32_16x16x32_bf16 v[96:99], v[170:173], v[202:205], v[96:99]
	v_mfma_f32_16x16x32_bf16 v[124:127], v[166:169], v[182:185], v[124:127]
	v_mfma_f32_16x16x32_bf16 v[120:123], v[174:177], v[182:185], v[120:123]
	v_mfma_f32_16x16x32_bf16 v[116:119], v[166:169], v[190:193], v[116:119]
	v_mfma_f32_16x16x32_bf16 v[112:115], v[174:177], v[190:193], v[112:115]
	v_mfma_f32_16x16x32_bf16 v[108:111], v[166:169], v[198:201], v[108:111]
	v_mfma_f32_16x16x32_bf16 v[104:107], v[174:177], v[198:201], v[104:107]
	v_mfma_f32_16x16x32_bf16 v[100:103], v[166:169], v[206:209], v[100:103]
	v_mfma_f32_16x16x32_bf16 v[96:99], v[174:177], v[206:209], v[96:99]
	s_setprio 0
	s_barrier
	s_add_u32 s42, s14, 0xffefff80
	s_addc_u32 s43, s15, -1
	s_mov_b64 s[48:49], s[42:43]
	s_mov_b32 m0, s24
	ds_read_b128 v[210:213], v149
	ds_read_b128 v[214:217], v150
	ds_read_b128 v[218:221], v151
	ds_read_b128 v[222:225], v152
	v_lshl_add_u64 v[226:227], v[138:139], 0, s[48:49]
	global_load_lds_dwordx4 v[226:227], off
	s_mov_b32 m0, s25
	v_lshl_add_u64 v[226:227], v[226:227], 0, s[10:11]
	global_load_lds_dwordx4 v[226:227], off
	s_barrier
	s_waitcnt lgkmcnt(0)
	s_setprio 1
	v_mfma_f32_16x16x32_bf16 v[92:95], v[210:213], v[178:181], v[92:95]
	v_mfma_f32_16x16x32_bf16 v[88:91], v[218:221], v[178:181], v[88:91]
	v_mfma_f32_16x16x32_bf16 v[84:87], v[210:213], v[186:189], v[84:87]
	v_mfma_f32_16x16x32_bf16 v[80:83], v[218:221], v[186:189], v[80:83]
	v_mfma_f32_16x16x32_bf16 v[76:79], v[210:213], v[194:197], v[76:79]
	v_mfma_f32_16x16x32_bf16 v[72:75], v[218:221], v[194:197], v[72:75]
	v_mfma_f32_16x16x32_bf16 v[68:71], v[210:213], v[202:205], v[68:71]
	v_mfma_f32_16x16x32_bf16 v[64:67], v[218:221], v[202:205], v[64:67]
	v_mfma_f32_16x16x32_bf16 v[92:95], v[214:217], v[182:185], v[92:95]
	v_mfma_f32_16x16x32_bf16 v[88:91], v[222:225], v[182:185], v[88:91]
	v_mfma_f32_16x16x32_bf16 v[84:87], v[214:217], v[190:193], v[84:87]
	v_mfma_f32_16x16x32_bf16 v[80:83], v[222:225], v[190:193], v[80:83]
	v_mfma_f32_16x16x32_bf16 v[76:79], v[214:217], v[198:201], v[76:79]
	v_mfma_f32_16x16x32_bf16 v[72:75], v[222:225], v[198:201], v[72:75]
	v_mfma_f32_16x16x32_bf16 v[68:71], v[214:217], v[206:209], v[68:71]
	v_mfma_f32_16x16x32_bf16 v[64:67], v[222:225], v[206:209], v[64:67]
	s_setprio 0
	s_mov_b32 m0, s1
	s_barrier
	ds_read_b128 v[178:181], v164 offset:16384
	ds_read_b128 v[182:185], v164 offset:17408
	ds_read_b128 v[186:189], v164 offset:18432
	ds_read_b128 v[190:193], v164 offset:19456
	ds_read_b128 v[194:197], v164 offset:20480
	ds_read_b128 v[198:201], v164 offset:21504
	ds_read_b128 v[202:205], v164 offset:22528
	ds_read_b128 v[206:209], v164 offset:23552
	v_lshl_add_u64 v[226:227], v[136:137], 0, s[42:43]
	global_load_lds_dwordx4 v[226:227], off
	s_mov_b32 m0, s30
	v_lshl_add_u64 v[226:227], v[226:227], 0, s[10:11]
	global_load_lds_dwordx4 v[226:227], off
	s_barrier
	s_waitcnt lgkmcnt(0)
	s_setprio 1
	v_mfma_f32_16x16x32_bf16 v[60:63], v[140:143], v[178:181], v[60:63]
	v_mfma_f32_16x16x32_bf16 v[56:59], v[170:173], v[178:181], v[56:59]
	v_mfma_f32_16x16x32_bf16 v[52:55], v[140:143], v[186:189], v[52:55]
	v_mfma_f32_16x16x32_bf16 v[48:51], v[170:173], v[186:189], v[48:51]
	v_mfma_f32_16x16x32_bf16 v[44:47], v[140:143], v[194:197], v[44:47]
	v_mfma_f32_16x16x32_bf16 v[40:43], v[170:173], v[194:197], v[40:43]
	v_mfma_f32_16x16x32_bf16 v[36:39], v[140:143], v[202:205], v[36:39]
	v_mfma_f32_16x16x32_bf16 v[32:35], v[170:173], v[202:205], v[32:35]
	v_mfma_f32_16x16x32_bf16 v[60:63], v[166:169], v[182:185], v[60:63]
	v_mfma_f32_16x16x32_bf16 v[56:59], v[174:177], v[182:185], v[56:59]
	v_mfma_f32_16x16x32_bf16 v[52:55], v[166:169], v[190:193], v[52:55]
	v_mfma_f32_16x16x32_bf16 v[48:51], v[174:177], v[190:193], v[48:51]
	v_mfma_f32_16x16x32_bf16 v[44:47], v[166:169], v[198:201], v[44:47]
	v_mfma_f32_16x16x32_bf16 v[40:43], v[174:177], v[198:201], v[40:43]
	v_mfma_f32_16x16x32_bf16 v[36:39], v[166:169], v[206:209], v[36:39]
	v_mfma_f32_16x16x32_bf16 v[32:35], v[174:177], v[206:209], v[32:35]
	s_setprio 0
	s_barrier
	s_add_u32 s42, s14, 0xffffff80
	s_addc_u32 s43, s15, -1
	s_mov_b64 s[48:49], s[42:43]
	s_mov_b32 m0, s26
	v_lshl_add_u64 v[140:141], v[138:139], 0, s[48:49]
	global_load_lds_dwordx4 v[140:141], off
	s_mov_b32 m0, s27
	v_lshl_add_u64 v[140:141], v[140:141], 0, s[10:11]
	global_load_lds_dwordx4 v[140:141], off
	s_waitcnt vmcnt(6)
	s_barrier
; #define STA(b, h, half, kt) STAGE(((b) * 2 + (h)) * G_HT * 2, pA, ((size_t)(half) * G_HALF * lda + (size_t)(kt) * G_BK) * 2, lda)
; #define STB(b, h, half, kt) STAGE((4 + (b) * 2 + (h)) * G_HT * 2, pB, ((size_t)(half) * G_HALF * K + (size_t)(kt) * G_BK) * 2, K)
; #define LDA(dst, b, h) for (int m = 0; m < 4; ++m) for (int k = 0; k < 2; ++k) \
;     dst[m][k] = *reinterpret_cast<const bf16x8*>(aRd + (((b) * 2 + (h)) * G_HT * 2 + m * 2048 + k * 1024))
; #define LDB(dst, b, h) for (int n = 0; n < 2; ++n) for (int k = 0; k < 2; ++k) \
;     dst[n][k] = *reinterpret_cast<const bf16x8*>(bRd + (((b) * 2 + (h)) * G_HT * 2 + n * 2048 + k * 1024))
; #define MMA(ai, bj, At, Bx) do { __builtin_amdgcn_s_setprio(1); \
;     for (int m = 0; m < 4; ++m) for (int n = 0; n < 2; ++n) for (int k = 0; k < 2; ++k) \
;       acc[ai][bj][m][n] = __builtin_amdgcn_mfma_f32_16x16x32_bf16(Bx[n][k], At[m][k], acc[ai][bj][m][n], 0, 0, 0);     \
;     __builtin_amdgcn_s_setprio(0); } while (0)
; #define WAIT_V(n) asm volatile("s_waitcnt vmcnt(" #n ")" ::: "memory")
; #define WAIT_L(n) asm volatile("s_waitcnt lgkmcnt(" #n ")" ::: "memory")
; #define BAR __builtin_amdgcn_s_barrier()
; #define SCHED __builtin_amdgcn_sched_barrier(0)
; template <int EPI>
; __device__ __forceinline__ void gemm_tile(const bf16* __restrict__ A, int lda, const bf16* __restrict__ Bt, int K,
;                                           int brow, int bcol, const EpiArgs& ea, char* shmc, bool has_next, int nbrow, int nbcol, bool first_tile) {
;     ...
;     WAIT_V(6); BAR; MMA(1, 1, At, B1); BAR;
;     LDB(B0, 1, 0); SCHED; LDA(At, 1, 0); STA(0, 1, 1, t + 2);
;     WAIT_L(8); BAR; WAIT_L(0); MMA(0, 0, At, B0); BAR; SCHED;
;     LDB(B1, 1, 1); STB(1, 0, 0, t + 3);
;     BAR; WAIT_L(0); MMA(0, 1, At, B1); BAR;
;     LDA(At, 1, 1); STA(1, 0, 0, t + 3);
;     BAR; WAIT_L(0); MMA(1, 0, At, B0); BAR; SCHED;
	s_setprio 1
	v_mfma_f32_16x16x32_bf16 v[28:31], v[210:213], v[178:181], v[28:31]
	v_mfma_f32_16x16x32_bf16 v[24:27], v[218:221], v[178:181], v[24:27]
	v_mfma_f32_16x16x32_bf16 v[20:23], v[210:213], v[186:189], v[20:23]
	v_mfma_f32_16x16x32_bf16 v[16:19], v[218:221], v[186:189], v[16:19]
	v_mfma_f32_16x16x32_bf16 v[12:15], v[210:213], v[194:197], v[12:15]
	v_mfma_f32_16x16x32_bf16 v[8:11], v[218:221], v[194:197], v[8:11]
	v_mfma_f32_16x16x32_bf16 v[4:7], v[210:213], v[202:205], v[4:7]
	v_mfma_f32_16x16x32_bf16 v[0:3], v[218:221], v[202:205], v[0:3]
	v_mfma_f32_16x16x32_bf16 v[28:31], v[214:217], v[182:185], v[28:31]
	v_mfma_f32_16x16x32_bf16 v[24:27], v[222:225], v[182:185], v[24:27]
	v_mfma_f32_16x16x32_bf16 v[20:23], v[214:217], v[190:193], v[20:23]
	v_mfma_f32_16x16x32_bf16 v[16:19], v[222:225], v[190:193], v[16:19]
	v_mfma_f32_16x16x32_bf16 v[12:15], v[214:217], v[198:201], v[12:15]
	v_mfma_f32_16x16x32_bf16 v[8:11], v[222:225], v[198:201], v[8:11]
	v_mfma_f32_16x16x32_bf16 v[4:7], v[214:217], v[206:209], v[4:7]
	v_mfma_f32_16x16x32_bf16 v[0:3], v[222:225], v[206:209], v[0:3]
	s_setprio 0
	s_barrier
	ds_read_b128 v[140:143], v153
	ds_read_b128 v[166:169], v154
	ds_read_b128 v[170:173], v155
	ds_read_b128 v[174:177], v156
	s_mov_b32 m0, s31
	ds_read_b128 v[178:181], v164 offset:32768
	ds_read_b128 v[182:185], v164 offset:33792
	ds_read_b128 v[186:189], v164 offset:34816
	ds_read_b128 v[190:193], v164 offset:35840
	ds_read_b128 v[194:197], v164 offset:36864
	ds_read_b128 v[198:201], v164 offset:37888
	ds_read_b128 v[202:205], v164 offset:38912
	ds_read_b128 v[206:209], v164 offset:39936
	v_lshl_add_u64 v[210:211], v[136:137], 0, s[42:43]
	global_load_lds_dwordx4 v[210:211], off
	s_mov_b32 m0, s34
	v_lshl_add_u64 v[210:211], v[210:211], 0, s[10:11]
	global_load_lds_dwordx4 v[210:211], off
	s_waitcnt lgkmcnt(8)
	s_barrier
	s_waitcnt lgkmcnt(0)
	s_setprio 1
	v_mfma_f32_16x16x32_bf16 v[124:127], v[140:143], v[178:181], v[124:127]
	v_mfma_f32_16x16x32_bf16 v[120:123], v[170:173], v[178:181], v[120:123]
	v_mfma_f32_16x16x32_bf16 v[116:119], v[140:143], v[186:189], v[116:119]
	v_mfma_f32_16x16x32_bf16 v[112:115], v[170:173], v[186:189], v[112:115]
	v_mfma_f32_16x16x32_bf16 v[108:111], v[140:143], v[194:197], v[108:111]
	v_mfma_f32_16x16x32_bf16 v[104:107], v[170:173], v[194:197], v[104:107]
	v_mfma_f32_16x16x32_bf16 v[100:103], v[140:143], v[202:205], v[100:103]
	v_mfma_f32_16x16x32_bf16 v[96:99], v[170:173], v[202:205], v[96:99]
	v_mfma_f32_16x16x32_bf16 v[124:127], v[166:169], v[182:185], v[124:127]
	v_mfma_f32_16x16x32_bf16 v[120:123], v[174:177], v[182:185], v[120:123]
	v_mfma_f32_16x16x32_bf16 v[116:119], v[166:169], v[190:193], v[116:119]
	v_mfma_f32_16x16x32_bf16 v[112:115], v[174:177], v[190:193], v[112:115]
	v_mfma_f32_16x16x32_bf16 v[108:111], v[166:169], v[198:201], v[108:111]
	v_mfma_f32_16x16x32_bf16 v[104:107], v[174:177], v[198:201], v[104:107]
	v_mfma_f32_16x16x32_bf16 v[100:103], v[166:169], v[206:209], v[100:103]
	v_mfma_f32_16x16x32_bf16 v[96:99], v[174:177], v[206:209], v[96:99]
	s_setprio 0
	s_barrier
	s_add_u32 s42, s14, 0xfff00000
	s_addc_u32 s43, s15, -1
	s_mov_b64 s[48:49], s[42:43]
	s_mov_b32 m0, s13
	ds_read_b128 v[210:213], v158
	ds_read_b128 v[214:217], v159
	ds_read_b128 v[218:221], v160
	ds_read_b128 v[222:225], v161
	v_lshl_add_u64 v[226:227], v[138:139], 0, s[48:49]
	global_load_lds_dwordx4 v[226:227], off
	s_mov_b32 m0, s18
	v_lshl_add_u64 v[226:227], v[226:227], 0, s[10:11]
	global_load_lds_dwordx4 v[226:227], off
	s_barrier
	s_waitcnt lgkmcnt(0)
	s_setprio 1
	v_mfma_f32_16x16x32_bf16 v[92:95], v[210:213], v[178:181], v[92:95]
	v_mfma_f32_16x16x32_bf16 v[88:91], v[218:221], v[178:181], v[88:91]
	v_mfma_f32_16x16x32_bf16 v[84:87], v[210:213], v[186:189], v[84:87]
	v_mfma_f32_16x16x32_bf16 v[80:83], v[218:221], v[186:189], v[80:83]
	v_mfma_f32_16x16x32_bf16 v[76:79], v[210:213], v[194:197], v[76:79]
	v_mfma_f32_16x16x32_bf16 v[72:75], v[218:221], v[194:197], v[72:75]
	v_mfma_f32_16x16x32_bf16 v[68:71], v[210:213], v[202:205], v[68:71]
	v_mfma_f32_16x16x32_bf16 v[64:67], v[218:221], v[202:205], v[64:67]
	v_mfma_f32_16x16x32_bf16 v[92:95], v[214:217], v[182:185], v[92:95]
	v_mfma_f32_16x16x32_bf16 v[88:91], v[222:225], v[182:185], v[88:91]
	v_mfma_f32_16x16x32_bf16 v[84:87], v[214:217], v[190:193], v[84:87]
	v_mfma_f32_16x16x32_bf16 v[80:83], v[222:225], v[190:193], v[80:83]
	v_mfma_f32_16x16x32_bf16 v[76:79], v[214:217], v[198:201], v[76:79]
	v_mfma_f32_16x16x32_bf16 v[72:75], v[222:225], v[198:201], v[72:75]
	v_mfma_f32_16x16x32_bf16 v[68:71], v[214:217], v[206:209], v[68:71]
	v_mfma_f32_16x16x32_bf16 v[64:67], v[222:225], v[206:209], v[64:67]
	s_setprio 0
	s_mov_b32 m0, s19
	s_barrier
	ds_read_b128 v[178:181], v164 offset:49152
	ds_read_b128 v[182:185], v164 offset:50176
	ds_read_b128 v[186:189], v164 offset:51200
	ds_read_b128 v[190:193], v164 offset:52224
	ds_read_b128 v[194:197], v164 offset:53248
	ds_read_b128 v[198:201], v164 offset:54272
	ds_read_b128 v[202:205], v164 offset:55296
	ds_read_b128 v[206:209], v164 offset:56320
	v_lshl_add_u64 v[226:227], v[136:137], 0, s[42:43]
	global_load_lds_dwordx4 v[226:227], off
	s_mov_b32 m0, s20
	v_lshl_add_u64 v[226:227], v[226:227], 0, s[10:11]
	global_load_lds_dwordx4 v[226:227], off
	s_barrier
; #define STA(b, h, half, kt) STAGE(((b) * 2 + (h)) * G_HT * 2, pA, ((size_t)(half) * G_HALF * lda + (size_t)(kt) * G_BK) * 2, lda)
; #define STB(b, h, half, kt) STAGE((4 + (b) * 2 + (h)) * G_HT * 2, pB, ((size_t)(half) * G_HALF * K + (size_t)(kt) * G_BK) * 2, K)
; #define LDA(dst, b, h) for (int m = 0; m < 4; ++m) for (int k = 0; k < 2; ++k) \
;     dst[m][k] = *reinterpret_cast<const bf16x8*>(aRd + (((b) * 2 + (h)) * G_HT * 2 + m * 2048 + k * 1024))
; #define LDB(dst, b, h) for (int n = 0; n < 2; ++n) for (int k = 0; k < 2; ++k) \
;     dst[n][k] = *reinterpret_cast<const bf16x8*>(bRd + (((b) * 2 + (h)) * G_HT * 2 + n * 2048 + k * 1024))
; #define MMA(ai, bj, At, Bx) do { __builtin_amdgcn_s_setprio(1); \
;     for (int m = 0; m < 4; ++m) for (int n = 0; n < 2; ++n) for (int k = 0; k < 2; ++k) \
;       acc[ai][bj][m][n] = __builtin_amdgcn_mfma_f32_16x16x32_bf16(Bx[n][k], At[m][k], acc[ai][bj][m][n], 0, 0, 0);     \
;     __builtin_amdgcn_s_setprio(0); } while (0)
; #define WAIT_V(n) asm volatile("s_waitcnt vmcnt(" #n ")" ::: "memory")
; #define WAIT_L(n) asm volatile("s_waitcnt lgkmcnt(" #n ")" ::: "memory")
; #define BAR __builtin_amdgcn_s_barrier()
; #define SCHED __builtin_amdgcn_sched_barrier(0)
; template <int EPI>
; __device__ __forceinline__ void gemm_tile(const bf16* __restrict__ A, int lda, const bf16* __restrict__ Bt, int K,
;                                           int brow, int bcol, const EpiArgs& ea, char* shmc, bool has_next, int nbrow, int nbcol, bool first_tile) {
;     ...
;     BAR; WAIT_L(0); MMA(1, 0, At, B0); BAR; SCHED;
;     STB(1, 1, 1, t + 3);
;     WAIT_V(6); BAR; MMA(1, 1, At, B1); BAR;
;   }
;   { LDB(B0, 0, 0); LDA(At, 0, 0); STA(1, 1, 1, nt - 1);
;     BAR; WAIT_L(0); MMA(0, 0, At, B0); BAR;
;     LDB(B1, 0, 1); BAR; WAIT_L(0); MMA(0, 1, At, B1); BAR;
;     LDA(At, 0, 1); WAIT_V(4); BAR; WAIT_L(0); MMA(1, 0, At, B0); MMA(1, 1, At, B1); BAR; }
	s_waitcnt lgkmcnt(0)
	s_setprio 1
	v_mfma_f32_16x16x32_bf16 v[60:63], v[140:143], v[178:181], v[60:63]
	v_mfma_f32_16x16x32_bf16 v[56:59], v[170:173], v[178:181], v[56:59]
	v_mfma_f32_16x16x32_bf16 v[52:55], v[140:143], v[186:189], v[52:55]
	v_mfma_f32_16x16x32_bf16 v[48:51], v[170:173], v[186:189], v[48:51]
	v_mfma_f32_16x16x32_bf16 v[44:47], v[140:143], v[194:197], v[44:47]
	v_mfma_f32_16x16x32_bf16 v[40:43], v[170:173], v[194:197], v[40:43]
	v_mfma_f32_16x16x32_bf16 v[36:39], v[140:143], v[202:205], v[36:39]
	v_mfma_f32_16x16x32_bf16 v[32:35], v[170:173], v[202:205], v[32:35]
	v_mfma_f32_16x16x32_bf16 v[60:63], v[166:169], v[182:185], v[60:63]
	v_mfma_f32_16x16x32_bf16 v[56:59], v[174:177], v[182:185], v[56:59]
	v_mfma_f32_16x16x32_bf16 v[52:55], v[166:169], v[190:193], v[52:55]
	v_mfma_f32_16x16x32_bf16 v[48:51], v[174:177], v[190:193], v[48:51]
	v_mfma_f32_16x16x32_bf16 v[44:47], v[166:169], v[198:201], v[44:47]
	v_mfma_f32_16x16x32_bf16 v[40:43], v[174:177], v[198:201], v[40:43]
	v_mfma_f32_16x16x32_bf16 v[36:39], v[166:169], v[206:209], v[36:39]
	v_mfma_f32_16x16x32_bf16 v[32:35], v[174:177], v[206:209], v[32:35]
	s_setprio 0
	s_barrier
	s_mov_b64 s[42:43], s[14:15]
	s_mov_b32 m0, s22
	v_lshl_add_u64 v[140:141], v[138:139], 0, s[42:43]
	global_load_lds_dwordx4 v[140:141], off
	s_mov_b32 m0, s23
	v_lshl_add_u64 v[140:141], v[140:141], 0, s[10:11]
	global_load_lds_dwordx4 v[140:141], off
	s_waitcnt vmcnt(6)
	s_barrier
	s_setprio 1
	v_mfma_f32_16x16x32_bf16 v[28:31], v[210:213], v[178:181], v[28:31]
	v_mfma_f32_16x16x32_bf16 v[24:27], v[218:221], v[178:181], v[24:27]
	v_mfma_f32_16x16x32_bf16 v[20:23], v[210:213], v[186:189], v[20:23]
	v_mfma_f32_16x16x32_bf16 v[16:19], v[218:221], v[186:189], v[16:19]
	v_mfma_f32_16x16x32_bf16 v[12:15], v[210:213], v[194:197], v[12:15]
	v_mfma_f32_16x16x32_bf16 v[8:11], v[218:221], v[194:197], v[8:11]
	v_mfma_f32_16x16x32_bf16 v[4:7], v[210:213], v[202:205], v[4:7]
	v_mfma_f32_16x16x32_bf16 v[0:3], v[218:221], v[202:205], v[0:3]
	v_mfma_f32_16x16x32_bf16 v[28:31], v[214:217], v[182:185], v[28:31]
	v_mfma_f32_16x16x32_bf16 v[24:27], v[222:225], v[182:185], v[24:27]
	v_mfma_f32_16x16x32_bf16 v[20:23], v[214:217], v[190:193], v[20:23]
	v_mfma_f32_16x16x32_bf16 v[16:19], v[222:225], v[190:193], v[16:19]
	v_mfma_f32_16x16x32_bf16 v[12:15], v[214:217], v[198:201], v[12:15]
	v_mfma_f32_16x16x32_bf16 v[8:11], v[222:225], v[198:201], v[8:11]
	v_mfma_f32_16x16x32_bf16 v[4:7], v[214:217], v[206:209], v[4:7]
	v_mfma_f32_16x16x32_bf16 v[0:3], v[222:225], v[206:209], v[0:3]
	s_setprio 0
	s_add_i32 s28, s28, 2
	s_add_u32 s14, s14, 0x100
	s_addc_u32 s15, s15, 0
	s_cmp_lt_u32 s28, 60
	s_barrier
	s_cbranch_scc1 .LBB0_654
	s_mov_b64 s[14:15], 0x101f80
	s_mov_b32 m0, s29
	ds_read_b128 v[138:141], v145
	ds_read_b128 v[166:169], v146
	ds_read_b128 v[170:173], v147
	ds_read_b128 v[174:177], v148
	ds_read_b128 v[178:181], v164
	ds_read_b128 v[182:185], v164 offset:1024
	ds_read_b128 v[186:189], v164 offset:2048
	ds_read_b128 v[190:193], v164 offset:3072
	ds_read_b128 v[194:197], v164 offset:4096
	ds_read_b128 v[198:201], v164 offset:5120
	ds_read_b128 v[202:205], v164 offset:6144
	ds_read_b128 v[206:209], v164 offset:7168
	s_nop 0
	v_lshl_add_u64 v[136:137], v[136:137], 0, s[14:15]
	global_load_lds_dwordx4 v[136:137], off
	v_lshl_add_u64 v[136:137], v[136:137], 0, s[10:11]
	s_mov_b32 m0, s21
	s_nop 0
	global_load_lds_dwordx4 v[136:137], off
	s_barrier
	s_waitcnt lgkmcnt(0)
	s_setprio 1
	s_waitcnt lgkmcnt(0)
	v_mfma_f32_16x16x32_bf16 v[124:127], v[138:141], v[178:181], v[124:127]
	v_mfma_f32_16x16x32_bf16 v[116:119], v[138:141], v[186:189], v[116:119]
	v_mfma_f32_16x16x32_bf16 v[112:115], v[170:173], v[186:189], v[112:115]
	v_mfma_f32_16x16x32_bf16 v[100:103], v[138:141], v[202:205], v[100:103]
	v_mfma_f32_16x16x32_bf16 v[96:99], v[170:173], v[202:205], v[96:99]
	v_mfma_f32_16x16x32_bf16 v[124:127], v[166:169], v[182:185], v[124:127]
	v_mfma_f32_16x16x32_bf16 v[120:123], v[170:173], v[178:181], v[120:123]
	v_mfma_f32_16x16x32_bf16 v[116:119], v[166:169], v[190:193], v[116:119]
	v_mfma_f32_16x16x32_bf16 v[112:115], v[174:177], v[190:193], v[112:115]
	v_mfma_f32_16x16x32_bf16 v[108:111], v[138:141], v[194:197], v[108:111]
	v_mfma_f32_16x16x32_bf16 v[104:107], v[170:173], v[194:197], v[104:107]
	v_mfma_f32_16x16x32_bf16 v[100:103], v[166:169], v[206:209], v[100:103]
	v_mfma_f32_16x16x32_bf16 v[96:99], v[174:177], v[206:209], v[96:99]
	v_mfma_f32_16x16x32_bf16 v[210:213], v[174:177], v[182:185], v[120:123]
	v_mfma_f32_16x16x32_bf16 v[214:217], v[166:169], v[198:201], v[108:111]
	v_mfma_f32_16x16x32_bf16 v[218:221], v[174:177], v[198:201], v[104:107]
	s_setprio 0
	s_barrier
	s_nop 0
	ds_read_b128 v[104:107], v149
	ds_read_b128 v[108:111], v150
	ds_read_b128 v[120:123], v151
	ds_read_b128 v[222:225], v152
	s_barrier
	s_waitcnt lgkmcnt(0)
	s_setprio 1
	s_waitcnt lgkmcnt(0)
	v_mfma_f32_16x16x32_bf16 v[84:87], v[104:107], v[186:189], v[84:87]
	v_mfma_f32_16x16x32_bf16 v[80:83], v[120:123], v[186:189], v[80:83]
	v_mfma_f32_16x16x32_bf16 v[68:71], v[104:107], v[202:205], v[68:71]
	v_mfma_f32_16x16x32_bf16 v[92:95], v[104:107], v[178:181], v[92:95]
	v_mfma_f32_16x16x32_bf16 v[88:91], v[120:123], v[178:181], v[88:91]
	v_mfma_f32_16x16x32_bf16 v[84:87], v[108:111], v[190:193], v[84:87]
	v_mfma_f32_16x16x32_bf16 v[80:83], v[222:225], v[190:193], v[80:83]
	v_mfma_f32_16x16x32_bf16 v[76:79], v[104:107], v[194:197], v[76:79]
	v_mfma_f32_16x16x32_bf16 v[72:75], v[120:123], v[194:197], v[72:75]
	v_mfma_f32_16x16x32_bf16 v[68:71], v[108:111], v[206:209], v[68:71]
	v_mfma_f32_16x16x32_bf16 v[64:67], v[120:123], v[202:205], v[64:67]
	v_mfma_f32_16x16x32_bf16 v[226:229], v[108:111], v[182:185], v[92:95]
	v_mfma_f32_16x16x32_bf16 v[178:181], v[222:225], v[182:185], v[88:91]
	v_mfma_f32_16x16x32_bf16 v[182:185], v[108:111], v[198:201], v[76:79]
	v_mfma_f32_16x16x32_bf16 v[186:189], v[222:225], v[198:201], v[72:75]
	v_mfma_f32_16x16x32_bf16 v[190:193], v[222:225], v[206:209], v[64:67]
	s_setprio 0
	s_barrier
; #define LDA(dst, b, h) for (int m = 0; m < 4; ++m) for (int k = 0; k < 2; ++k) \
;     dst[m][k] = *reinterpret_cast<const bf16x8*>(aRd + (((b) * 2 + (h)) * G_HT * 2 + m * 2048 + k * 1024))
; #define LDB(dst, b, h) for (int n = 0; n < 2; ++n) for (int k = 0; k < 2; ++k) \
;     dst[n][k] = *reinterpret_cast<const bf16x8*>(bRd + (((b) * 2 + (h)) * G_HT * 2 + n * 2048 + k * 1024))
; #define MMA(ai, bj, At, Bx) do { __builtin_amdgcn_s_setprio(1); \
;     for (int m = 0; m < 4; ++m) for (int n = 0; n < 2; ++n) for (int k = 0; k < 2; ++k) \
;       acc[ai][bj][m][n] = __builtin_amdgcn_mfma_f32_16x16x32_bf16(Bx[n][k], At[m][k], acc[ai][bj][m][n], 0, 0, 0);     \
;     __builtin_amdgcn_s_setprio(0); } while (0)
; #define WAIT_V(n) asm volatile("s_waitcnt vmcnt(" #n ")" ::: "memory")
; #define WAIT_L(n) asm volatile("s_waitcnt lgkmcnt(" #n ")" ::: "memory")
; #define BAR __builtin_amdgcn_s_barrier()
; template <int EPI>
; __device__ __forceinline__ void gemm_tile(const bf16* __restrict__ A, int lda, const bf16* __restrict__ Bt, int K,
;                                           int brow, int bcol, const EpiArgs& ea, char* shmc, bool has_next, int nbrow, int nbcol, bool first_tile) {
;     ...
;     LDA(At, 0, 1); WAIT_V(4); BAR; WAIT_L(0); MMA(1, 0, At, B0); MMA(1, 1, At, B1); BAR; }
;   { LDB(B0, 1, 0); LDA(At, 1, 0); WAIT_V(2); BAR; WAIT_L(0); MMA(0, 0, At, B0); BAR;
	s_nop 0
	ds_read_b128 v[64:67], v164 offset:16384
	ds_read_b128 v[72:75], v164 offset:17408
	ds_read_b128 v[76:79], v164 offset:18432
	ds_read_b128 v[88:91], v164 offset:19456
	ds_read_b128 v[92:95], v164 offset:20480
	ds_read_b128 v[194:197], v164 offset:21504
	ds_read_b128 v[198:201], v164 offset:22528
	ds_read_b128 v[202:205], v164 offset:23552
	s_waitcnt vmcnt(4)
	s_barrier
	s_waitcnt lgkmcnt(0)
	s_setprio 1
	s_waitcnt lgkmcnt(0)
	v_mfma_f32_16x16x32_bf16 v[60:63], v[138:141], v[64:67], v[60:63]
	v_mfma_f32_16x16x32_bf16 v[52:55], v[138:141], v[76:79], v[52:55]
	v_mfma_f32_16x16x32_bf16 v[48:51], v[170:173], v[76:79], v[48:51]
	v_mfma_f32_16x16x32_bf16 v[36:39], v[138:141], v[198:201], v[36:39]
	v_mfma_f32_16x16x32_bf16 v[32:35], v[170:173], v[198:201], v[32:35]
	v_mfma_f32_16x16x32_bf16 v[60:63], v[166:169], v[72:75], v[60:63]
	v_mfma_f32_16x16x32_bf16 v[56:59], v[170:173], v[64:67], v[56:59]
	v_mfma_f32_16x16x32_bf16 v[52:55], v[166:169], v[88:91], v[52:55]
	v_mfma_f32_16x16x32_bf16 v[48:51], v[174:177], v[88:91], v[48:51]
	v_mfma_f32_16x16x32_bf16 v[44:47], v[138:141], v[92:95], v[44:47]
	v_mfma_f32_16x16x32_bf16 v[40:43], v[170:173], v[92:95], v[40:43]
	v_mfma_f32_16x16x32_bf16 v[36:39], v[166:169], v[202:205], v[36:39]
	v_mfma_f32_16x16x32_bf16 v[32:35], v[174:177], v[202:205], v[32:35]
	v_mfma_f32_16x16x32_bf16 v[206:209], v[174:177], v[72:75], v[56:59]
	v_mfma_f32_16x16x32_bf16 v[230:233], v[166:169], v[194:197], v[44:47]
	v_mfma_f32_16x16x32_bf16 v[234:237], v[174:177], v[194:197], v[40:43]
	s_setprio 0
	s_setprio 1
	v_mfma_f32_16x16x32_bf16 v[20:23], v[104:107], v[76:79], v[20:23]
	v_mfma_f32_16x16x32_bf16 v[16:19], v[120:123], v[76:79], v[16:19]
	v_mfma_f32_16x16x32_bf16 v[4:7], v[104:107], v[198:201], v[4:7]
	v_mfma_f32_16x16x32_bf16 v[28:31], v[104:107], v[64:67], v[28:31]
	v_mfma_f32_16x16x32_bf16 v[24:27], v[120:123], v[64:67], v[24:27]
	v_mfma_f32_16x16x32_bf16 v[20:23], v[108:111], v[88:91], v[20:23]
	v_mfma_f32_16x16x32_bf16 v[16:19], v[222:225], v[88:91], v[16:19]
	v_mfma_f32_16x16x32_bf16 v[12:15], v[104:107], v[92:95], v[12:15]
	v_mfma_f32_16x16x32_bf16 v[8:11], v[120:123], v[92:95], v[8:11]
	v_mfma_f32_16x16x32_bf16 v[4:7], v[108:111], v[202:205], v[4:7]
	v_mfma_f32_16x16x32_bf16 v[0:3], v[120:123], v[198:201], v[0:3]
	v_mfma_f32_16x16x32_bf16 v[136:139], v[108:111], v[72:75], v[28:31]
	v_mfma_f32_16x16x32_bf16 v[140:143], v[222:225], v[72:75], v[24:27]
	v_mfma_f32_16x16x32_bf16 v[166:169], v[108:111], v[194:197], v[12:15]
	v_mfma_f32_16x16x32_bf16 v[170:173], v[222:225], v[194:197], v[8:11]
	v_mfma_f32_16x16x32_bf16 v[174:177], v[222:225], v[202:205], v[0:3]
	s_setprio 0
	s_barrier
	s_nop 0
	ds_read_b128 v[0:3], v153
	ds_read_b128 v[8:11], v154
	ds_read_b128 v[12:15], v155
	ds_read_b128 v[194:197], v156
	ds_read_b128 v[24:27], v164 offset:32768
	ds_read_b128 v[28:31], v164 offset:33792
	ds_read_b128 v[40:43], v164 offset:34816
	ds_read_b128 v[44:47], v164 offset:35840
	ds_read_b128 v[56:59], v164 offset:36864
	ds_read_b128 v[64:67], v164 offset:37888
	ds_read_b128 v[198:201], v164 offset:38912
	ds_read_b128 v[202:205], v164 offset:39936
	s_waitcnt vmcnt(2)
	s_barrier
	s_waitcnt lgkmcnt(0)
	s_setprio 1
	s_waitcnt lgkmcnt(0)
	v_mfma_f32_16x16x32_bf16 v[72:75], v[0:3], v[24:27], v[124:127]
	v_mfma_f32_16x16x32_bf16 v[120:123], v[8:11], v[28:31], v[72:75]
	v_mfma_f32_16x16x32_bf16 v[72:75], v[12:15], v[24:27], v[210:213]
	v_mfma_f32_16x16x32_bf16 v[124:127], v[194:197], v[28:31], v[72:75]
	v_mfma_f32_16x16x32_bf16 v[72:75], v[0:3], v[40:43], v[116:119]
	v_mfma_f32_16x16x32_bf16 v[104:107], v[8:11], v[44:47], v[72:75]
	v_mfma_f32_16x16x32_bf16 v[72:75], v[12:15], v[40:43], v[112:115]
	v_mfma_f32_16x16x32_bf16 v[108:111], v[194:197], v[44:47], v[72:75]
	v_mfma_f32_16x16x32_bf16 v[72:75], v[0:3], v[56:59], v[214:217]
	v_mfma_f32_16x16x32_bf16 v[88:91], v[8:11], v[64:67], v[72:75]
	v_mfma_f32_16x16x32_bf16 v[72:75], v[12:15], v[56:59], v[218:221]
	v_mfma_f32_16x16x32_bf16 v[92:95], v[194:197], v[64:67], v[72:75]
	v_mfma_f32_16x16x32_bf16 v[72:75], v[0:3], v[198:201], v[100:103]
	v_mfma_f32_16x16x32_bf16 v[76:79], v[12:15], v[198:201], v[96:99]
	v_mfma_f32_16x16x32_bf16 v[72:75], v[8:11], v[202:205], v[72:75]
	v_mfma_f32_16x16x32_bf16 v[76:79], v[194:197], v[202:205], v[76:79]
	s_setprio 0
	s_barrier
; #define LDA(dst, b, h) for (int m = 0; m < 4; ++m) for (int k = 0; k < 2; ++k) \
;     dst[m][k] = *reinterpret_cast<const bf16x8*>(aRd + (((b) * 2 + (h)) * G_HT * 2 + m * 2048 + k * 1024))
; #define LDB(dst, b, h) for (int n = 0; n < 2; ++n) for (int k = 0; k < 2; ++k) \
;     dst[n][k] = *reinterpret_cast<const bf16x8*>(bRd + (((b) * 2 + (h)) * G_HT * 2 + n * 2048 + k * 1024))
; #define MMA(ai, bj, At, Bx) do { __builtin_amdgcn_s_setprio(1); \
;     for (int m = 0; m < 4; ++m) for (int n = 0; n < 2; ++n) for (int k = 0; k < 2; ++k) \
;       acc[ai][bj][m][n] = __builtin_amdgcn_mfma_f32_16x16x32_bf16(Bx[n][k], At[m][k], acc[ai][bj][m][n], 0, 0, 0);     \
;     __builtin_amdgcn_s_setprio(0); } while (0)
; #define WAIT_V(n) asm volatile("s_waitcnt vmcnt(" #n ")" ::: "memory")
; #define WAIT_L(n) asm volatile("s_waitcnt lgkmcnt(" #n ")" ::: "memory")
; #define BAR __builtin_amdgcn_s_barrier()
; template <int EPI>
; __device__ __forceinline__ void gemm_tile(const bf16* __restrict__ A, int lda, const bf16* __restrict__ Bt, int K,
;                                           int brow, int bcol, const EpiArgs& ea, char* shmc, bool has_next, int nbrow, int nbcol, bool first_tile) {
;     ...
;   { LDB(B0, 1, 0); LDA(At, 1, 0); WAIT_V(2); BAR; WAIT_L(0); MMA(0, 0, At, B0); BAR;
;     LDB(B1, 1, 1); WAIT_V(0); BAR; WAIT_L(0); MMA(0, 1, At, B1); BAR;
;     LDA(At, 1, 1); BAR; WAIT_L(0); MMA(1, 0, At, B0); MMA(1, 1, At, B1); BAR; }
;   if (wr == 0) BAR;
	ds_read_b128 v[210:213], v158
	ds_read_b128 v[214:217], v159
	ds_read_b128 v[218:221], v160
	ds_read_b128 v[222:225], v161
	s_waitcnt vmcnt(0)
	s_barrier
	s_waitcnt lgkmcnt(0)
	s_setprio 1
	s_waitcnt lgkmcnt(0)
	v_mfma_f32_16x16x32_bf16 v[96:99], v[210:213], v[24:27], v[226:229]
	v_mfma_f32_16x16x32_bf16 v[24:27], v[218:221], v[24:27], v[178:181]
	v_mfma_f32_16x16x32_bf16 v[116:119], v[222:225], v[28:31], v[24:27]
	v_mfma_f32_16x16x32_bf16 v[24:27], v[210:213], v[40:43], v[84:87]
	v_mfma_f32_16x16x32_bf16 v[112:115], v[214:217], v[28:31], v[96:99]
	v_mfma_f32_16x16x32_bf16 v[96:99], v[214:217], v[44:47], v[24:27]
	v_mfma_f32_16x16x32_bf16 v[24:27], v[218:221], v[40:43], v[80:83]
	v_mfma_f32_16x16x32_bf16 v[100:103], v[222:225], v[44:47], v[24:27]
	v_mfma_f32_16x16x32_bf16 v[24:27], v[210:213], v[56:59], v[182:185]
	v_mfma_f32_16x16x32_bf16 v[80:83], v[214:217], v[64:67], v[24:27]
	v_mfma_f32_16x16x32_bf16 v[24:27], v[218:221], v[56:59], v[186:189]
	v_mfma_f32_16x16x32_bf16 v[84:87], v[222:225], v[64:67], v[24:27]
	v_mfma_f32_16x16x32_bf16 v[24:27], v[210:213], v[198:201], v[68:71]
	v_mfma_f32_16x16x32_bf16 v[64:67], v[214:217], v[202:205], v[24:27]
	v_mfma_f32_16x16x32_bf16 v[24:27], v[218:221], v[198:201], v[190:193]
	v_mfma_f32_16x16x32_bf16 v[68:71], v[222:225], v[202:205], v[24:27]
	s_setprio 0
	s_barrier
	ds_read_b128 v[178:181], v164 offset:49152
	ds_read_b128 v[182:185], v164 offset:50176
	ds_read_b128 v[186:189], v164 offset:51200
	ds_read_b128 v[190:193], v164 offset:52224
	ds_read_b128 v[198:201], v164 offset:53248
	ds_read_b128 v[202:205], v164 offset:54272
	ds_read_b128 v[226:229], v164 offset:55296
	ds_read_b128 v[238:241], v164 offset:56320
	s_barrier
	s_waitcnt lgkmcnt(0)
	s_setprio 1
	s_waitcnt lgkmcnt(0)
	v_mfma_f32_16x16x32_bf16 v[24:27], v[0:3], v[178:181], v[60:63]
	v_mfma_f32_16x16x32_bf16 v[56:59], v[8:11], v[182:185], v[24:27]
	v_mfma_f32_16x16x32_bf16 v[24:27], v[12:15], v[178:181], v[206:209]
	v_mfma_f32_16x16x32_bf16 v[60:63], v[194:197], v[182:185], v[24:27]
	v_mfma_f32_16x16x32_bf16 v[24:27], v[0:3], v[186:189], v[52:55]
	v_mfma_f32_16x16x32_bf16 v[40:43], v[8:11], v[190:193], v[24:27]
	v_mfma_f32_16x16x32_bf16 v[24:27], v[12:15], v[186:189], v[48:51]
	v_mfma_f32_16x16x32_bf16 v[44:47], v[194:197], v[190:193], v[24:27]
	v_mfma_f32_16x16x32_bf16 v[24:27], v[0:3], v[198:201], v[230:233]
	v_mfma_f32_16x16x32_bf16 v[0:3], v[0:3], v[226:229], v[36:39]
	v_mfma_f32_16x16x32_bf16 v[24:27], v[8:11], v[202:205], v[24:27]
	v_mfma_f32_16x16x32_bf16 v[28:31], v[12:15], v[198:201], v[234:237]
	v_mfma_f32_16x16x32_bf16 v[8:11], v[8:11], v[238:241], v[0:3]
	v_mfma_f32_16x16x32_bf16 v[0:3], v[12:15], v[226:229], v[32:35]
	v_mfma_f32_16x16x32_bf16 v[28:31], v[194:197], v[202:205], v[28:31]
	v_mfma_f32_16x16x32_bf16 v[12:15], v[194:197], v[238:241], v[0:3]
	s_setprio 0
	s_setprio 1
	v_mfma_f32_16x16x32_bf16 v[0:3], v[210:213], v[178:181], v[136:139]
	v_mfma_f32_16x16x32_bf16 v[48:51], v[214:217], v[182:185], v[0:3]
	v_mfma_f32_16x16x32_bf16 v[0:3], v[218:221], v[178:181], v[140:143]
	v_mfma_f32_16x16x32_bf16 v[52:55], v[222:225], v[182:185], v[0:3]
	v_mfma_f32_16x16x32_bf16 v[0:3], v[210:213], v[186:189], v[20:23]
	v_mfma_f32_16x16x32_bf16 v[32:35], v[214:217], v[190:193], v[0:3]
	v_mfma_f32_16x16x32_bf16 v[0:3], v[218:221], v[186:189], v[16:19]
	v_mfma_f32_16x16x32_bf16 v[36:39], v[222:225], v[190:193], v[0:3]
	v_mfma_f32_16x16x32_bf16 v[0:3], v[210:213], v[198:201], v[166:169]
	v_mfma_f32_16x16x32_bf16 v[16:19], v[214:217], v[202:205], v[0:3]
	v_mfma_f32_16x16x32_bf16 v[0:3], v[218:221], v[198:201], v[170:173]
	v_mfma_f32_16x16x32_bf16 v[20:23], v[222:225], v[202:205], v[0:3]
	v_mfma_f32_16x16x32_bf16 v[0:3], v[210:213], v[226:229], v[4:7]
	v_mfma_f32_16x16x32_bf16 v[4:7], v[218:221], v[226:229], v[174:177]
	v_mfma_f32_16x16x32_bf16 v[0:3], v[214:217], v[238:241], v[0:3]
	v_mfma_f32_16x16x32_bf16 v[4:7], v[222:225], v[238:241], v[4:7]
	s_setprio 0
	s_barrier
	s_and_saveexec_b64 s[14:15], s[4:5]
	s_cbranch_execz .LBB0_657
	s_barrier

; #define STA(b, h, half, kt) STAGE(((b) * 2 + (h)) * G_HT * 2, pA, ((size_t)(half) * G_HALF * lda + (size_t)(kt) * G_BK) * 2, lda)
; #define STB(b, h, half, kt) STAGE((4 + (b) * 2 + (h)) * G_HT * 2, pB, ((size_t)(half) * G_HALF * K + (size_t)(kt) * G_BK) * 2, K)
; #define LDA(dst, b, h) for (int m = 0; m < 4; ++m) for (int k = 0; k < 2; ++k) \
;     dst[m][k] = *reinterpret_cast<const bf16x8*>(aRd + (((b) * 2 + (h)) * G_HT * 2 + m * 2048 + k * 1024))
; #define LDB(dst, b, h) for (int n = 0; n < 2; ++n) for (int k = 0; k < 2; ++k) \
;     dst[n][k] = *reinterpret_cast<const bf16x8*>(bRd + (((b) * 2 + (h)) * G_HT * 2 + n * 2048 + k * 1024))
; #define MMA(ai, bj, At, Bx) do { __builtin_amdgcn_s_setprio(1); \
;     for (int m = 0; m < 4; ++m) for (int n = 0; n < 2; ++n) for (int k = 0; k < 2; ++k) \
;       acc[ai][bj][m][n] = __builtin_amdgcn_mfma_f32_16x16x32_bf16(Bx[n][k], At[m][k], acc[ai][bj][m][n], 0, 0, 0);     \
;     __builtin_amdgcn_s_setprio(0); } while (0)
; #define WAIT_V(n) asm volatile("s_waitcnt vmcnt(" #n ")" ::: "memory")
; #define WAIT_L(n) asm volatile("s_waitcnt lgkmcnt(" #n ")" ::: "memory")
; #define BAR __builtin_amdgcn_s_barrier()
; #define SCHED __builtin_amdgcn_sched_barrier(0)
; template <int EPI>
; __device__ __forceinline__ void gemm_tile(const bf16* __restrict__ A, int lda, const bf16* __restrict__ Bt, int K,
;                                           int brow, int bcol, const EpiArgs& ea, char* shmc, bool has_next, int nbrow, int nbcol, bool first_tile) {
;     ...
;   for (int t = 0; t < nt - 2; t += 2) {
;     LDB(B0, 0, 0); SCHED; LDA(At, 0, 0); STA(1, 1, 1, t + 1);
;     WAIT_L(8); BAR; WAIT_L(0); MMA(0, 0, At, B0); BAR; SCHED;
;     LDB(B1, 0, 1); STB(0, 0, 0, t + 2);
;     BAR; WAIT_L(0); MMA(0, 1, At, B1); BAR;
;     LDA(At, 0, 1); STA(0, 0, 0, t + 2);
;     BAR; WAIT_L(0); MMA(1, 0, At, B0); BAR; SCHED;
;     STB(0, 1, 1, t + 2);
;     WAIT_V(6); BAR; MMA(1, 1, At, B1); BAR;
.LBB0_727:
	ds_read_b128 v[136:139], v141
	ds_read_b128 v[162:165], v142
	ds_read_b128 v[166:169], v143
	ds_read_b128 v[170:173], v144
	s_add_u32 s52, s20, 0xffffff00
	s_addc_u32 s53, s21, -1
	s_mov_b32 m0, s50
	ds_read_b128 v[174:177], v160
	ds_read_b128 v[178:181], v160 offset:1024
	ds_read_b128 v[182:185], v160 offset:2048
	ds_read_b128 v[186:189], v160 offset:3072
	ds_read_b128 v[190:193], v160 offset:4096
	ds_read_b128 v[194:197], v160 offset:5120
	ds_read_b128 v[198:201], v160 offset:6144
	ds_read_b128 v[202:205], v160 offset:7168
	v_lshl_add_u64 v[206:207], v[132:133], 0, s[52:53]
	global_load_lds_dwordx4 v[206:207], off
	s_mov_b32 m0, s34
	v_lshl_add_u64 v[206:207], v[206:207], 0, s[10:11]
	global_load_lds_dwordx4 v[206:207], off
	s_waitcnt lgkmcnt(8)
	s_barrier
	s_waitcnt lgkmcnt(0)
	s_setprio 1
	v_mfma_f32_16x16x32_bf16 v[124:127], v[136:139], v[174:177], v[124:127]
	v_mfma_f32_16x16x32_bf16 v[120:123], v[166:169], v[174:177], v[120:123]
	v_mfma_f32_16x16x32_bf16 v[116:119], v[136:139], v[182:185], v[116:119]
	v_mfma_f32_16x16x32_bf16 v[112:115], v[166:169], v[182:185], v[112:115]
	v_mfma_f32_16x16x32_bf16 v[108:111], v[136:139], v[190:193], v[108:111]
	v_mfma_f32_16x16x32_bf16 v[104:107], v[166:169], v[190:193], v[104:107]
	v_mfma_f32_16x16x32_bf16 v[100:103], v[136:139], v[198:201], v[100:103]
	v_mfma_f32_16x16x32_bf16 v[96:99], v[166:169], v[198:201], v[96:99]
	v_mfma_f32_16x16x32_bf16 v[124:127], v[162:165], v[178:181], v[124:127]
	v_mfma_f32_16x16x32_bf16 v[120:123], v[170:173], v[178:181], v[120:123]
	v_mfma_f32_16x16x32_bf16 v[116:119], v[162:165], v[186:189], v[116:119]
	v_mfma_f32_16x16x32_bf16 v[112:115], v[170:173], v[186:189], v[112:115]
	v_mfma_f32_16x16x32_bf16 v[108:111], v[162:165], v[194:197], v[108:111]
	v_mfma_f32_16x16x32_bf16 v[104:107], v[170:173], v[194:197], v[104:107]
	v_mfma_f32_16x16x32_bf16 v[100:103], v[162:165], v[202:205], v[100:103]
	v_mfma_f32_16x16x32_bf16 v[96:99], v[170:173], v[202:205], v[96:99]
	s_setprio 0
	s_barrier
	s_add_u32 s52, s20, 0xffefff80
	s_addc_u32 s53, s21, -1
	s_mov_b64 s[54:55], s[52:53]
	s_mov_b32 m0, s41
	ds_read_b128 v[206:209], v145
	ds_read_b128 v[210:213], v146
	ds_read_b128 v[214:217], v147
	ds_read_b128 v[218:221], v148
	v_lshl_add_u64 v[222:223], v[134:135], 0, s[54:55]
	global_load_lds_dwordx4 v[222:223], off
	s_mov_b32 m0, s42
	v_lshl_add_u64 v[222:223], v[222:223], 0, s[10:11]
	global_load_lds_dwordx4 v[222:223], off
	s_barrier
	s_waitcnt lgkmcnt(0)
	s_setprio 1
	v_mfma_f32_16x16x32_bf16 v[92:95], v[206:209], v[174:177], v[92:95]
	v_mfma_f32_16x16x32_bf16 v[88:91], v[214:217], v[174:177], v[88:91]
	v_mfma_f32_16x16x32_bf16 v[84:87], v[206:209], v[182:185], v[84:87]
	v_mfma_f32_16x16x32_bf16 v[80:83], v[214:217], v[182:185], v[80:83]
	v_mfma_f32_16x16x32_bf16 v[76:79], v[206:209], v[190:193], v[76:79]
	v_mfma_f32_16x16x32_bf16 v[72:75], v[214:217], v[190:193], v[72:75]
	v_mfma_f32_16x16x32_bf16 v[68:71], v[206:209], v[198:201], v[68:71]
	v_mfma_f32_16x16x32_bf16 v[64:67], v[214:217], v[198:201], v[64:67]
	v_mfma_f32_16x16x32_bf16 v[92:95], v[210:213], v[178:181], v[92:95]
	v_mfma_f32_16x16x32_bf16 v[88:91], v[218:221], v[178:181], v[88:91]
	v_mfma_f32_16x16x32_bf16 v[84:87], v[210:213], v[186:189], v[84:87]
	v_mfma_f32_16x16x32_bf16 v[80:83], v[218:221], v[186:189], v[80:83]
	v_mfma_f32_16x16x32_bf16 v[76:79], v[210:213], v[194:197], v[76:79]
	v_mfma_f32_16x16x32_bf16 v[72:75], v[218:221], v[194:197], v[72:75]
	v_mfma_f32_16x16x32_bf16 v[68:71], v[210:213], v[202:205], v[68:71]
	v_mfma_f32_16x16x32_bf16 v[64:67], v[218:221], v[202:205], v[64:67]
	s_setprio 0
	s_mov_b32 m0, s1
	s_barrier
	ds_read_b128 v[174:177], v160 offset:16384
	ds_read_b128 v[178:181], v160 offset:17408
	ds_read_b128 v[182:185], v160 offset:18432
	ds_read_b128 v[186:189], v160 offset:19456
	ds_read_b128 v[190:193], v160 offset:20480
	ds_read_b128 v[194:197], v160 offset:21504
	ds_read_b128 v[198:201], v160 offset:22528
	ds_read_b128 v[202:205], v160 offset:23552
	v_lshl_add_u64 v[222:223], v[132:133], 0, s[52:53]
	global_load_lds_dwordx4 v[222:223], off
	s_add_i32 m0, s1, 0x2000
	v_lshl_add_u64 v[222:223], v[222:223], 0, s[10:11]
	global_load_lds_dwordx4 v[222:223], off
	s_barrier
	s_waitcnt lgkmcnt(0)
	s_setprio 1
	v_mfma_f32_16x16x32_bf16 v[60:63], v[136:139], v[174:177], v[60:63]
	v_mfma_f32_16x16x32_bf16 v[56:59], v[166:169], v[174:177], v[56:59]
	v_mfma_f32_16x16x32_bf16 v[52:55], v[136:139], v[182:185], v[52:55]
	v_mfma_f32_16x16x32_bf16 v[48:51], v[166:169], v[182:185], v[48:51]
	v_mfma_f32_16x16x32_bf16 v[44:47], v[136:139], v[190:193], v[44:47]
	v_mfma_f32_16x16x32_bf16 v[40:43], v[166:169], v[190:193], v[40:43]
	v_mfma_f32_16x16x32_bf16 v[36:39], v[136:139], v[198:201], v[36:39]
	v_mfma_f32_16x16x32_bf16 v[32:35], v[166:169], v[198:201], v[32:35]
	v_mfma_f32_16x16x32_bf16 v[60:63], v[162:165], v[178:181], v[60:63]
	v_mfma_f32_16x16x32_bf16 v[56:59], v[170:173], v[178:181], v[56:59]
	v_mfma_f32_16x16x32_bf16 v[52:55], v[162:165], v[186:189], v[52:55]
	v_mfma_f32_16x16x32_bf16 v[48:51], v[170:173], v[186:189], v[48:51]
	v_mfma_f32_16x16x32_bf16 v[44:47], v[162:165], v[194:197], v[44:47]
	v_mfma_f32_16x16x32_bf16 v[40:43], v[170:173], v[194:197], v[40:43]
	v_mfma_f32_16x16x32_bf16 v[36:39], v[162:165], v[202:205], v[36:39]
	v_mfma_f32_16x16x32_bf16 v[32:35], v[170:173], v[202:205], v[32:35]
	s_setprio 0
	s_barrier
	s_add_u32 s52, s20, 0xffffff80
	s_addc_u32 s53, s21, -1
	s_mov_b64 s[54:55], s[52:53]
	s_mov_b32 m0, s43
	v_lshl_add_u64 v[136:137], v[134:135], 0, s[54:55]
	global_load_lds_dwordx4 v[136:137], off
	s_mov_b32 m0, s48
	v_lshl_add_u64 v[136:137], v[136:137], 0, s[10:11]
	global_load_lds_dwordx4 v[136:137], off
	s_waitcnt vmcnt(6)
	s_barrier
; #define STA(b, h, half, kt) STAGE(((b) * 2 + (h)) * G_HT * 2, pA, ((size_t)(half) * G_HALF * lda + (size_t)(kt) * G_BK) * 2, lda)
; #define STB(b, h, half, kt) STAGE((4 + (b) * 2 + (h)) * G_HT * 2, pB, ((size_t)(half) * G_HALF * K + (size_t)(kt) * G_BK) * 2, K)
; #define LDA(dst, b, h) for (int m = 0; m < 4; ++m) for (int k = 0; k < 2; ++k) \
;     dst[m][k] = *reinterpret_cast<const bf16x8*>(aRd + (((b) * 2 + (h)) * G_HT * 2 + m * 2048 + k * 1024))
; #define LDB(dst, b, h) for (int n = 0; n < 2; ++n) for (int k = 0; k < 2; ++k) \
;     dst[n][k] = *reinterpret_cast<const bf16x8*>(bRd + (((b) * 2 + (h)) * G_HT * 2 + n * 2048 + k * 1024))
; #define MMA(ai, bj, At, Bx) do { __builtin_amdgcn_s_setprio(1); \
;     for (int m = 0; m < 4; ++m) for (int n = 0; n < 2; ++n) for (int k = 0; k < 2; ++k) \
;       acc[ai][bj][m][n] = __builtin_amdgcn_mfma_f32_16x16x32_bf16(Bx[n][k], At[m][k], acc[ai][bj][m][n], 0, 0, 0);     \
;     __builtin_amdgcn_s_setprio(0); } while (0)
; #define WAIT_V(n) asm volatile("s_waitcnt vmcnt(" #n ")" ::: "memory")
; #define WAIT_L(n) asm volatile("s_waitcnt lgkmcnt(" #n ")" ::: "memory")
; #define BAR __builtin_amdgcn_s_barrier()
; #define SCHED __builtin_amdgcn_sched_barrier(0)
; template <int EPI>
; __device__ __forceinline__ void gemm_tile(const bf16* __restrict__ A, int lda, const bf16* __restrict__ Bt, int K,
;                                           int brow, int bcol, const EpiArgs& ea, char* shmc, bool has_next, int nbrow, int nbcol, bool first_tile) {
;     ...
;     WAIT_V(6); BAR; MMA(1, 1, At, B1); BAR;
;     LDB(B0, 1, 0); SCHED; LDA(At, 1, 0); STA(0, 1, 1, t + 2);
;     WAIT_L(8); BAR; WAIT_L(0); MMA(0, 0, At, B0); BAR; SCHED;
;     LDB(B1, 1, 1); STB(1, 0, 0, t + 3);
;     BAR; WAIT_L(0); MMA(0, 1, At, B1); BAR;
;     LDA(At, 1, 1); STA(1, 0, 0, t + 3);
;     BAR; WAIT_L(0); MMA(1, 0, At, B0); BAR; SCHED;
	s_setprio 1
	v_mfma_f32_16x16x32_bf16 v[28:31], v[206:209], v[174:177], v[28:31]
	v_mfma_f32_16x16x32_bf16 v[24:27], v[214:217], v[174:177], v[24:27]
	v_mfma_f32_16x16x32_bf16 v[20:23], v[206:209], v[182:185], v[20:23]
	v_mfma_f32_16x16x32_bf16 v[16:19], v[214:217], v[182:185], v[16:19]
	v_mfma_f32_16x16x32_bf16 v[12:15], v[206:209], v[190:193], v[12:15]
	v_mfma_f32_16x16x32_bf16 v[8:11], v[214:217], v[190:193], v[8:11]
	v_mfma_f32_16x16x32_bf16 v[4:7], v[206:209], v[198:201], v[4:7]
	v_mfma_f32_16x16x32_bf16 v[0:3], v[214:217], v[198:201], v[0:3]
	v_mfma_f32_16x16x32_bf16 v[28:31], v[210:213], v[178:181], v[28:31]
	v_mfma_f32_16x16x32_bf16 v[24:27], v[218:221], v[178:181], v[24:27]
	v_mfma_f32_16x16x32_bf16 v[20:23], v[210:213], v[186:189], v[20:23]
	v_mfma_f32_16x16x32_bf16 v[16:19], v[218:221], v[186:189], v[16:19]
	v_mfma_f32_16x16x32_bf16 v[12:15], v[210:213], v[194:197], v[12:15]
	v_mfma_f32_16x16x32_bf16 v[8:11], v[218:221], v[194:197], v[8:11]
	v_mfma_f32_16x16x32_bf16 v[4:7], v[210:213], v[202:205], v[4:7]
	v_mfma_f32_16x16x32_bf16 v[0:3], v[218:221], v[202:205], v[0:3]
	s_setprio 0
	s_barrier
	ds_read_b128 v[136:139], v149
	ds_read_b128 v[162:165], v150
	ds_read_b128 v[166:169], v151
	ds_read_b128 v[170:173], v152
	ds_read_b128 v[174:177], v160 offset:32768
	ds_read_b128 v[178:181], v160 offset:33792
	ds_read_b128 v[182:185], v160 offset:34816
	ds_read_b128 v[186:189], v160 offset:35840
	ds_read_b128 v[190:193], v160 offset:36864
	ds_read_b128 v[194:197], v160 offset:37888
	ds_read_b128 v[198:201], v160 offset:38912
	ds_read_b128 v[202:205], v160 offset:39936
	s_add_i32 m0, s1, 0x4000
	v_lshl_add_u64 v[206:207], v[132:133], 0, s[52:53]
	global_load_lds_dwordx4 v[206:207], off
	s_add_i32 m0, s1, 0x6000
	v_lshl_add_u64 v[206:207], v[206:207], 0, s[10:11]
	global_load_lds_dwordx4 v[206:207], off
	s_waitcnt lgkmcnt(8)
	s_barrier
	s_waitcnt lgkmcnt(0)
	s_setprio 1
	v_mfma_f32_16x16x32_bf16 v[124:127], v[136:139], v[174:177], v[124:127]
	v_mfma_f32_16x16x32_bf16 v[120:123], v[166:169], v[174:177], v[120:123]
	v_mfma_f32_16x16x32_bf16 v[116:119], v[136:139], v[182:185], v[116:119]
	v_mfma_f32_16x16x32_bf16 v[112:115], v[166:169], v[182:185], v[112:115]
	v_mfma_f32_16x16x32_bf16 v[108:111], v[136:139], v[190:193], v[108:111]
	v_mfma_f32_16x16x32_bf16 v[104:107], v[166:169], v[190:193], v[104:107]
	v_mfma_f32_16x16x32_bf16 v[100:103], v[136:139], v[198:201], v[100:103]
	v_mfma_f32_16x16x32_bf16 v[96:99], v[166:169], v[198:201], v[96:99]
	v_mfma_f32_16x16x32_bf16 v[124:127], v[162:165], v[178:181], v[124:127]
	v_mfma_f32_16x16x32_bf16 v[120:123], v[170:173], v[178:181], v[120:123]
	v_mfma_f32_16x16x32_bf16 v[116:119], v[162:165], v[186:189], v[116:119]
	v_mfma_f32_16x16x32_bf16 v[112:115], v[170:173], v[186:189], v[112:115]
	v_mfma_f32_16x16x32_bf16 v[108:111], v[162:165], v[194:197], v[108:111]
	v_mfma_f32_16x16x32_bf16 v[104:107], v[170:173], v[194:197], v[104:107]
	v_mfma_f32_16x16x32_bf16 v[100:103], v[162:165], v[202:205], v[100:103]
	v_mfma_f32_16x16x32_bf16 v[96:99], v[170:173], v[202:205], v[96:99]
	s_setprio 0
	s_barrier
	s_add_u32 s52, s20, 0xfff00000
	s_addc_u32 s53, s21, -1
	s_mov_b64 s[54:55], s[52:53]
	s_mov_b32 m0, s7
	ds_read_b128 v[206:209], v153
	ds_read_b128 v[210:213], v154
	ds_read_b128 v[214:217], v155
	ds_read_b128 v[218:221], v156
	v_lshl_add_u64 v[222:223], v[134:135], 0, s[54:55]
	global_load_lds_dwordx4 v[222:223], off
	s_mov_b32 m0, s29
	v_lshl_add_u64 v[222:223], v[222:223], 0, s[10:11]
	global_load_lds_dwordx4 v[222:223], off
	s_barrier
	s_waitcnt lgkmcnt(0)
	s_setprio 1
	v_mfma_f32_16x16x32_bf16 v[92:95], v[206:209], v[174:177], v[92:95]
	v_mfma_f32_16x16x32_bf16 v[88:91], v[214:217], v[174:177], v[88:91]
	v_mfma_f32_16x16x32_bf16 v[84:87], v[206:209], v[182:185], v[84:87]
	v_mfma_f32_16x16x32_bf16 v[80:83], v[214:217], v[182:185], v[80:83]
	v_mfma_f32_16x16x32_bf16 v[76:79], v[206:209], v[190:193], v[76:79]
	v_mfma_f32_16x16x32_bf16 v[72:75], v[214:217], v[190:193], v[72:75]
	v_mfma_f32_16x16x32_bf16 v[68:71], v[206:209], v[198:201], v[68:71]
	v_mfma_f32_16x16x32_bf16 v[64:67], v[214:217], v[198:201], v[64:67]
	v_mfma_f32_16x16x32_bf16 v[92:95], v[210:213], v[178:181], v[92:95]
	v_mfma_f32_16x16x32_bf16 v[88:91], v[218:221], v[178:181], v[88:91]
	v_mfma_f32_16x16x32_bf16 v[84:87], v[210:213], v[186:189], v[84:87]
	v_mfma_f32_16x16x32_bf16 v[80:83], v[218:221], v[186:189], v[80:83]
	v_mfma_f32_16x16x32_bf16 v[76:79], v[210:213], v[194:197], v[76:79]
	v_mfma_f32_16x16x32_bf16 v[72:75], v[218:221], v[194:197], v[72:75]
	v_mfma_f32_16x16x32_bf16 v[68:71], v[210:213], v[202:205], v[68:71]
	v_mfma_f32_16x16x32_bf16 v[64:67], v[218:221], v[202:205], v[64:67]
	s_setprio 0
	s_mov_b32 m0, s30
	s_barrier
	ds_read_b128 v[174:177], v160 offset:49152
	ds_read_b128 v[178:181], v160 offset:50176
	ds_read_b128 v[182:185], v160 offset:51200
	ds_read_b128 v[186:189], v160 offset:52224
	ds_read_b128 v[190:193], v160 offset:53248
	ds_read_b128 v[194:197], v160 offset:54272
	ds_read_b128 v[198:201], v160 offset:55296
	ds_read_b128 v[202:205], v160 offset:56320
	v_lshl_add_u64 v[222:223], v[132:133], 0, s[52:53]
	global_load_lds_dwordx4 v[222:223], off
	s_mov_b32 m0, s31
	v_lshl_add_u64 v[222:223], v[222:223], 0, s[10:11]
	global_load_lds_dwordx4 v[222:223], off
	s_barrier
; #define STA(b, h, half, kt) STAGE(((b) * 2 + (h)) * G_HT * 2, pA, ((size_t)(half) * G_HALF * lda + (size_t)(kt) * G_BK) * 2, lda)
; #define STB(b, h, half, kt) STAGE((4 + (b) * 2 + (h)) * G_HT * 2, pB, ((size_t)(half) * G_HALF * K + (size_t)(kt) * G_BK) * 2, K)
; #define LDA(dst, b, h) for (int m = 0; m < 4; ++m) for (int k = 0; k < 2; ++k) \
;     dst[m][k] = *reinterpret_cast<const bf16x8*>(aRd + (((b) * 2 + (h)) * G_HT * 2 + m * 2048 + k * 1024))
; #define LDB(dst, b, h) for (int n = 0; n < 2; ++n) for (int k = 0; k < 2; ++k) \
;     dst[n][k] = *reinterpret_cast<const bf16x8*>(bRd + (((b) * 2 + (h)) * G_HT * 2 + n * 2048 + k * 1024))
; #define MMA(ai, bj, At, Bx) do { __builtin_amdgcn_s_setprio(1); \
;     for (int m = 0; m < 4; ++m) for (int n = 0; n < 2; ++n) for (int k = 0; k < 2; ++k) \
;       acc[ai][bj][m][n] = __builtin_amdgcn_mfma_f32_16x16x32_bf16(Bx[n][k], At[m][k], acc[ai][bj][m][n], 0, 0, 0);     \
;     __builtin_amdgcn_s_setprio(0); } while (0)
; #define WAIT_V(n) asm volatile("s_waitcnt vmcnt(" #n ")" ::: "memory")
; #define WAIT_L(n) asm volatile("s_waitcnt lgkmcnt(" #n ")" ::: "memory")
; #define BAR __builtin_amdgcn_s_barrier()
; #define SCHED __builtin_amdgcn_sched_barrier(0)
; template <int EPI>
; __device__ __forceinline__ void gemm_tile(const bf16* __restrict__ A, int lda, const bf16* __restrict__ Bt, int K,
;                                           int brow, int bcol, const EpiArgs& ea, char* shmc, bool has_next, int nbrow, int nbcol, bool first_tile) {
;     ...
;     BAR; WAIT_L(0); MMA(1, 0, At, B0); BAR; SCHED;
;     STB(1, 1, 1, t + 3);
;     WAIT_V(6); BAR; MMA(1, 1, At, B1); BAR;
;   }
;   { LDB(B0, 0, 0); LDA(At, 0, 0); STA(1, 1, 1, nt - 1);
;     BAR; WAIT_L(0); MMA(0, 0, At, B0); BAR;
;     LDB(B1, 0, 1); BAR; WAIT_L(0); MMA(0, 1, At, B1); BAR;
;     LDA(At, 0, 1); WAIT_V(4); BAR; WAIT_L(0); MMA(1, 0, At, B0); MMA(1, 1, At, B1); BAR; }
	s_waitcnt lgkmcnt(0)
	s_setprio 1
	v_mfma_f32_16x16x32_bf16 v[60:63], v[136:139], v[174:177], v[60:63]
	v_mfma_f32_16x16x32_bf16 v[56:59], v[166:169], v[174:177], v[56:59]
	v_mfma_f32_16x16x32_bf16 v[52:55], v[136:139], v[182:185], v[52:55]
	v_mfma_f32_16x16x32_bf16 v[48:51], v[166:169], v[182:185], v[48:51]
	v_mfma_f32_16x16x32_bf16 v[44:47], v[136:139], v[190:193], v[44:47]
	v_mfma_f32_16x16x32_bf16 v[40:43], v[166:169], v[190:193], v[40:43]
	v_mfma_f32_16x16x32_bf16 v[36:39], v[136:139], v[198:201], v[36:39]
	v_mfma_f32_16x16x32_bf16 v[32:35], v[166:169], v[198:201], v[32:35]
	v_mfma_f32_16x16x32_bf16 v[60:63], v[162:165], v[178:181], v[60:63]
	v_mfma_f32_16x16x32_bf16 v[56:59], v[170:173], v[178:181], v[56:59]
	v_mfma_f32_16x16x32_bf16 v[52:55], v[162:165], v[186:189], v[52:55]
	v_mfma_f32_16x16x32_bf16 v[48:51], v[170:173], v[186:189], v[48:51]
	v_mfma_f32_16x16x32_bf16 v[44:47], v[162:165], v[194:197], v[44:47]
	v_mfma_f32_16x16x32_bf16 v[40:43], v[170:173], v[194:197], v[40:43]
	v_mfma_f32_16x16x32_bf16 v[36:39], v[162:165], v[202:205], v[36:39]
	v_mfma_f32_16x16x32_bf16 v[32:35], v[170:173], v[202:205], v[32:35]
	s_setprio 0
	s_barrier
	s_mov_b64 s[52:53], s[20:21]
	s_mov_b32 m0, s35
	v_lshl_add_u64 v[136:137], v[134:135], 0, s[52:53]
	global_load_lds_dwordx4 v[136:137], off
	s_mov_b32 m0, s40
	v_lshl_add_u64 v[136:137], v[136:137], 0, s[10:11]
	global_load_lds_dwordx4 v[136:137], off
	s_waitcnt vmcnt(6)
	s_barrier
	s_setprio 1
	v_mfma_f32_16x16x32_bf16 v[28:31], v[206:209], v[174:177], v[28:31]
	v_mfma_f32_16x16x32_bf16 v[24:27], v[214:217], v[174:177], v[24:27]
	v_mfma_f32_16x16x32_bf16 v[20:23], v[206:209], v[182:185], v[20:23]
	v_mfma_f32_16x16x32_bf16 v[16:19], v[214:217], v[182:185], v[16:19]
	v_mfma_f32_16x16x32_bf16 v[12:15], v[206:209], v[190:193], v[12:15]
	v_mfma_f32_16x16x32_bf16 v[8:11], v[214:217], v[190:193], v[8:11]
	v_mfma_f32_16x16x32_bf16 v[4:7], v[206:209], v[198:201], v[4:7]
	v_mfma_f32_16x16x32_bf16 v[0:3], v[214:217], v[198:201], v[0:3]
	v_mfma_f32_16x16x32_bf16 v[28:31], v[210:213], v[178:181], v[28:31]
	v_mfma_f32_16x16x32_bf16 v[24:27], v[218:221], v[178:181], v[24:27]
	v_mfma_f32_16x16x32_bf16 v[20:23], v[210:213], v[186:189], v[20:23]
	v_mfma_f32_16x16x32_bf16 v[16:19], v[218:221], v[186:189], v[16:19]
	v_mfma_f32_16x16x32_bf16 v[12:15], v[210:213], v[194:197], v[12:15]
	v_mfma_f32_16x16x32_bf16 v[8:11], v[218:221], v[194:197], v[8:11]
	v_mfma_f32_16x16x32_bf16 v[4:7], v[210:213], v[202:205], v[4:7]
	v_mfma_f32_16x16x32_bf16 v[0:3], v[218:221], v[202:205], v[0:3]
	s_setprio 0
	s_add_i32 s49, s49, 2
	s_add_u32 s20, s20, 0x100
	s_addc_u32 s21, s21, 0
	s_cmp_lt_u32 s49, 60
	s_barrier
	s_cbranch_scc1 .LBB0_727
	s_mov_b64 s[20:21], 0x101f80
	s_mov_b32 m0, s50
	ds_read_b128 v[134:137], v141
	ds_read_b128 v[162:165], v142
	ds_read_b128 v[166:169], v143
	ds_read_b128 v[170:173], v144
	ds_read_b128 v[174:177], v160
	ds_read_b128 v[178:181], v160 offset:1024
	ds_read_b128 v[182:185], v160 offset:2048
	ds_read_b128 v[186:189], v160 offset:3072
	ds_read_b128 v[190:193], v160 offset:4096
	ds_read_b128 v[194:197], v160 offset:5120
	ds_read_b128 v[198:201], v160 offset:6144
	ds_read_b128 v[202:205], v160 offset:7168
	s_nop 0
	v_lshl_add_u64 v[132:133], v[132:133], 0, s[20:21]
	global_load_lds_dwordx4 v[132:133], off
	v_lshl_add_u64 v[132:133], v[132:133], 0, s[10:11]
	s_mov_b32 m0, s34
	s_nop 0
	global_load_lds_dwordx4 v[132:133], off
	s_barrier
	s_waitcnt lgkmcnt(0)
	s_setprio 1
	s_waitcnt lgkmcnt(0)
	v_mfma_f32_16x16x32_bf16 v[124:127], v[134:137], v[174:177], v[124:127]
	v_mfma_f32_16x16x32_bf16 v[120:123], v[166:169], v[174:177], v[120:123]
	v_mfma_f32_16x16x32_bf16 v[108:111], v[134:137], v[190:193], v[108:111]
	v_mfma_f32_16x16x32_bf16 v[104:107], v[166:169], v[190:193], v[104:107]
	v_mfma_f32_16x16x32_bf16 v[124:127], v[162:165], v[178:181], v[124:127]
	v_mfma_f32_16x16x32_bf16 v[120:123], v[170:173], v[178:181], v[120:123]
	v_mfma_f32_16x16x32_bf16 v[116:119], v[134:137], v[182:185], v[116:119]
	v_mfma_f32_16x16x32_bf16 v[112:115], v[166:169], v[182:185], v[112:115]
	v_mfma_f32_16x16x32_bf16 v[108:111], v[162:165], v[194:197], v[108:111]
	v_mfma_f32_16x16x32_bf16 v[104:107], v[170:173], v[194:197], v[104:107]
	v_mfma_f32_16x16x32_bf16 v[100:103], v[134:137], v[198:201], v[100:103]
	v_mfma_f32_16x16x32_bf16 v[96:99], v[166:169], v[198:201], v[96:99]
	v_mfma_f32_16x16x32_bf16 v[206:209], v[162:165], v[186:189], v[116:119]
	v_mfma_f32_16x16x32_bf16 v[210:213], v[170:173], v[186:189], v[112:115]
	v_mfma_f32_16x16x32_bf16 v[214:217], v[162:165], v[202:205], v[100:103]
	v_mfma_f32_16x16x32_bf16 v[218:221], v[170:173], v[202:205], v[96:99]
	s_setprio 0
	s_barrier
	s_nop 1
	ds_read_b128 v[96:99], v145
	ds_read_b128 v[100:103], v146
	ds_read_b128 v[112:115], v147
	ds_read_b128 v[116:119], v148
	s_barrier
	s_waitcnt lgkmcnt(0)
	s_setprio 1
	s_waitcnt lgkmcnt(0)
	v_mfma_f32_16x16x32_bf16 v[92:95], v[96:99], v[174:177], v[92:95]
	v_mfma_f32_16x16x32_bf16 v[88:91], v[112:115], v[174:177], v[88:91]
	v_mfma_f32_16x16x32_bf16 v[76:79], v[96:99], v[190:193], v[76:79]
	v_mfma_f32_16x16x32_bf16 v[72:75], v[112:115], v[190:193], v[72:75]
	v_mfma_f32_16x16x32_bf16 v[92:95], v[100:103], v[178:181], v[92:95]
	v_mfma_f32_16x16x32_bf16 v[88:91], v[116:119], v[178:181], v[88:91]
	v_mfma_f32_16x16x32_bf16 v[84:87], v[96:99], v[182:185], v[84:87]
	v_mfma_f32_16x16x32_bf16 v[80:83], v[112:115], v[182:185], v[80:83]
	v_mfma_f32_16x16x32_bf16 v[76:79], v[100:103], v[194:197], v[76:79]
	v_mfma_f32_16x16x32_bf16 v[72:75], v[116:119], v[194:197], v[72:75]
	v_mfma_f32_16x16x32_bf16 v[68:71], v[96:99], v[198:201], v[68:71]
	v_mfma_f32_16x16x32_bf16 v[64:67], v[112:115], v[198:201], v[64:67]
	v_mfma_f32_16x16x32_bf16 v[174:177], v[100:103], v[186:189], v[84:87]
	v_mfma_f32_16x16x32_bf16 v[178:181], v[116:119], v[186:189], v[80:83]
	v_mfma_f32_16x16x32_bf16 v[182:185], v[100:103], v[202:205], v[68:71]
	v_mfma_f32_16x16x32_bf16 v[186:189], v[116:119], v[202:205], v[64:67]
	s_setprio 0
	s_barrier
; #define LDA(dst, b, h) for (int m = 0; m < 4; ++m) for (int k = 0; k < 2; ++k) \
;     dst[m][k] = *reinterpret_cast<const bf16x8*>(aRd + (((b) * 2 + (h)) * G_HT * 2 + m * 2048 + k * 1024))
; #define LDB(dst, b, h) for (int n = 0; n < 2; ++n) for (int k = 0; k < 2; ++k) \
;     dst[n][k] = *reinterpret_cast<const bf16x8*>(bRd + (((b) * 2 + (h)) * G_HT * 2 + n * 2048 + k * 1024))
; #define MMA(ai, bj, At, Bx) do { __builtin_amdgcn_s_setprio(1); \
;     for (int m = 0; m < 4; ++m) for (int n = 0; n < 2; ++n) for (int k = 0; k < 2; ++k) \
;       acc[ai][bj][m][n] = __builtin_amdgcn_mfma_f32_16x16x32_bf16(Bx[n][k], At[m][k], acc[ai][bj][m][n], 0, 0, 0);     \
;     __builtin_amdgcn_s_setprio(0); } while (0)
; #define WAIT_V(n) asm volatile("s_waitcnt vmcnt(" #n ")" ::: "memory")
; #define WAIT_L(n) asm volatile("s_waitcnt lgkmcnt(" #n ")" ::: "memory")
; #define BAR __builtin_amdgcn_s_barrier()
; template <int EPI>
; __device__ __forceinline__ void gemm_tile(const bf16* __restrict__ A, int lda, const bf16* __restrict__ Bt, int K,
;                                           int brow, int bcol, const EpiArgs& ea, char* shmc, bool has_next, int nbrow, int nbcol, bool first_tile) {
;     ...
;     LDA(At, 0, 1); WAIT_V(4); BAR; WAIT_L(0); MMA(1, 0, At, B0); MMA(1, 1, At, B1); BAR; }
;   { LDB(B0, 1, 0); LDA(At, 1, 0); WAIT_V(2); BAR; WAIT_L(0); MMA(0, 0, At, B0); BAR;
;     LDB(B1, 1, 1); WAIT_V(0); BAR; WAIT_L(0); MMA(0, 1, At, B1); BAR;
;     LDA(At, 1, 1); BAR; WAIT_L(0); MMA(1, 0, At, B0); MMA(1, 1, At, B1); BAR; }
	s_nop 1
	ds_read_b128 v[64:67], v160 offset:16384
	ds_read_b128 v[68:71], v160 offset:17408
	ds_read_b128 v[80:83], v160 offset:18432
	ds_read_b128 v[84:87], v160 offset:19456
	ds_read_b128 v[190:193], v160 offset:20480
	ds_read_b128 v[194:197], v160 offset:21504
	ds_read_b128 v[198:201], v160 offset:22528
	ds_read_b128 v[202:205], v160 offset:23552
	s_waitcnt vmcnt(4)
	s_barrier
	s_waitcnt lgkmcnt(0)
	s_setprio 1
	s_waitcnt lgkmcnt(0)
	v_mfma_f32_16x16x32_bf16 v[60:63], v[134:137], v[64:67], v[60:63]
	v_mfma_f32_16x16x32_bf16 v[52:55], v[134:137], v[80:83], v[52:55]
	v_mfma_f32_16x16x32_bf16 v[48:51], v[166:169], v[80:83], v[48:51]
	v_mfma_f32_16x16x32_bf16 v[36:39], v[134:137], v[198:201], v[36:39]
	v_mfma_f32_16x16x32_bf16 v[32:35], v[166:169], v[198:201], v[32:35]
	v_mfma_f32_16x16x32_bf16 v[60:63], v[162:165], v[68:71], v[60:63]
	v_mfma_f32_16x16x32_bf16 v[56:59], v[166:169], v[64:67], v[56:59]
	v_mfma_f32_16x16x32_bf16 v[52:55], v[162:165], v[84:87], v[52:55]
	v_mfma_f32_16x16x32_bf16 v[48:51], v[170:173], v[84:87], v[48:51]
	v_mfma_f32_16x16x32_bf16 v[44:47], v[134:137], v[190:193], v[44:47]
	v_mfma_f32_16x16x32_bf16 v[40:43], v[166:169], v[190:193], v[40:43]
	v_mfma_f32_16x16x32_bf16 v[36:39], v[162:165], v[202:205], v[36:39]
	v_mfma_f32_16x16x32_bf16 v[32:35], v[170:173], v[202:205], v[32:35]
	v_mfma_f32_16x16x32_bf16 v[222:225], v[170:173], v[68:71], v[56:59]
	v_mfma_f32_16x16x32_bf16 v[226:229], v[162:165], v[194:197], v[44:47]
	v_mfma_f32_16x16x32_bf16 v[230:233], v[170:173], v[194:197], v[40:43]
	s_setprio 0
	s_setprio 1
	v_mfma_f32_16x16x32_bf16 v[20:23], v[96:99], v[80:83], v[20:23]
	v_mfma_f32_16x16x32_bf16 v[16:19], v[112:115], v[80:83], v[16:19]
	v_mfma_f32_16x16x32_bf16 v[12:15], v[96:99], v[190:193], v[12:15]
	v_mfma_f32_16x16x32_bf16 v[8:11], v[112:115], v[190:193], v[8:11]
	v_mfma_f32_16x16x32_bf16 v[28:31], v[96:99], v[64:67], v[28:31]
	v_mfma_f32_16x16x32_bf16 v[24:27], v[112:115], v[64:67], v[24:27]
	v_mfma_f32_16x16x32_bf16 v[20:23], v[100:103], v[84:87], v[20:23]
	v_mfma_f32_16x16x32_bf16 v[16:19], v[116:119], v[84:87], v[16:19]
	v_mfma_f32_16x16x32_bf16 v[12:15], v[100:103], v[194:197], v[12:15]
	v_mfma_f32_16x16x32_bf16 v[8:11], v[116:119], v[194:197], v[8:11]
	v_mfma_f32_16x16x32_bf16 v[4:7], v[96:99], v[198:201], v[4:7]
	v_mfma_f32_16x16x32_bf16 v[0:3], v[112:115], v[198:201], v[0:3]
	v_mfma_f32_16x16x32_bf16 v[132:135], v[100:103], v[68:71], v[28:31]
	v_mfma_f32_16x16x32_bf16 v[136:139], v[116:119], v[68:71], v[24:27]
	v_mfma_f32_16x16x32_bf16 v[162:165], v[100:103], v[202:205], v[4:7]
	v_mfma_f32_16x16x32_bf16 v[166:169], v[116:119], v[202:205], v[0:3]
	s_setprio 0
	s_barrier
	s_nop 1
	ds_read_b128 v[0:3], v149
	ds_read_b128 v[4:7], v150
	ds_read_b128 v[170:173], v151
	ds_read_b128 v[190:193], v152
	ds_read_b128 v[24:27], v160 offset:32768
	ds_read_b128 v[28:31], v160 offset:33792
	ds_read_b128 v[40:43], v160 offset:34816
	ds_read_b128 v[44:47], v160 offset:35840
	ds_read_b128 v[56:59], v160 offset:36864
	ds_read_b128 v[194:197], v160 offset:37888
	ds_read_b128 v[198:201], v160 offset:38912
	ds_read_b128 v[202:205], v160 offset:39936
	s_waitcnt vmcnt(2)
	s_barrier
	s_waitcnt lgkmcnt(0)
	s_setprio 1
	s_waitcnt lgkmcnt(0)
	v_mfma_f32_16x16x32_bf16 v[64:67], v[0:3], v[24:27], v[124:127]
	v_mfma_f32_16x16x32_bf16 v[112:115], v[4:7], v[28:31], v[64:67]
	v_mfma_f32_16x16x32_bf16 v[64:67], v[170:173], v[24:27], v[120:123]
	v_mfma_f32_16x16x32_bf16 v[116:119], v[190:193], v[28:31], v[64:67]
	v_mfma_f32_16x16x32_bf16 v[64:67], v[0:3], v[40:43], v[206:209]
	v_mfma_f32_16x16x32_bf16 v[96:99], v[4:7], v[44:47], v[64:67]
	v_mfma_f32_16x16x32_bf16 v[64:67], v[170:173], v[40:43], v[210:213]
	v_mfma_f32_16x16x32_bf16 v[100:103], v[190:193], v[44:47], v[64:67]
	v_mfma_f32_16x16x32_bf16 v[64:67], v[0:3], v[56:59], v[108:111]
	v_mfma_f32_16x16x32_bf16 v[80:83], v[4:7], v[194:197], v[64:67]
	v_mfma_f32_16x16x32_bf16 v[64:67], v[170:173], v[56:59], v[104:107]
	v_mfma_f32_16x16x32_bf16 v[84:87], v[190:193], v[194:197], v[64:67]
	v_mfma_f32_16x16x32_bf16 v[64:67], v[0:3], v[198:201], v[214:217]
	v_mfma_f32_16x16x32_bf16 v[68:71], v[170:173], v[198:201], v[218:221]
	v_mfma_f32_16x16x32_bf16 v[64:67], v[4:7], v[202:205], v[64:67]
	v_mfma_f32_16x16x32_bf16 v[68:71], v[190:193], v[202:205], v[68:71]
	s_setprio 0
	s_barrier
; #define LDA(dst, b, h) for (int m = 0; m < 4; ++m) for (int k = 0; k < 2; ++k) \
;     dst[m][k] = *reinterpret_cast<const bf16x8*>(aRd + (((b) * 2 + (h)) * G_HT * 2 + m * 2048 + k * 1024))
; #define LDB(dst, b, h) for (int n = 0; n < 2; ++n) for (int k = 0; k < 2; ++k) \
;     dst[n][k] = *reinterpret_cast<const bf16x8*>(bRd + (((b) * 2 + (h)) * G_HT * 2 + n * 2048 + k * 1024))
; #define MMA(ai, bj, At, Bx) do { __builtin_amdgcn_s_setprio(1); \
;     for (int m = 0; m < 4; ++m) for (int n = 0; n < 2; ++n) for (int k = 0; k < 2; ++k) \
;       acc[ai][bj][m][n] = __builtin_amdgcn_mfma_f32_16x16x32_bf16(Bx[n][k], At[m][k], acc[ai][bj][m][n], 0, 0, 0);     \
;     __builtin_amdgcn_s_setprio(0); } while (0)
; #define WAIT_V(n) asm volatile("s_waitcnt vmcnt(" #n ")" ::: "memory")
; #define WAIT_L(n) asm volatile("s_waitcnt lgkmcnt(" #n ")" ::: "memory")
; #define BAR __builtin_amdgcn_s_barrier()
; template <int EPI>
; __device__ __forceinline__ void gemm_tile(const bf16* __restrict__ A, int lda, const bf16* __restrict__ Bt, int K,
;                                           int brow, int bcol, const EpiArgs& ea, char* shmc, bool has_next, int nbrow, int nbcol, bool first_tile) {
;     ...
;   { LDB(B0, 1, 0); LDA(At, 1, 0); WAIT_V(2); BAR; WAIT_L(0); MMA(0, 0, At, B0); BAR;
;     LDB(B1, 1, 1); WAIT_V(0); BAR; WAIT_L(0); MMA(0, 1, At, B1); BAR;
;     LDA(At, 1, 1); BAR; WAIT_L(0); MMA(1, 0, At, B0); MMA(1, 1, At, B1); BAR; }
;   if (wr == 0) BAR;
;   if (has_next) gemm_prefetch(A, lda, Bt, K, nbrow, nbcol, shmc);
	ds_read_b128 v[206:209], v153
	ds_read_b128 v[210:213], v154
	ds_read_b128 v[214:217], v155
	ds_read_b128 v[218:221], v156
	s_waitcnt vmcnt(0)
	s_barrier
	s_waitcnt lgkmcnt(0)
	s_setprio 1
	s_waitcnt lgkmcnt(0)
	v_mfma_f32_16x16x32_bf16 v[92:95], v[206:209], v[24:27], v[92:95]
	v_mfma_f32_16x16x32_bf16 v[24:27], v[214:217], v[24:27], v[88:91]
	v_mfma_f32_16x16x32_bf16 v[124:127], v[218:221], v[28:31], v[24:27]
	v_mfma_f32_16x16x32_bf16 v[24:27], v[206:209], v[40:43], v[174:177]
	v_mfma_f32_16x16x32_bf16 v[104:107], v[210:213], v[44:47], v[24:27]
	v_mfma_f32_16x16x32_bf16 v[24:27], v[214:217], v[40:43], v[178:181]
	v_mfma_f32_16x16x32_bf16 v[108:111], v[218:221], v[44:47], v[24:27]
	v_mfma_f32_16x16x32_bf16 v[24:27], v[206:209], v[56:59], v[76:79]
	v_mfma_f32_16x16x32_bf16 v[88:91], v[210:213], v[194:197], v[24:27]
	v_mfma_f32_16x16x32_bf16 v[24:27], v[214:217], v[56:59], v[72:75]
	v_mfma_f32_16x16x32_bf16 v[120:123], v[210:213], v[28:31], v[92:95]
	v_mfma_f32_16x16x32_bf16 v[92:95], v[218:221], v[194:197], v[24:27]
	v_mfma_f32_16x16x32_bf16 v[24:27], v[206:209], v[198:201], v[182:185]
	v_mfma_f32_16x16x32_bf16 v[72:75], v[210:213], v[202:205], v[24:27]
	v_mfma_f32_16x16x32_bf16 v[24:27], v[214:217], v[198:201], v[186:189]
	v_mfma_f32_16x16x32_bf16 v[76:79], v[218:221], v[202:205], v[24:27]
	s_setprio 0
	s_barrier
	ds_read_b128 v[174:177], v160 offset:49152
	ds_read_b128 v[178:181], v160 offset:50176
	ds_read_b128 v[182:185], v160 offset:51200
	ds_read_b128 v[186:189], v160 offset:52224
	ds_read_b128 v[194:197], v160 offset:53248
	ds_read_b128 v[198:201], v160 offset:54272
	ds_read_b128 v[202:205], v160 offset:55296
	ds_read_b128 v[234:237], v160 offset:56320
	s_barrier
	s_waitcnt lgkmcnt(0)
	s_setprio 1
	s_waitcnt lgkmcnt(0)
	v_mfma_f32_16x16x32_bf16 v[24:27], v[0:3], v[174:177], v[60:63]
	v_mfma_f32_16x16x32_bf16 v[56:59], v[4:7], v[178:181], v[24:27]
	v_mfma_f32_16x16x32_bf16 v[24:27], v[170:173], v[174:177], v[222:225]
	v_mfma_f32_16x16x32_bf16 v[60:63], v[190:193], v[178:181], v[24:27]
	v_mfma_f32_16x16x32_bf16 v[24:27], v[0:3], v[182:185], v[52:55]
	v_mfma_f32_16x16x32_bf16 v[40:43], v[4:7], v[186:189], v[24:27]
	v_mfma_f32_16x16x32_bf16 v[24:27], v[170:173], v[182:185], v[48:51]
	v_mfma_f32_16x16x32_bf16 v[44:47], v[190:193], v[186:189], v[24:27]
	v_mfma_f32_16x16x32_bf16 v[24:27], v[0:3], v[194:197], v[226:229]
	v_mfma_f32_16x16x32_bf16 v[0:3], v[0:3], v[202:205], v[36:39]
	v_mfma_f32_16x16x32_bf16 v[24:27], v[4:7], v[198:201], v[24:27]
	v_mfma_f32_16x16x32_bf16 v[28:31], v[170:173], v[194:197], v[230:233]
	v_mfma_f32_16x16x32_bf16 v[0:3], v[4:7], v[234:237], v[0:3]
	v_mfma_f32_16x16x32_bf16 v[4:7], v[170:173], v[202:205], v[32:35]
	v_mfma_f32_16x16x32_bf16 v[28:31], v[190:193], v[198:201], v[28:31]
	v_mfma_f32_16x16x32_bf16 v[4:7], v[190:193], v[234:237], v[4:7]
	s_setprio 0
	s_setprio 1
	v_mfma_f32_16x16x32_bf16 v[32:35], v[206:209], v[174:177], v[132:135]
	v_mfma_f32_16x16x32_bf16 v[48:51], v[210:213], v[178:181], v[32:35]
	v_mfma_f32_16x16x32_bf16 v[32:35], v[214:217], v[174:177], v[136:139]
	v_mfma_f32_16x16x32_bf16 v[20:23], v[206:209], v[182:185], v[20:23]
	v_mfma_f32_16x16x32_bf16 v[16:19], v[214:217], v[182:185], v[16:19]
	v_mfma_f32_16x16x32_bf16 v[12:15], v[206:209], v[194:197], v[12:15]
	v_mfma_f32_16x16x32_bf16 v[8:11], v[214:217], v[194:197], v[8:11]
	v_mfma_f32_16x16x32_bf16 v[52:55], v[218:221], v[178:181], v[32:35]
	v_mfma_f32_16x16x32_bf16 v[32:35], v[210:213], v[186:189], v[20:23]
	v_mfma_f32_16x16x32_bf16 v[36:39], v[218:221], v[186:189], v[16:19]
	v_mfma_f32_16x16x32_bf16 v[16:19], v[210:213], v[198:201], v[12:15]
	v_mfma_f32_16x16x32_bf16 v[20:23], v[218:221], v[198:201], v[8:11]
	v_mfma_f32_16x16x32_bf16 v[8:11], v[206:209], v[202:205], v[162:165]
	v_mfma_f32_16x16x32_bf16 v[12:15], v[214:217], v[202:205], v[166:169]
	v_mfma_f32_16x16x32_bf16 v[8:11], v[210:213], v[234:237], v[8:11]
	v_mfma_f32_16x16x32_bf16 v[12:15], v[218:221], v[234:237], v[12:15]
	s_setprio 0
	s_barrier
	s_and_saveexec_b64 s[20:21], s[4:5]
	s_cbranch_execz .LBB0_730
	s_barrier

; #define STA(b, h, half, kt) STAGE(((b) * 2 + (h)) * G_HT * 2, pA, ((size_t)(half) * G_HALF * lda + (size_t)(kt) * G_BK) * 2, lda)
; #define STB(b, h, half, kt) STAGE((4 + (b) * 2 + (h)) * G_HT * 2, pB, ((size_t)(half) * G_HALF * K + (size_t)(kt) * G_BK) * 2, K)
; #define LDA(dst, b, h) for (int m = 0; m < 4; ++m) for (int k = 0; k < 2; ++k) \
;     dst[m][k] = *reinterpret_cast<const bf16x8*>(aRd + (((b) * 2 + (h)) * G_HT * 2 + m * 2048 + k * 1024))
; #define LDB(dst, b, h) for (int n = 0; n < 2; ++n) for (int k = 0; k < 2; ++k) \
;     dst[n][k] = *reinterpret_cast<const bf16x8*>(bRd + (((b) * 2 + (h)) * G_HT * 2 + n * 2048 + k * 1024))
; #define MMA(ai, bj, At, Bx) do { __builtin_amdgcn_s_setprio(1); \
;     for (int m = 0; m < 4; ++m) for (int n = 0; n < 2; ++n) for (int k = 0; k < 2; ++k) \
;       acc[ai][bj][m][n] = __builtin_amdgcn_mfma_f32_16x16x32_bf16(Bx[n][k], At[m][k], acc[ai][bj][m][n], 0, 0, 0);     \
;     __builtin_amdgcn_s_setprio(0); } while (0)
; #define WAIT_V(n) asm volatile("s_waitcnt vmcnt(" #n ")" ::: "memory")
; #define WAIT_L(n) asm volatile("s_waitcnt lgkmcnt(" #n ")" ::: "memory")
; #define BAR __builtin_amdgcn_s_barrier()
; #define SCHED __builtin_amdgcn_sched_barrier(0)
; template <int EPI>
; __device__ __forceinline__ void gemm_tile(const bf16* __restrict__ A, int lda, const bf16* __restrict__ Bt, int K,
;                                           int brow, int bcol, const EpiArgs& ea, char* shmc, bool has_next, int nbrow, int nbcol, bool first_tile) {
;     ...
;   for (int t = 0; t < nt - 2; t += 2) {
;     LDB(B0, 0, 0); SCHED; LDA(At, 0, 0); STA(1, 1, 1, t + 1);
;     WAIT_L(8); BAR; WAIT_L(0); MMA(0, 0, At, B0); BAR; SCHED;
;     LDB(B1, 0, 1); STB(0, 0, 0, t + 2);
;     BAR; WAIT_L(0); MMA(0, 1, At, B1); BAR;
;     LDA(At, 0, 1); STA(0, 0, 0, t + 2);
;     BAR; WAIT_L(0); MMA(1, 0, At, B0); BAR; SCHED;
;     STB(0, 1, 1, t + 2);
;     WAIT_V(6); BAR; MMA(1, 1, At, B1); BAR;
;     LDB(B0, 1, 0); SCHED; LDA(At, 1, 0); STA(0, 1, 1, t + 2);
;     WAIT_L(8); BAR; WAIT_L(0); MMA(0, 0, At, B0); BAR; SCHED;
;     LDB(B1, 1, 1); STB(1, 0, 0, t + 3);
;     BAR; WAIT_L(0); MMA(0, 1, At, B1); BAR;
;     LDA(At, 1, 1); STA(1, 0, 0, t + 3);
;     BAR; WAIT_L(0); MMA(1, 0, At, B0); BAR; SCHED;
.LBB0_784:
	ds_read_b128 v[136:139], v141
	ds_read_b128 v[162:165], v142
	ds_read_b128 v[166:169], v143
	ds_read_b128 v[170:173], v144
	s_add_u32 s40, s18, 0xffffff00
	s_addc_u32 s41, s19, -1
	s_mov_b32 m0, s34
	ds_read_b128 v[174:177], v160
	ds_read_b128 v[178:181], v160 offset:1024
	ds_read_b128 v[182:185], v160 offset:2048
	ds_read_b128 v[186:189], v160 offset:3072
	ds_read_b128 v[190:193], v160 offset:4096
	ds_read_b128 v[194:197], v160 offset:5120
	ds_read_b128 v[198:201], v160 offset:6144
	ds_read_b128 v[202:205], v160 offset:7168
	v_lshl_add_u64 v[206:207], v[132:133], 0, s[40:41]
	global_load_lds_dwordx4 v[206:207], off
	s_mov_b32 m0, s24
	v_lshl_add_u64 v[206:207], v[206:207], 0, s[4:5]
	global_load_lds_dwordx4 v[206:207], off
	s_waitcnt lgkmcnt(8)
	s_barrier
	s_waitcnt lgkmcnt(0)
	s_setprio 1
	v_mfma_f32_16x16x32_bf16 v[124:127], v[136:139], v[174:177], v[124:127]
	v_mfma_f32_16x16x32_bf16 v[120:123], v[166:169], v[174:177], v[120:123]
	v_mfma_f32_16x16x32_bf16 v[116:119], v[136:139], v[182:185], v[116:119]
	v_mfma_f32_16x16x32_bf16 v[112:115], v[166:169], v[182:185], v[112:115]
	v_mfma_f32_16x16x32_bf16 v[108:111], v[136:139], v[190:193], v[108:111]
	v_mfma_f32_16x16x32_bf16 v[104:107], v[166:169], v[190:193], v[104:107]
	v_mfma_f32_16x16x32_bf16 v[100:103], v[136:139], v[198:201], v[100:103]
	v_mfma_f32_16x16x32_bf16 v[96:99], v[166:169], v[198:201], v[96:99]
	v_mfma_f32_16x16x32_bf16 v[124:127], v[162:165], v[178:181], v[124:127]
	v_mfma_f32_16x16x32_bf16 v[120:123], v[170:173], v[178:181], v[120:123]
	v_mfma_f32_16x16x32_bf16 v[116:119], v[162:165], v[186:189], v[116:119]
	v_mfma_f32_16x16x32_bf16 v[112:115], v[170:173], v[186:189], v[112:115]
	v_mfma_f32_16x16x32_bf16 v[108:111], v[162:165], v[194:197], v[108:111]
	v_mfma_f32_16x16x32_bf16 v[104:107], v[170:173], v[194:197], v[104:107]
	v_mfma_f32_16x16x32_bf16 v[100:103], v[162:165], v[202:205], v[100:103]
	v_mfma_f32_16x16x32_bf16 v[96:99], v[170:173], v[202:205], v[96:99]
	s_setprio 0
	s_barrier
	s_add_u32 s40, s18, 0xffbfff80
	s_addc_u32 s41, s19, -1
	s_mov_b64 s[42:43], s[40:41]
	s_mov_b32 m0, s27
	ds_read_b128 v[206:209], v145
	ds_read_b128 v[210:213], v146
	ds_read_b128 v[214:217], v147
	ds_read_b128 v[218:221], v148
	v_lshl_add_u64 v[222:223], v[134:135], 0, s[42:43]
	global_load_lds_dwordx4 v[222:223], off
	s_mov_b32 m0, s28
	v_lshl_add_u64 v[222:223], v[222:223], 0, s[4:5]
	global_load_lds_dwordx4 v[222:223], off
	s_barrier
	s_waitcnt lgkmcnt(0)
	s_setprio 1
	v_mfma_f32_16x16x32_bf16 v[92:95], v[206:209], v[174:177], v[92:95]
	v_mfma_f32_16x16x32_bf16 v[88:91], v[214:217], v[174:177], v[88:91]
	v_mfma_f32_16x16x32_bf16 v[84:87], v[206:209], v[182:185], v[84:87]
	v_mfma_f32_16x16x32_bf16 v[80:83], v[214:217], v[182:185], v[80:83]
	v_mfma_f32_16x16x32_bf16 v[76:79], v[206:209], v[190:193], v[76:79]
	v_mfma_f32_16x16x32_bf16 v[72:75], v[214:217], v[190:193], v[72:75]
	v_mfma_f32_16x16x32_bf16 v[68:71], v[206:209], v[198:201], v[68:71]
	v_mfma_f32_16x16x32_bf16 v[64:67], v[214:217], v[198:201], v[64:67]
	v_mfma_f32_16x16x32_bf16 v[92:95], v[210:213], v[178:181], v[92:95]
	v_mfma_f32_16x16x32_bf16 v[88:91], v[218:221], v[178:181], v[88:91]
	v_mfma_f32_16x16x32_bf16 v[84:87], v[210:213], v[186:189], v[84:87]
	v_mfma_f32_16x16x32_bf16 v[80:83], v[218:221], v[186:189], v[80:83]
	v_mfma_f32_16x16x32_bf16 v[76:79], v[210:213], v[194:197], v[76:79]
	v_mfma_f32_16x16x32_bf16 v[72:75], v[218:221], v[194:197], v[72:75]
	v_mfma_f32_16x16x32_bf16 v[68:71], v[210:213], v[202:205], v[68:71]
	v_mfma_f32_16x16x32_bf16 v[64:67], v[218:221], v[202:205], v[64:67]
	s_setprio 0
	s_mov_b32 m0, s15
	s_barrier
	ds_read_b128 v[174:177], v160 offset:16384
	ds_read_b128 v[178:181], v160 offset:17408
	ds_read_b128 v[182:185], v160 offset:18432
	ds_read_b128 v[186:189], v160 offset:19456
	ds_read_b128 v[190:193], v160 offset:20480
	ds_read_b128 v[194:197], v160 offset:21504
	ds_read_b128 v[198:201], v160 offset:22528
	ds_read_b128 v[202:205], v160 offset:23552
	v_lshl_add_u64 v[222:223], v[132:133], 0, s[40:41]
	global_load_lds_dwordx4 v[222:223], off
	s_mov_b32 m0, s35
	v_lshl_add_u64 v[222:223], v[222:223], 0, s[4:5]
	global_load_lds_dwordx4 v[222:223], off
	s_barrier
	s_waitcnt lgkmcnt(0)
	s_setprio 1
	v_mfma_f32_16x16x32_bf16 v[60:63], v[136:139], v[174:177], v[60:63]
	v_mfma_f32_16x16x32_bf16 v[56:59], v[166:169], v[174:177], v[56:59]
	v_mfma_f32_16x16x32_bf16 v[52:55], v[136:139], v[182:185], v[52:55]
	v_mfma_f32_16x16x32_bf16 v[48:51], v[166:169], v[182:185], v[48:51]
	v_mfma_f32_16x16x32_bf16 v[44:47], v[136:139], v[190:193], v[44:47]
	v_mfma_f32_16x16x32_bf16 v[40:43], v[166:169], v[190:193], v[40:43]
	v_mfma_f32_16x16x32_bf16 v[36:39], v[136:139], v[198:201], v[36:39]
	v_mfma_f32_16x16x32_bf16 v[32:35], v[166:169], v[198:201], v[32:35]
	v_mfma_f32_16x16x32_bf16 v[60:63], v[162:165], v[178:181], v[60:63]
	v_mfma_f32_16x16x32_bf16 v[56:59], v[170:173], v[178:181], v[56:59]
	v_mfma_f32_16x16x32_bf16 v[52:55], v[162:165], v[186:189], v[52:55]
	v_mfma_f32_16x16x32_bf16 v[48:51], v[170:173], v[186:189], v[48:51]
	v_mfma_f32_16x16x32_bf16 v[44:47], v[162:165], v[194:197], v[44:47]
	v_mfma_f32_16x16x32_bf16 v[40:43], v[170:173], v[194:197], v[40:43]
	v_mfma_f32_16x16x32_bf16 v[36:39], v[162:165], v[202:205], v[36:39]
	v_mfma_f32_16x16x32_bf16 v[32:35], v[170:173], v[202:205], v[32:35]
	s_setprio 0
	s_barrier
	s_add_u32 s40, s18, 0xffffff80
	s_addc_u32 s41, s19, -1
	s_mov_b64 s[42:43], s[40:41]
	s_mov_b32 m0, s29
	v_lshl_add_u64 v[136:137], v[134:135], 0, s[42:43]
	global_load_lds_dwordx4 v[136:137], off
	s_mov_b32 m0, s30
	v_lshl_add_u64 v[136:137], v[136:137], 0, s[4:5]
	global_load_lds_dwordx4 v[136:137], off
	s_waitcnt vmcnt(6)
	s_barrier
; #define STA(b, h, half, kt) STAGE(((b) * 2 + (h)) * G_HT * 2, pA, ((size_t)(half) * G_HALF * lda + (size_t)(kt) * G_BK) * 2, lda)
; #define STB(b, h, half, kt) STAGE((4 + (b) * 2 + (h)) * G_HT * 2, pB, ((size_t)(half) * G_HALF * K + (size_t)(kt) * G_BK) * 2, K)
; #define LDA(dst, b, h) for (int m = 0; m < 4; ++m) for (int k = 0; k < 2; ++k) \
;     dst[m][k] = *reinterpret_cast<const bf16x8*>(aRd + (((b) * 2 + (h)) * G_HT * 2 + m * 2048 + k * 1024))
; #define LDB(dst, b, h) for (int n = 0; n < 2; ++n) for (int k = 0; k < 2; ++k) \
;     dst[n][k] = *reinterpret_cast<const bf16x8*>(bRd + (((b) * 2 + (h)) * G_HT * 2 + n * 2048 + k * 1024))
; #define MMA(ai, bj, At, Bx) do { __builtin_amdgcn_s_setprio(1); \
;     for (int m = 0; m < 4; ++m) for (int n = 0; n < 2; ++n) for (int k = 0; k < 2; ++k) \
;       acc[ai][bj][m][n] = __builtin_amdgcn_mfma_f32_16x16x32_bf16(Bx[n][k], At[m][k], acc[ai][bj][m][n], 0, 0, 0);     \
;     __builtin_amdgcn_s_setprio(0); } while (0)
; #define WAIT_V(n) asm volatile("s_waitcnt vmcnt(" #n ")" ::: "memory")
; #define WAIT_L(n) asm volatile("s_waitcnt lgkmcnt(" #n ")" ::: "memory")
; #define BAR __builtin_amdgcn_s_barrier()
; #define SCHED __builtin_amdgcn_sched_barrier(0)
; template <int EPI>
; __device__ __forceinline__ void gemm_tile(const bf16* __restrict__ A, int lda, const bf16* __restrict__ Bt, int K,
;                                           int brow, int bcol, const EpiArgs& ea, char* shmc, bool has_next, int nbrow, int nbcol, bool first_tile) {
;     ...
;     WAIT_V(6); BAR; MMA(1, 1, At, B1); BAR;
;     LDB(B0, 1, 0); SCHED; LDA(At, 1, 0); STA(0, 1, 1, t + 2);
;     WAIT_L(8); BAR; WAIT_L(0); MMA(0, 0, At, B0); BAR; SCHED;
;     LDB(B1, 1, 1); STB(1, 0, 0, t + 3);
;     BAR; WAIT_L(0); MMA(0, 1, At, B1); BAR;
;     LDA(At, 1, 1); STA(1, 0, 0, t + 3);
;     BAR; WAIT_L(0); MMA(1, 0, At, B0); BAR; SCHED;
	s_setprio 1
	v_mfma_f32_16x16x32_bf16 v[28:31], v[206:209], v[174:177], v[28:31]
	v_mfma_f32_16x16x32_bf16 v[24:27], v[214:217], v[174:177], v[24:27]
	v_mfma_f32_16x16x32_bf16 v[20:23], v[206:209], v[182:185], v[20:23]
	v_mfma_f32_16x16x32_bf16 v[16:19], v[214:217], v[182:185], v[16:19]
	v_mfma_f32_16x16x32_bf16 v[12:15], v[206:209], v[190:193], v[12:15]
	v_mfma_f32_16x16x32_bf16 v[8:11], v[214:217], v[190:193], v[8:11]
	v_mfma_f32_16x16x32_bf16 v[4:7], v[206:209], v[198:201], v[4:7]
	v_mfma_f32_16x16x32_bf16 v[0:3], v[214:217], v[198:201], v[0:3]
	v_mfma_f32_16x16x32_bf16 v[28:31], v[210:213], v[178:181], v[28:31]
	v_mfma_f32_16x16x32_bf16 v[24:27], v[218:221], v[178:181], v[24:27]
	v_mfma_f32_16x16x32_bf16 v[20:23], v[210:213], v[186:189], v[20:23]
	v_mfma_f32_16x16x32_bf16 v[16:19], v[218:221], v[186:189], v[16:19]
	v_mfma_f32_16x16x32_bf16 v[12:15], v[210:213], v[194:197], v[12:15]
	v_mfma_f32_16x16x32_bf16 v[8:11], v[218:221], v[194:197], v[8:11]
	v_mfma_f32_16x16x32_bf16 v[4:7], v[210:213], v[202:205], v[4:7]
	v_mfma_f32_16x16x32_bf16 v[0:3], v[218:221], v[202:205], v[0:3]
	s_setprio 0
	s_barrier
	ds_read_b128 v[136:139], v149
	ds_read_b128 v[162:165], v150
	ds_read_b128 v[166:169], v151
	ds_read_b128 v[170:173], v152
	s_mov_b32 m0, s36
	ds_read_b128 v[174:177], v160 offset:32768
	ds_read_b128 v[178:181], v160 offset:33792
	ds_read_b128 v[182:185], v160 offset:34816
	ds_read_b128 v[186:189], v160 offset:35840
	ds_read_b128 v[190:193], v160 offset:36864
	ds_read_b128 v[194:197], v160 offset:37888
	ds_read_b128 v[198:201], v160 offset:38912
	ds_read_b128 v[202:205], v160 offset:39936
	v_lshl_add_u64 v[206:207], v[132:133], 0, s[40:41]
	global_load_lds_dwordx4 v[206:207], off
	s_mov_b32 m0, s37
	v_lshl_add_u64 v[206:207], v[206:207], 0, s[4:5]
	global_load_lds_dwordx4 v[206:207], off
	s_waitcnt lgkmcnt(8)
	s_barrier
	s_waitcnt lgkmcnt(0)
	s_setprio 1
	v_mfma_f32_16x16x32_bf16 v[124:127], v[136:139], v[174:177], v[124:127]
	v_mfma_f32_16x16x32_bf16 v[120:123], v[166:169], v[174:177], v[120:123]
	v_mfma_f32_16x16x32_bf16 v[116:119], v[136:139], v[182:185], v[116:119]
	v_mfma_f32_16x16x32_bf16 v[112:115], v[166:169], v[182:185], v[112:115]
	v_mfma_f32_16x16x32_bf16 v[108:111], v[136:139], v[190:193], v[108:111]
	v_mfma_f32_16x16x32_bf16 v[104:107], v[166:169], v[190:193], v[104:107]
	v_mfma_f32_16x16x32_bf16 v[100:103], v[136:139], v[198:201], v[100:103]
	v_mfma_f32_16x16x32_bf16 v[96:99], v[166:169], v[198:201], v[96:99]
	v_mfma_f32_16x16x32_bf16 v[124:127], v[162:165], v[178:181], v[124:127]
	v_mfma_f32_16x16x32_bf16 v[120:123], v[170:173], v[178:181], v[120:123]
	v_mfma_f32_16x16x32_bf16 v[116:119], v[162:165], v[186:189], v[116:119]
	v_mfma_f32_16x16x32_bf16 v[112:115], v[170:173], v[186:189], v[112:115]
	v_mfma_f32_16x16x32_bf16 v[108:111], v[162:165], v[194:197], v[108:111]
	v_mfma_f32_16x16x32_bf16 v[104:107], v[170:173], v[194:197], v[104:107]
	v_mfma_f32_16x16x32_bf16 v[100:103], v[162:165], v[202:205], v[100:103]
	v_mfma_f32_16x16x32_bf16 v[96:99], v[170:173], v[202:205], v[96:99]
	s_setprio 0
	s_barrier
	s_add_u32 s40, s18, 0xffc00000
	s_addc_u32 s41, s19, -1
	s_mov_b64 s[42:43], s[40:41]
	s_mov_b32 m0, s17
	ds_read_b128 v[206:209], v153
	ds_read_b128 v[210:213], v154
	ds_read_b128 v[214:217], v155
	ds_read_b128 v[218:221], v156
	v_lshl_add_u64 v[222:223], v[134:135], 0, s[42:43]
	global_load_lds_dwordx4 v[222:223], off
	s_mov_b32 m0, s21
	v_lshl_add_u64 v[222:223], v[222:223], 0, s[4:5]
	global_load_lds_dwordx4 v[222:223], off
	s_barrier
	s_waitcnt lgkmcnt(0)
	s_setprio 1
	v_mfma_f32_16x16x32_bf16 v[92:95], v[206:209], v[174:177], v[92:95]
	v_mfma_f32_16x16x32_bf16 v[88:91], v[214:217], v[174:177], v[88:91]
	v_mfma_f32_16x16x32_bf16 v[84:87], v[206:209], v[182:185], v[84:87]
	v_mfma_f32_16x16x32_bf16 v[80:83], v[214:217], v[182:185], v[80:83]
	v_mfma_f32_16x16x32_bf16 v[76:79], v[206:209], v[190:193], v[76:79]
	v_mfma_f32_16x16x32_bf16 v[72:75], v[214:217], v[190:193], v[72:75]
	v_mfma_f32_16x16x32_bf16 v[68:71], v[206:209], v[198:201], v[68:71]
	v_mfma_f32_16x16x32_bf16 v[64:67], v[214:217], v[198:201], v[64:67]
	v_mfma_f32_16x16x32_bf16 v[92:95], v[210:213], v[178:181], v[92:95]
	v_mfma_f32_16x16x32_bf16 v[88:91], v[218:221], v[178:181], v[88:91]
	v_mfma_f32_16x16x32_bf16 v[84:87], v[210:213], v[186:189], v[84:87]
	v_mfma_f32_16x16x32_bf16 v[80:83], v[218:221], v[186:189], v[80:83]
	v_mfma_f32_16x16x32_bf16 v[76:79], v[210:213], v[194:197], v[76:79]
	v_mfma_f32_16x16x32_bf16 v[72:75], v[218:221], v[194:197], v[72:75]
	v_mfma_f32_16x16x32_bf16 v[68:71], v[210:213], v[202:205], v[68:71]
	v_mfma_f32_16x16x32_bf16 v[64:67], v[218:221], v[202:205], v[64:67]
	s_setprio 0
	s_mov_b32 m0, s22
	s_barrier
	ds_read_b128 v[174:177], v160 offset:49152
	ds_read_b128 v[178:181], v160 offset:50176
	ds_read_b128 v[182:185], v160 offset:51200
	ds_read_b128 v[186:189], v160 offset:52224
	ds_read_b128 v[190:193], v160 offset:53248
	ds_read_b128 v[194:197], v160 offset:54272
	ds_read_b128 v[198:201], v160 offset:55296
	ds_read_b128 v[202:205], v160 offset:56320
	v_lshl_add_u64 v[222:223], v[132:133], 0, s[40:41]
	global_load_lds_dwordx4 v[222:223], off
	s_mov_b32 m0, s23
	v_lshl_add_u64 v[222:223], v[222:223], 0, s[4:5]
	global_load_lds_dwordx4 v[222:223], off
	s_barrier
; #define STA(b, h, half, kt) STAGE(((b) * 2 + (h)) * G_HT * 2, pA, ((size_t)(half) * G_HALF * lda + (size_t)(kt) * G_BK) * 2, lda)
; #define STB(b, h, half, kt) STAGE((4 + (b) * 2 + (h)) * G_HT * 2, pB, ((size_t)(half) * G_HALF * K + (size_t)(kt) * G_BK) * 2, K)
; #define LDA(dst, b, h) for (int m = 0; m < 4; ++m) for (int k = 0; k < 2; ++k) \
;     dst[m][k] = *reinterpret_cast<const bf16x8*>(aRd + (((b) * 2 + (h)) * G_HT * 2 + m * 2048 + k * 1024))
; #define LDB(dst, b, h) for (int n = 0; n < 2; ++n) for (int k = 0; k < 2; ++k) \
;     dst[n][k] = *reinterpret_cast<const bf16x8*>(bRd + (((b) * 2 + (h)) * G_HT * 2 + n * 2048 + k * 1024))
; #define MMA(ai, bj, At, Bx) do { __builtin_amdgcn_s_setprio(1); \
;     for (int m = 0; m < 4; ++m) for (int n = 0; n < 2; ++n) for (int k = 0; k < 2; ++k) \
;       acc[ai][bj][m][n] = __builtin_amdgcn_mfma_f32_16x16x32_bf16(Bx[n][k], At[m][k], acc[ai][bj][m][n], 0, 0, 0);     \
;     __builtin_amdgcn_s_setprio(0); } while (0)
; #define WAIT_V(n) asm volatile("s_waitcnt vmcnt(" #n ")" ::: "memory")
; #define WAIT_L(n) asm volatile("s_waitcnt lgkmcnt(" #n ")" ::: "memory")
; #define BAR __builtin_amdgcn_s_barrier()
; #define SCHED __builtin_amdgcn_sched_barrier(0)
; template <int EPI>
; __device__ __forceinline__ void gemm_tile(const bf16* __restrict__ A, int lda, const bf16* __restrict__ Bt, int K,
;                                           int brow, int bcol, const EpiArgs& ea, char* shmc, bool has_next, int nbrow, int nbcol, bool first_tile) {
;     ...
;     BAR; WAIT_L(0); MMA(1, 0, At, B0); BAR; SCHED;
;     STB(1, 1, 1, t + 3);
;     WAIT_V(6); BAR; MMA(1, 1, At, B1); BAR;
;   }
;   { LDB(B0, 0, 0); LDA(At, 0, 0); STA(1, 1, 1, nt - 1);
;     BAR; WAIT_L(0); MMA(0, 0, At, B0); BAR;
;     LDB(B1, 0, 1); BAR; WAIT_L(0); MMA(0, 1, At, B1); BAR;
;     LDA(At, 0, 1); WAIT_V(4); BAR; WAIT_L(0); MMA(1, 0, At, B0); MMA(1, 1, At, B1); BAR; }
	s_waitcnt lgkmcnt(0)
	s_setprio 1
	v_mfma_f32_16x16x32_bf16 v[60:63], v[136:139], v[174:177], v[60:63]
	v_mfma_f32_16x16x32_bf16 v[56:59], v[166:169], v[174:177], v[56:59]
	v_mfma_f32_16x16x32_bf16 v[52:55], v[136:139], v[182:185], v[52:55]
	v_mfma_f32_16x16x32_bf16 v[48:51], v[166:169], v[182:185], v[48:51]
	v_mfma_f32_16x16x32_bf16 v[44:47], v[136:139], v[190:193], v[44:47]
	v_mfma_f32_16x16x32_bf16 v[40:43], v[166:169], v[190:193], v[40:43]
	v_mfma_f32_16x16x32_bf16 v[36:39], v[136:139], v[198:201], v[36:39]
	v_mfma_f32_16x16x32_bf16 v[32:35], v[166:169], v[198:201], v[32:35]
	v_mfma_f32_16x16x32_bf16 v[60:63], v[162:165], v[178:181], v[60:63]
	v_mfma_f32_16x16x32_bf16 v[56:59], v[170:173], v[178:181], v[56:59]
	v_mfma_f32_16x16x32_bf16 v[52:55], v[162:165], v[186:189], v[52:55]
	v_mfma_f32_16x16x32_bf16 v[48:51], v[170:173], v[186:189], v[48:51]
	v_mfma_f32_16x16x32_bf16 v[44:47], v[162:165], v[194:197], v[44:47]
	v_mfma_f32_16x16x32_bf16 v[40:43], v[170:173], v[194:197], v[40:43]
	v_mfma_f32_16x16x32_bf16 v[36:39], v[162:165], v[202:205], v[36:39]
	v_mfma_f32_16x16x32_bf16 v[32:35], v[170:173], v[202:205], v[32:35]
	s_setprio 0
	s_barrier
	s_mov_b64 s[40:41], s[18:19]
	s_mov_b32 m0, s25
	v_lshl_add_u64 v[136:137], v[134:135], 0, s[40:41]
	global_load_lds_dwordx4 v[136:137], off
	s_mov_b32 m0, s26
	v_lshl_add_u64 v[136:137], v[136:137], 0, s[4:5]
	global_load_lds_dwordx4 v[136:137], off
	s_waitcnt vmcnt(6)
	s_barrier
	s_setprio 1
	v_mfma_f32_16x16x32_bf16 v[28:31], v[206:209], v[174:177], v[28:31]
	v_mfma_f32_16x16x32_bf16 v[24:27], v[214:217], v[174:177], v[24:27]
	v_mfma_f32_16x16x32_bf16 v[20:23], v[206:209], v[182:185], v[20:23]
	v_mfma_f32_16x16x32_bf16 v[16:19], v[214:217], v[182:185], v[16:19]
	v_mfma_f32_16x16x32_bf16 v[12:15], v[206:209], v[190:193], v[12:15]
	v_mfma_f32_16x16x32_bf16 v[8:11], v[214:217], v[190:193], v[8:11]
	v_mfma_f32_16x16x32_bf16 v[4:7], v[206:209], v[198:201], v[4:7]
	v_mfma_f32_16x16x32_bf16 v[0:3], v[214:217], v[198:201], v[0:3]
	v_mfma_f32_16x16x32_bf16 v[28:31], v[210:213], v[178:181], v[28:31]
	v_mfma_f32_16x16x32_bf16 v[24:27], v[218:221], v[178:181], v[24:27]
	v_mfma_f32_16x16x32_bf16 v[20:23], v[210:213], v[186:189], v[20:23]
	v_mfma_f32_16x16x32_bf16 v[16:19], v[218:221], v[186:189], v[16:19]
	v_mfma_f32_16x16x32_bf16 v[12:15], v[210:213], v[194:197], v[12:15]
	v_mfma_f32_16x16x32_bf16 v[8:11], v[218:221], v[194:197], v[8:11]
	v_mfma_f32_16x16x32_bf16 v[4:7], v[210:213], v[202:205], v[4:7]
	v_mfma_f32_16x16x32_bf16 v[0:3], v[218:221], v[202:205], v[0:3]
	s_setprio 0
	s_add_i32 s31, s31, 2
	s_add_u32 s18, s18, 0x100
	s_addc_u32 s19, s19, 0
	s_cmpk_lt_u32 s31, 0xfc
	s_barrier
	s_cbranch_scc1 .LBB0_784
	s_mov_b64 s[18:19], 0x407f80
	s_mov_b32 m0, s34
	ds_read_b128 v[134:137], v141
	ds_read_b128 v[162:165], v142
	ds_read_b128 v[166:169], v143
	ds_read_b128 v[170:173], v144
	ds_read_b128 v[174:177], v160
	ds_read_b128 v[178:181], v160 offset:1024
	ds_read_b128 v[182:185], v160 offset:2048
	ds_read_b128 v[186:189], v160 offset:3072
	ds_read_b128 v[190:193], v160 offset:4096
	ds_read_b128 v[194:197], v160 offset:5120
	ds_read_b128 v[198:201], v160 offset:6144
	ds_read_b128 v[202:205], v160 offset:7168
	s_nop 0
	v_lshl_add_u64 v[132:133], v[132:133], 0, s[18:19]
	global_load_lds_dwordx4 v[132:133], off
	v_lshl_add_u64 v[132:133], v[132:133], 0, s[4:5]
	s_mov_b32 m0, s24
	s_nop 0
	global_load_lds_dwordx4 v[132:133], off
	s_barrier
	s_waitcnt lgkmcnt(0)
	s_setprio 1
	s_waitcnt lgkmcnt(0)
	v_mfma_f32_16x16x32_bf16 v[124:127], v[134:137], v[174:177], v[124:127]
	v_mfma_f32_16x16x32_bf16 v[120:123], v[166:169], v[174:177], v[120:123]
	v_mfma_f32_16x16x32_bf16 v[116:119], v[134:137], v[182:185], v[116:119]
	v_mfma_f32_16x16x32_bf16 v[112:115], v[166:169], v[182:185], v[112:115]
	v_mfma_f32_16x16x32_bf16 v[100:103], v[134:137], v[198:201], v[100:103]
	v_mfma_f32_16x16x32_bf16 v[96:99], v[166:169], v[198:201], v[96:99]
	v_mfma_f32_16x16x32_bf16 v[124:127], v[162:165], v[178:181], v[124:127]
	v_mfma_f32_16x16x32_bf16 v[120:123], v[170:173], v[178:181], v[120:123]
	v_mfma_f32_16x16x32_bf16 v[116:119], v[162:165], v[186:189], v[116:119]
	v_mfma_f32_16x16x32_bf16 v[112:115], v[170:173], v[186:189], v[112:115]
	v_mfma_f32_16x16x32_bf16 v[108:111], v[134:137], v[190:193], v[108:111]
	v_mfma_f32_16x16x32_bf16 v[104:107], v[166:169], v[190:193], v[104:107]
	v_mfma_f32_16x16x32_bf16 v[100:103], v[162:165], v[202:205], v[100:103]
	v_mfma_f32_16x16x32_bf16 v[96:99], v[170:173], v[202:205], v[96:99]
	v_mfma_f32_16x16x32_bf16 v[206:209], v[162:165], v[194:197], v[108:111]
	v_mfma_f32_16x16x32_bf16 v[210:213], v[170:173], v[194:197], v[104:107]
	s_setprio 0
	s_barrier
	s_nop 1
	ds_read_b128 v[104:107], v145
	ds_read_b128 v[108:111], v146
	ds_read_b128 v[214:217], v147
	ds_read_b128 v[218:221], v148
	s_barrier
	s_waitcnt lgkmcnt(0)
	s_setprio 1
	s_waitcnt lgkmcnt(0)
	v_mfma_f32_16x16x32_bf16 v[84:87], v[104:107], v[182:185], v[84:87]
	v_mfma_f32_16x16x32_bf16 v[80:83], v[214:217], v[182:185], v[80:83]
	v_mfma_f32_16x16x32_bf16 v[68:71], v[104:107], v[198:201], v[68:71]
	v_mfma_f32_16x16x32_bf16 v[64:67], v[214:217], v[198:201], v[64:67]
	v_mfma_f32_16x16x32_bf16 v[92:95], v[104:107], v[174:177], v[92:95]
	v_mfma_f32_16x16x32_bf16 v[88:91], v[214:217], v[174:177], v[88:91]
	v_mfma_f32_16x16x32_bf16 v[84:87], v[108:111], v[186:189], v[84:87]
	v_mfma_f32_16x16x32_bf16 v[80:83], v[218:221], v[186:189], v[80:83]
	v_mfma_f32_16x16x32_bf16 v[76:79], v[104:107], v[190:193], v[76:79]
	v_mfma_f32_16x16x32_bf16 v[72:75], v[214:217], v[190:193], v[72:75]
	v_mfma_f32_16x16x32_bf16 v[68:71], v[108:111], v[202:205], v[68:71]
	v_mfma_f32_16x16x32_bf16 v[64:67], v[218:221], v[202:205], v[64:67]
	v_mfma_f32_16x16x32_bf16 v[222:225], v[108:111], v[178:181], v[92:95]
	v_mfma_f32_16x16x32_bf16 v[174:177], v[218:221], v[178:181], v[88:91]
	v_mfma_f32_16x16x32_bf16 v[178:181], v[108:111], v[194:197], v[76:79]
	v_mfma_f32_16x16x32_bf16 v[182:185], v[218:221], v[194:197], v[72:75]
	s_setprio 0
	s_barrier
; #define LDA(dst, b, h) for (int m = 0; m < 4; ++m) for (int k = 0; k < 2; ++k) \
;     dst[m][k] = *reinterpret_cast<const bf16x8*>(aRd + (((b) * 2 + (h)) * G_HT * 2 + m * 2048 + k * 1024))
; #define LDB(dst, b, h) for (int n = 0; n < 2; ++n) for (int k = 0; k < 2; ++k) \
;     dst[n][k] = *reinterpret_cast<const bf16x8*>(bRd + (((b) * 2 + (h)) * G_HT * 2 + n * 2048 + k * 1024))
; #define MMA(ai, bj, At, Bx) do { __builtin_amdgcn_s_setprio(1); \
;     for (int m = 0; m < 4; ++m) for (int n = 0; n < 2; ++n) for (int k = 0; k < 2; ++k) \
;       acc[ai][bj][m][n] = __builtin_amdgcn_mfma_f32_16x16x32_bf16(Bx[n][k], At[m][k], acc[ai][bj][m][n], 0, 0, 0);     \
;     __builtin_amdgcn_s_setprio(0); } while (0)
; #define WAIT_V(n) asm volatile("s_waitcnt vmcnt(" #n ")" ::: "memory")
; #define WAIT_L(n) asm volatile("s_waitcnt lgkmcnt(" #n ")" ::: "memory")
; #define BAR __builtin_amdgcn_s_barrier()
; template <int EPI>
; __device__ __forceinline__ void gemm_tile(const bf16* __restrict__ A, int lda, const bf16* __restrict__ Bt, int K,
;                                           int brow, int bcol, const EpiArgs& ea, char* shmc, bool has_next, int nbrow, int nbcol, bool first_tile) {
;     ...
;     LDA(At, 0, 1); WAIT_V(4); BAR; WAIT_L(0); MMA(1, 0, At, B0); MMA(1, 1, At, B1); BAR; }
;   { LDB(B0, 1, 0); LDA(At, 1, 0); WAIT_V(2); BAR; WAIT_L(0); MMA(0, 0, At, B0); BAR;
;     LDB(B1, 1, 1); WAIT_V(0); BAR; WAIT_L(0); MMA(0, 1, At, B1); BAR;
;     LDA(At, 1, 1); BAR; WAIT_L(0); MMA(1, 0, At, B0); MMA(1, 1, At, B1); BAR; }
	s_nop 0
	ds_read_b128 v[72:75], v160 offset:16384
	ds_read_b128 v[76:79], v160 offset:17408
	ds_read_b128 v[88:91], v160 offset:18432
	ds_read_b128 v[92:95], v160 offset:19456
	ds_read_b128 v[186:189], v160 offset:20480
	ds_read_b128 v[190:193], v160 offset:21504
	ds_read_b128 v[194:197], v160 offset:22528
	ds_read_b128 v[198:201], v160 offset:23552
	s_waitcnt vmcnt(4)
	s_barrier
	s_waitcnt lgkmcnt(0)
	s_setprio 1
	s_waitcnt lgkmcnt(0)
	v_mfma_f32_16x16x32_bf16 v[60:63], v[134:137], v[72:75], v[60:63]
	v_mfma_f32_16x16x32_bf16 v[56:59], v[166:169], v[72:75], v[56:59]
	v_mfma_f32_16x16x32_bf16 v[52:55], v[134:137], v[88:91], v[52:55]
	v_mfma_f32_16x16x32_bf16 v[48:51], v[166:169], v[88:91], v[48:51]
	v_mfma_f32_16x16x32_bf16 v[36:39], v[134:137], v[194:197], v[36:39]
	v_mfma_f32_16x16x32_bf16 v[32:35], v[166:169], v[194:197], v[32:35]
	v_mfma_f32_16x16x32_bf16 v[60:63], v[162:165], v[76:79], v[60:63]
	v_mfma_f32_16x16x32_bf16 v[56:59], v[170:173], v[76:79], v[56:59]
	v_mfma_f32_16x16x32_bf16 v[52:55], v[162:165], v[92:95], v[52:55]
	v_mfma_f32_16x16x32_bf16 v[48:51], v[170:173], v[92:95], v[48:51]
	v_mfma_f32_16x16x32_bf16 v[44:47], v[134:137], v[186:189], v[44:47]
	v_mfma_f32_16x16x32_bf16 v[40:43], v[166:169], v[186:189], v[40:43]
	v_mfma_f32_16x16x32_bf16 v[36:39], v[162:165], v[198:201], v[36:39]
	v_mfma_f32_16x16x32_bf16 v[32:35], v[170:173], v[198:201], v[32:35]
	v_mfma_f32_16x16x32_bf16 v[202:205], v[162:165], v[190:193], v[44:47]
	v_mfma_f32_16x16x32_bf16 v[226:229], v[170:173], v[190:193], v[40:43]
	s_setprio 0
	s_setprio 1
	v_mfma_f32_16x16x32_bf16 v[20:23], v[104:107], v[88:91], v[20:23]
	v_mfma_f32_16x16x32_bf16 v[16:19], v[214:217], v[88:91], v[16:19]
	v_mfma_f32_16x16x32_bf16 v[4:7], v[104:107], v[194:197], v[4:7]
	v_mfma_f32_16x16x32_bf16 v[0:3], v[214:217], v[194:197], v[0:3]
	v_mfma_f32_16x16x32_bf16 v[28:31], v[104:107], v[72:75], v[28:31]
	v_mfma_f32_16x16x32_bf16 v[24:27], v[214:217], v[72:75], v[24:27]
	v_mfma_f32_16x16x32_bf16 v[20:23], v[108:111], v[92:95], v[20:23]
	v_mfma_f32_16x16x32_bf16 v[16:19], v[218:221], v[92:95], v[16:19]
	v_mfma_f32_16x16x32_bf16 v[12:15], v[104:107], v[186:189], v[12:15]
	v_mfma_f32_16x16x32_bf16 v[8:11], v[214:217], v[186:189], v[8:11]
	v_mfma_f32_16x16x32_bf16 v[4:7], v[108:111], v[198:201], v[4:7]
	v_mfma_f32_16x16x32_bf16 v[0:3], v[218:221], v[198:201], v[0:3]
	v_mfma_f32_16x16x32_bf16 v[132:135], v[108:111], v[76:79], v[28:31]
	v_mfma_f32_16x16x32_bf16 v[136:139], v[218:221], v[76:79], v[24:27]
	v_mfma_f32_16x16x32_bf16 v[162:165], v[108:111], v[190:193], v[12:15]
	v_mfma_f32_16x16x32_bf16 v[166:169], v[218:221], v[190:193], v[8:11]
	s_setprio 0
	s_barrier
	s_nop 0
	ds_read_b128 v[8:11], v149
	ds_read_b128 v[12:15], v150
	ds_read_b128 v[170:173], v151
	ds_read_b128 v[186:189], v152
	ds_read_b128 v[24:27], v160 offset:32768
	ds_read_b128 v[28:31], v160 offset:33792
	ds_read_b128 v[40:43], v160 offset:34816
	ds_read_b128 v[44:47], v160 offset:35840
	ds_read_b128 v[190:193], v160 offset:36864
	ds_read_b128 v[194:197], v160 offset:37888
	ds_read_b128 v[198:201], v160 offset:38912
	ds_read_b128 v[214:217], v160 offset:39936
	s_waitcnt vmcnt(2)
	s_barrier
	s_waitcnt lgkmcnt(0)
	s_setprio 1
	s_waitcnt lgkmcnt(0)
	v_mfma_f32_16x16x32_bf16 v[72:75], v[8:11], v[24:27], v[124:127]
	v_mfma_f32_16x16x32_bf16 v[124:127], v[12:15], v[28:31], v[72:75]
	v_mfma_f32_16x16x32_bf16 v[72:75], v[170:173], v[24:27], v[120:123]
	v_mfma_f32_16x16x32_bf16 v[120:123], v[186:189], v[28:31], v[72:75]
	v_mfma_f32_16x16x32_bf16 v[72:75], v[8:11], v[40:43], v[116:119]
	v_mfma_f32_16x16x32_bf16 v[108:111], v[12:15], v[44:47], v[72:75]
	v_mfma_f32_16x16x32_bf16 v[72:75], v[170:173], v[40:43], v[112:115]
	v_mfma_f32_16x16x32_bf16 v[104:107], v[186:189], v[44:47], v[72:75]
	v_mfma_f32_16x16x32_bf16 v[72:75], v[8:11], v[190:193], v[206:209]
	v_mfma_f32_16x16x32_bf16 v[92:95], v[12:15], v[194:197], v[72:75]
	v_mfma_f32_16x16x32_bf16 v[72:75], v[170:173], v[190:193], v[210:213]
	v_mfma_f32_16x16x32_bf16 v[88:91], v[186:189], v[194:197], v[72:75]
	v_mfma_f32_16x16x32_bf16 v[72:75], v[8:11], v[198:201], v[100:103]
	v_mfma_f32_16x16x32_bf16 v[76:79], v[12:15], v[214:217], v[72:75]
	v_mfma_f32_16x16x32_bf16 v[72:75], v[170:173], v[198:201], v[96:99]
	v_mfma_f32_16x16x32_bf16 v[72:75], v[186:189], v[214:217], v[72:75]
	s_setprio 0
	s_barrier
; #define LDA(dst, b, h) for (int m = 0; m < 4; ++m) for (int k = 0; k < 2; ++k) \
;     dst[m][k] = *reinterpret_cast<const bf16x8*>(aRd + (((b) * 2 + (h)) * G_HT * 2 + m * 2048 + k * 1024))
; #define LDB(dst, b, h) for (int n = 0; n < 2; ++n) for (int k = 0; k < 2; ++k) \
;     dst[n][k] = *reinterpret_cast<const bf16x8*>(bRd + (((b) * 2 + (h)) * G_HT * 2 + n * 2048 + k * 1024))
; #define MMA(ai, bj, At, Bx) do { __builtin_amdgcn_s_setprio(1); \
;     for (int m = 0; m < 4; ++m) for (int n = 0; n < 2; ++n) for (int k = 0; k < 2; ++k) \
;       acc[ai][bj][m][n] = __builtin_amdgcn_mfma_f32_16x16x32_bf16(Bx[n][k], At[m][k], acc[ai][bj][m][n], 0, 0, 0);     \
;     __builtin_amdgcn_s_setprio(0); } while (0)
; #define WAIT_V(n) asm volatile("s_waitcnt vmcnt(" #n ")" ::: "memory")
; #define WAIT_L(n) asm volatile("s_waitcnt lgkmcnt(" #n ")" ::: "memory")
; #define BAR __builtin_amdgcn_s_barrier()
; template <int EPI>
; __device__ __forceinline__ void gemm_tile(const bf16* __restrict__ A, int lda, const bf16* __restrict__ Bt, int K,
;                                           int brow, int bcol, const EpiArgs& ea, char* shmc, bool has_next, int nbrow, int nbcol, bool first_tile) {
;     ...
;   { LDB(B0, 1, 0); LDA(At, 1, 0); WAIT_V(2); BAR; WAIT_L(0); MMA(0, 0, At, B0); BAR;
;     LDB(B1, 1, 1); WAIT_V(0); BAR; WAIT_L(0); MMA(0, 1, At, B1); BAR;
;     LDA(At, 1, 1); BAR; WAIT_L(0); MMA(1, 0, At, B0); MMA(1, 1, At, B1); BAR; }
;   if (wr == 0) BAR;
;   if (has_next) gemm_prefetch(A, lda, Bt, K, nbrow, nbcol, shmc);
	ds_read_b128 v[206:209], v153
	ds_read_b128 v[210:213], v154
	ds_read_b128 v[218:221], v155
	ds_read_b128 v[230:233], v156
	s_waitcnt vmcnt(0)
	s_barrier
	s_waitcnt lgkmcnt(0)
	s_setprio 1
	s_waitcnt lgkmcnt(0)
	v_mfma_f32_16x16x32_bf16 v[96:99], v[206:209], v[24:27], v[222:225]
	v_mfma_f32_16x16x32_bf16 v[24:27], v[218:221], v[24:27], v[174:177]
	v_mfma_f32_16x16x32_bf16 v[112:115], v[230:233], v[28:31], v[24:27]
	v_mfma_f32_16x16x32_bf16 v[24:27], v[206:209], v[40:43], v[84:87]
	v_mfma_f32_16x16x32_bf16 v[100:103], v[210:213], v[44:47], v[24:27]
	v_mfma_f32_16x16x32_bf16 v[24:27], v[218:221], v[40:43], v[80:83]
	v_mfma_f32_16x16x32_bf16 v[116:119], v[210:213], v[28:31], v[96:99]
	v_mfma_f32_16x16x32_bf16 v[96:99], v[230:233], v[44:47], v[24:27]
	v_mfma_f32_16x16x32_bf16 v[24:27], v[206:209], v[190:193], v[178:181]
	v_mfma_f32_16x16x32_bf16 v[84:87], v[210:213], v[194:197], v[24:27]
	v_mfma_f32_16x16x32_bf16 v[24:27], v[218:221], v[190:193], v[182:185]
	v_mfma_f32_16x16x32_bf16 v[80:83], v[230:233], v[194:197], v[24:27]
	v_mfma_f32_16x16x32_bf16 v[24:27], v[206:209], v[198:201], v[68:71]
	v_mfma_f32_16x16x32_bf16 v[68:71], v[210:213], v[214:217], v[24:27]
	v_mfma_f32_16x16x32_bf16 v[24:27], v[218:221], v[198:201], v[64:67]
	v_mfma_f32_16x16x32_bf16 v[64:67], v[230:233], v[214:217], v[24:27]
	s_setprio 0
	s_barrier
	ds_read_b128 v[174:177], v160 offset:49152
	ds_read_b128 v[178:181], v160 offset:50176
	ds_read_b128 v[182:185], v160 offset:51200
	ds_read_b128 v[190:193], v160 offset:52224
	ds_read_b128 v[194:197], v160 offset:53248
	ds_read_b128 v[198:201], v160 offset:54272
	ds_read_b128 v[214:217], v160 offset:55296
	ds_read_b128 v[222:225], v160 offset:56320
	s_barrier
	s_waitcnt lgkmcnt(0)
	s_setprio 1
	s_waitcnt lgkmcnt(0)
	v_mfma_f32_16x16x32_bf16 v[24:27], v[8:11], v[174:177], v[60:63]
	v_mfma_f32_16x16x32_bf16 v[60:63], v[12:15], v[178:181], v[24:27]
	v_mfma_f32_16x16x32_bf16 v[24:27], v[170:173], v[174:177], v[56:59]
	v_mfma_f32_16x16x32_bf16 v[56:59], v[186:189], v[178:181], v[24:27]
	v_mfma_f32_16x16x32_bf16 v[24:27], v[8:11], v[182:185], v[52:55]
	v_mfma_f32_16x16x32_bf16 v[44:47], v[12:15], v[190:193], v[24:27]
	v_mfma_f32_16x16x32_bf16 v[24:27], v[170:173], v[182:185], v[48:51]
	v_mfma_f32_16x16x32_bf16 v[40:43], v[186:189], v[190:193], v[24:27]
	v_mfma_f32_16x16x32_bf16 v[24:27], v[8:11], v[194:197], v[202:205]
	v_mfma_f32_16x16x32_bf16 v[8:11], v[8:11], v[214:217], v[36:39]
	v_mfma_f32_16x16x32_bf16 v[28:31], v[12:15], v[198:201], v[24:27]
	v_mfma_f32_16x16x32_bf16 v[24:27], v[170:173], v[194:197], v[226:229]
	v_mfma_f32_16x16x32_bf16 v[12:15], v[12:15], v[222:225], v[8:11]
	v_mfma_f32_16x16x32_bf16 v[8:11], v[170:173], v[214:217], v[32:35]
	v_mfma_f32_16x16x32_bf16 v[24:27], v[186:189], v[198:201], v[24:27]
	v_mfma_f32_16x16x32_bf16 v[8:11], v[186:189], v[222:225], v[8:11]
	s_setprio 0
	s_setprio 1
	v_mfma_f32_16x16x32_bf16 v[32:35], v[206:209], v[174:177], v[132:135]
	v_mfma_f32_16x16x32_bf16 v[52:55], v[210:213], v[178:181], v[32:35]
	v_mfma_f32_16x16x32_bf16 v[32:35], v[218:221], v[174:177], v[136:139]
	v_mfma_f32_16x16x32_bf16 v[16:19], v[218:221], v[182:185], v[16:19]
	v_mfma_f32_16x16x32_bf16 v[48:51], v[230:233], v[178:181], v[32:35]
	v_mfma_f32_16x16x32_bf16 v[20:23], v[206:209], v[182:185], v[20:23]
	v_mfma_f32_16x16x32_bf16 v[32:35], v[230:233], v[190:193], v[16:19]
	v_mfma_f32_16x16x32_bf16 v[16:19], v[206:209], v[194:197], v[162:165]
	v_mfma_f32_16x16x32_bf16 v[36:39], v[210:213], v[190:193], v[20:23]
	v_mfma_f32_16x16x32_bf16 v[20:23], v[210:213], v[198:201], v[16:19]
	v_mfma_f32_16x16x32_bf16 v[16:19], v[218:221], v[194:197], v[166:169]
	v_mfma_f32_16x16x32_bf16 v[4:7], v[206:209], v[214:217], v[4:7]
	v_mfma_f32_16x16x32_bf16 v[0:3], v[218:221], v[214:217], v[0:3]
	v_mfma_f32_16x16x32_bf16 v[16:19], v[230:233], v[198:201], v[16:19]
	v_mfma_f32_16x16x32_bf16 v[4:7], v[210:213], v[222:225], v[4:7]
	v_mfma_f32_16x16x32_bf16 v[0:3], v[230:233], v[222:225], v[0:3]
	s_setprio 0
	s_barrier
	s_and_saveexec_b64 s[18:19], s[2:3]
	s_cbranch_execz .LBB0_787
	s_barrier
